# v11 plus removal of redundant s_nop 0 between dependent v_max3 in attention loops
# speedup vs baseline: 1.0321x; 1.0061x over previous
.Lgqa_stag_in:
.LBB0_106:
	global_load_dwordx4 v[2:5], v[178:179], off
	s_and_b32 s1, s0, 1
	s_mul_i32 s31, s1, 0x2400
	v_add_u32_e32 v202, s31, v190
	ds_read_b128 v[10:13], v202 offset:4608
	ds_read_b128 v[80:83], v202
	ds_read_b128 v[186:189], v202 offset:32
	v_mov_b32_e32 v0, v194
	s_waitcnt lgkmcnt(2)
	v_mfma_f32_32x32x16_bf16 v[112:127], v[10:13], v[156:159], 0
	s_waitcnt lgkmcnt(1)
	v_mfma_f32_32x32x16_bf16 v[128:143], v[80:83], v[156:159], 0
	v_mfma_f32_32x32x16_bf16 v[96:111], v[80:83], v[172:175], 0
	v_mfma_f32_32x32x16_bf16 v[80:95], v[10:13], v[172:175], 0
	ds_read_b128 v[10:13], v202 offset:4640
	s_waitcnt lgkmcnt(1)
	v_mfma_f32_32x32x16_bf16 v[128:143], v[186:189], v[148:151], v[128:143]
	s_waitcnt lgkmcnt(0)
	v_mfma_f32_32x32x16_bf16 v[112:127], v[10:13], v[148:151], v[112:127]
	v_mfma_f32_32x32x16_bf16 v[96:111], v[186:189], v[168:171], v[96:111]
	v_mfma_f32_32x32x16_bf16 v[80:95], v[10:13], v[168:171], v[80:95]
	ds_read_b128 v[10:13], v202 offset:64
	ds_read_b128 v[186:189], v202 offset:4672
	s_waitcnt lgkmcnt(1)
	v_mfma_f32_32x32x16_bf16 v[128:143], v[10:13], v[152:155], v[128:143]
	s_waitcnt lgkmcnt(0)
	v_mfma_f32_32x32x16_bf16 v[112:127], v[186:189], v[152:155], v[112:127]
	v_mfma_f32_32x32x16_bf16 v[96:111], v[10:13], v[164:167], v[96:111]
	v_mfma_f32_32x32x16_bf16 v[80:95], v[186:189], v[164:167], v[80:95]
	ds_read_b128 v[10:13], v202 offset:96
	ds_read_b128 v[186:189], v202 offset:4704
	s_waitcnt lgkmcnt(1)
	v_mfma_f32_32x32x16_bf16 v[128:143], v[10:13], v[144:147], v[128:143]
	s_waitcnt lgkmcnt(0)
	v_mfma_f32_32x32x16_bf16 v[112:127], v[186:189], v[144:147], v[112:127]
	v_mfma_f32_32x32x16_bf16 v[96:111], v[10:13], v[160:163], v[96:111]
	v_max3_f32 v10, v128, v112, v129
	s_nop 10
	v_max_f32_e32 v11, v127, v127
	v_max3_f32 v10, v10, v113, v130
	v_max3_f32 v10, v10, v114, v131
	v_max3_f32 v10, v10, v115, v132
	v_mfma_f32_32x32x16_bf16 v[80:95], v[186:189], v[160:163], v[80:95]
	v_max3_f32 v10, v10, v116, v133
	v_max3_f32 v10, v10, v117, v134
	v_max3_f32 v10, v10, v118, v135
	v_max3_f32 v10, v10, v119, v136
	v_max3_f32 v10, v10, v120, v137
	v_max3_f32 v10, v10, v121, v138
	v_max3_f32 v10, v10, v122, v139
	v_max3_f32 v10, v10, v123, v140
	v_max3_f32 v10, v10, v124, v141
	v_max3_f32 v10, v10, v125, v142
	v_max3_f32 v10, v10, v126, v143
	s_nop 0
	v_max_f32_e32 v10, v10, v10
	v_max_f32_e32 v10, v10, v11
	v_mov_b32_e32 v11, v10
	v_nop
	v_nop
	v_permlane32_swap_b32 v10, v11
	s_nop 0
	v_max3_f32 v194, v0, v10, v11
	v_sub_f32_e32 v0, v0, v194
	v_exp_f32_e32 v14, v0
	s_nop 0
	v_cmp_neq_f32_e32 vcc, 1.0, v14
	s_cbranch_vccz .LBB0_108
	v_pk_mul_f32 v[78:79], v[78:79], v[14:15] op_sel_hi:[1,0]
	v_pk_mul_f32 v[76:77], v[76:77], v[14:15] op_sel_hi:[1,0]
	v_pk_mul_f32 v[74:75], v[74:75], v[14:15] op_sel_hi:[1,0]
	v_pk_mul_f32 v[72:73], v[72:73], v[14:15] op_sel_hi:[1,0]
	v_pk_mul_f32 v[70:71], v[70:71], v[14:15] op_sel_hi:[1,0]
	v_pk_mul_f32 v[68:69], v[68:69], v[14:15] op_sel_hi:[1,0]
	v_pk_mul_f32 v[66:67], v[66:67], v[14:15] op_sel_hi:[1,0]
	v_pk_mul_f32 v[64:65], v[64:65], v[14:15] op_sel_hi:[1,0]
	v_pk_mul_f32 v[62:63], v[62:63], v[14:15] op_sel_hi:[1,0]
	v_pk_mul_f32 v[60:61], v[60:61], v[14:15] op_sel_hi:[1,0]
	v_pk_mul_f32 v[58:59], v[58:59], v[14:15] op_sel_hi:[1,0]
	v_pk_mul_f32 v[56:57], v[56:57], v[14:15] op_sel_hi:[1,0]
	v_pk_mul_f32 v[54:55], v[54:55], v[14:15] op_sel_hi:[1,0]
	v_pk_mul_f32 v[52:53], v[52:53], v[14:15] op_sel_hi:[1,0]
	v_pk_mul_f32 v[50:51], v[50:51], v[14:15] op_sel_hi:[1,0]
	v_pk_mul_f32 v[48:49], v[48:49], v[14:15] op_sel_hi:[1,0]
.LBB0_108:
	v_max3_f32 v0, v96, v80, v97
	v_max_f32_e32 v10, v95, v95
	v_max3_f32 v0, v0, v81, v98
	v_max3_f32 v0, v0, v82, v99
	v_max3_f32 v0, v0, v83, v100
	v_max3_f32 v0, v0, v84, v101
	v_max3_f32 v0, v0, v85, v102
	v_max3_f32 v0, v0, v86, v103
	v_max3_f32 v0, v0, v87, v104
	v_max3_f32 v0, v0, v88, v105
	v_max3_f32 v0, v0, v89, v106
	v_max3_f32 v0, v0, v90, v107
	v_max3_f32 v0, v0, v91, v108
	v_max3_f32 v0, v0, v92, v109
	v_max3_f32 v0, v0, v93, v110
	v_max3_f32 v0, v0, v94, v111
	s_nop 0
	v_max_f32_e32 v0, v0, v0
	v_max_f32_e32 v0, v0, v10
	v_mov_b32_e32 v10, v0
	v_nop
	v_nop
	v_permlane32_swap_b32 v10, v0
	s_nop 0
	v_max3_f32 v195, v182, v10, v0
	v_sub_f32_e32 v0, v182, v195
	v_exp_f32_e32 v182, v0
	s_nop 0
	v_cmp_neq_f32_e32 vcc, 1.0, v182
	s_cbranch_vccz .LBB0_110
	v_pk_mul_f32 v[46:47], v[46:47], v[182:183] op_sel_hi:[1,0]
	v_pk_mul_f32 v[44:45], v[44:45], v[182:183] op_sel_hi:[1,0]
	v_pk_mul_f32 v[42:43], v[42:43], v[182:183] op_sel_hi:[1,0]
	v_pk_mul_f32 v[40:41], v[40:41], v[182:183] op_sel_hi:[1,0]
	v_pk_mul_f32 v[38:39], v[38:39], v[182:183] op_sel_hi:[1,0]
	v_pk_mul_f32 v[36:37], v[36:37], v[182:183] op_sel_hi:[1,0]
	v_pk_mul_f32 v[34:35], v[34:35], v[182:183] op_sel_hi:[1,0]
	v_pk_mul_f32 v[32:33], v[32:33], v[182:183] op_sel_hi:[1,0]
	v_pk_mul_f32 v[30:31], v[30:31], v[182:183] op_sel_hi:[1,0]
	v_pk_mul_f32 v[28:29], v[28:29], v[182:183] op_sel_hi:[1,0]
	v_pk_mul_f32 v[26:27], v[26:27], v[182:183] op_sel_hi:[1,0]
	v_pk_mul_f32 v[24:25], v[24:25], v[182:183] op_sel_hi:[1,0]
	v_pk_mul_f32 v[22:23], v[22:23], v[182:183] op_sel_hi:[1,0]
	v_pk_mul_f32 v[20:21], v[20:21], v[182:183] op_sel_hi:[1,0]
	v_pk_mul_f32 v[18:19], v[18:19], v[182:183] op_sel_hi:[1,0]
	v_pk_mul_f32 v[16:17], v[16:17], v[182:183] op_sel_hi:[1,0]

.Lgqa_stag_out:
	ds_read_b128 v[2:5], v190 offset:9216
	ds_read_b128 v[10:13], v190 offset:9312
	ds_read_b128 v[6:9], v190 offset:13824
	s_waitcnt lgkmcnt(2)
	v_mfma_f32_32x32x16_bf16 v[80:95], v[2:5], v[156:159], 0
	v_mfma_f32_32x32x16_bf16 v[112:127], v[2:5], v[172:175], 0
	ds_read_b128 v[2:5], v190 offset:9248
	s_waitcnt lgkmcnt(1)
	v_mfma_f32_32x32x16_bf16 v[96:111], v[6:9], v[156:159], 0
	v_mfma_f32_32x32x16_bf16 v[128:143], v[6:9], v[172:175], 0
	ds_read_b128 v[6:9], v190 offset:13856
	s_waitcnt lgkmcnt(1)
	v_mfma_f32_32x32x16_bf16 v[80:95], v[2:5], v[148:151], v[80:95]
	v_mfma_f32_32x32x16_bf16 v[112:127], v[2:5], v[168:171], v[112:127]
	ds_read_b128 v[2:5], v190 offset:9280
	s_waitcnt lgkmcnt(1)
	v_mfma_f32_32x32x16_bf16 v[96:111], v[6:9], v[148:151], v[96:111]
	ds_read_b128 v[148:151], v190 offset:13920
	v_mfma_f32_32x32x16_bf16 v[128:143], v[6:9], v[168:171], v[128:143]
	ds_read_b128 v[6:9], v190 offset:13888
	s_waitcnt lgkmcnt(2)
	v_mfma_f32_32x32x16_bf16 v[80:95], v[2:5], v[152:155], v[80:95]
	s_waitcnt lgkmcnt(0)
	v_mfma_f32_32x32x16_bf16 v[96:111], v[6:9], v[152:155], v[96:111]
	v_mfma_f32_32x32x16_bf16 v[80:95], v[10:13], v[144:147], v[80:95]
	v_mfma_f32_32x32x16_bf16 v[96:111], v[148:151], v[144:147], v[96:111]
	v_max3_f32 v0, v80, v96, v81
	v_max3_f32 v0, v0, v97, v82
	v_max3_f32 v0, v0, v98, v83
	v_max3_f32 v0, v0, v99, v84
	v_mfma_f32_32x32x16_bf16 v[112:127], v[2:5], v[164:167], v[112:127]
	v_max3_f32 v0, v0, v100, v85
	s_nop 7
	v_max_f32_e32 v2, v111, v111
	v_max3_f32 v0, v0, v101, v86
	v_max3_f32 v0, v0, v102, v87
	v_max3_f32 v0, v0, v103, v88
	v_mfma_f32_32x32x16_bf16 v[128:143], v[6:9], v[164:167], v[128:143]
	v_max3_f32 v0, v0, v104, v89
	v_max3_f32 v0, v0, v105, v90
	v_max3_f32 v0, v0, v106, v91
	v_max3_f32 v0, v0, v107, v92
	v_mfma_f32_32x32x16_bf16 v[112:127], v[10:13], v[160:163], v[112:127]
	v_max3_f32 v0, v0, v108, v93
	v_max3_f32 v0, v0, v109, v94
	v_max3_f32 v0, v0, v110, v95
	s_nop 0
	v_max_f32_e32 v0, v0, v0
	v_max_f32_e32 v0, v0, v2
	v_mov_b32_e32 v2, v0
	v_mfma_f32_32x32x16_bf16 v[128:143], v[148:151], v[160:163], v[128:143]
	v_nop
	v_nop
	v_permlane32_swap_b32 v0, v2
	s_nop 0
	v_max3_f32 v147, v194, v0, v2
	v_sub_f32_e32 v0, v194, v147
	v_exp_f32_e32 v14, v0
	s_nop 0
	v_cmp_neq_f32_e32 vcc, 1.0, v14
	s_cbranch_vccz .LBB0_114
	v_pk_mul_f32 v[78:79], v[78:79], v[14:15] op_sel_hi:[1,0]
	v_pk_mul_f32 v[76:77], v[76:77], v[14:15] op_sel_hi:[1,0]
	v_pk_mul_f32 v[74:75], v[74:75], v[14:15] op_sel_hi:[1,0]
	v_pk_mul_f32 v[72:73], v[72:73], v[14:15] op_sel_hi:[1,0]
	v_pk_mul_f32 v[70:71], v[70:71], v[14:15] op_sel_hi:[1,0]
	v_pk_mul_f32 v[68:69], v[68:69], v[14:15] op_sel_hi:[1,0]
	v_pk_mul_f32 v[66:67], v[66:67], v[14:15] op_sel_hi:[1,0]
	v_pk_mul_f32 v[64:65], v[64:65], v[14:15] op_sel_hi:[1,0]
	v_pk_mul_f32 v[62:63], v[62:63], v[14:15] op_sel_hi:[1,0]
	v_pk_mul_f32 v[60:61], v[60:61], v[14:15] op_sel_hi:[1,0]
	v_pk_mul_f32 v[58:59], v[58:59], v[14:15] op_sel_hi:[1,0]
	v_pk_mul_f32 v[56:57], v[56:57], v[14:15] op_sel_hi:[1,0]
	v_pk_mul_f32 v[54:55], v[54:55], v[14:15] op_sel_hi:[1,0]
	v_pk_mul_f32 v[52:53], v[52:53], v[14:15] op_sel_hi:[1,0]
	v_pk_mul_f32 v[50:51], v[50:51], v[14:15] op_sel_hi:[1,0]
	v_pk_mul_f32 v[48:49], v[48:49], v[14:15] op_sel_hi:[1,0]
.LBB0_114:
	v_max3_f32 v0, v112, v128, v113
	v_max_f32_e32 v2, v143, v143
	v_max3_f32 v0, v0, v129, v114
	v_max3_f32 v0, v0, v130, v115
	v_max3_f32 v0, v0, v131, v116
	v_max3_f32 v0, v0, v132, v117
	v_max3_f32 v0, v0, v133, v118
	v_max3_f32 v0, v0, v134, v119
	v_max3_f32 v0, v0, v135, v120
	v_max3_f32 v0, v0, v136, v121
	v_max3_f32 v0, v0, v137, v122
	v_max3_f32 v0, v0, v138, v123
	v_max3_f32 v0, v0, v139, v124
	v_max3_f32 v0, v0, v140, v125
	v_max3_f32 v0, v0, v141, v126
	v_max3_f32 v0, v0, v142, v127
	s_nop 0
	v_max_f32_e32 v0, v0, v0
	v_max_f32_e32 v0, v0, v2
	v_mov_b32_e32 v2, v0
	v_nop
	v_nop
	v_permlane32_swap_b32 v0, v2
	s_nop 0
	v_max3_f32 v2, v195, v0, v2
	v_sub_f32_e32 v0, v195, v2
	v_exp_f32_e32 v144, v0
	s_nop 0
	v_cmp_neq_f32_e32 vcc, 1.0, v144
	s_cbranch_vccz .LBB0_104
	v_pk_mul_f32 v[46:47], v[46:47], v[144:145] op_sel_hi:[1,0]
	v_pk_mul_f32 v[44:45], v[44:45], v[144:145] op_sel_hi:[1,0]
	v_pk_mul_f32 v[42:43], v[42:43], v[144:145] op_sel_hi:[1,0]
	v_pk_mul_f32 v[40:41], v[40:41], v[144:145] op_sel_hi:[1,0]
	v_pk_mul_f32 v[38:39], v[38:39], v[144:145] op_sel_hi:[1,0]
	v_pk_mul_f32 v[36:37], v[36:37], v[144:145] op_sel_hi:[1,0]
	v_pk_mul_f32 v[34:35], v[34:35], v[144:145] op_sel_hi:[1,0]
	v_pk_mul_f32 v[32:33], v[32:33], v[144:145] op_sel_hi:[1,0]
	v_pk_mul_f32 v[30:31], v[30:31], v[144:145] op_sel_hi:[1,0]
	v_pk_mul_f32 v[28:29], v[28:29], v[144:145] op_sel_hi:[1,0]
	v_pk_mul_f32 v[26:27], v[26:27], v[144:145] op_sel_hi:[1,0]
	v_pk_mul_f32 v[24:25], v[24:25], v[144:145] op_sel_hi:[1,0]
	v_pk_mul_f32 v[22:23], v[22:23], v[144:145] op_sel_hi:[1,0]
	v_pk_mul_f32 v[20:21], v[20:21], v[144:145] op_sel_hi:[1,0]
	v_pk_mul_f32 v[18:19], v[18:19], v[144:145] op_sel_hi:[1,0]
	v_pk_mul_f32 v[16:17], v[16:17], v[144:145] op_sel_hi:[1,0]
	s_branch .LBB0_104

.LBB0_123:
	v_mov_b32_e32 v68, v197
	s_and_b32 s0, s2, 0xffffff00
	s_and_b32 s17, s4, 15
	v_and_b32_e32 v7, 31, v68
	v_ashrrev_i32_e32 v0, 1, v68
	v_and_b32_e32 v0, 0xffffffe0, v0
	v_or_b32_e32 v2, s0, v7
	v_add_u32_e32 v130, v2, v0
	v_ashrrev_i32_e32 v131, 31, v130
	v_lshlrev_b64 v[2:3], 11, v[130:131]
	s_waitcnt vmcnt(0)
	v_bfe_u32 v133, v68, 5, 1
	v_lshl_add_u64 v[2:3], s[48:49], 0, v[2:3]
	s_lshl_b32 s80, s17, 7
	v_lshl_add_u64 v[2:3], v[2:3], 0, s[80:81]
	v_lshlrev_b32_e32 v0, 4, v133
	v_lshl_add_u64 v[16:17], v[2:3], 0, v[0:1]
	global_load_dwordx4 v[2:5], v[16:17], off
	global_load_dwordx4 v[8:11], v[16:17], off offset:32
	global_load_dwordx4 v[12:15], v[16:17], off offset:64
	s_nop 0
	global_load_dwordx4 v[16:19], v[16:17], off offset:96
	v_lshlrev_b32_e32 v69, 5, v133
	s_mov_b32 s20, 0x3e38aa3b
	s_lshl_b32 s1, s4, 4
	s_and_b32 s28, s1, 0xc0
	s_lshl_b32 s80, s28, 1
	s_ashr_i32 s1, s0, 31
	s_waitcnt vmcnt(3)
	v_and_b32_e32 v67, 0xffff0000, v2
	v_lshlrev_b32_e32 v66, 16, v2
	v_and_b32_e32 v63, 0xffff0000, v3
	v_lshlrev_b32_e32 v62, 16, v3
	v_pk_mul_f32 v[2:3], v[66:67], v[66:67]
	v_pk_mul_f32 v[64:65], v[62:63], v[62:63]
	v_add_f32_e32 v2, v2, v3
	v_and_b32_e32 v61, 0xffff0000, v4
	v_lshlrev_b32_e32 v60, 16, v4
	v_add_f32_e32 v2, v64, v2
	v_and_b32_e32 v57, 0xffff0000, v5
	v_lshlrev_b32_e32 v56, 16, v5
	v_pk_mul_f32 v[4:5], v[60:61], v[60:61]
	v_add_f32_e32 v2, v65, v2
	v_add_f32_e32 v2, v4, v2
	v_pk_mul_f32 v[58:59], v[56:57], v[56:57]
	v_add_f32_e32 v2, v5, v2
	s_waitcnt vmcnt(2)
	v_and_b32_e32 v55, 0xffff0000, v8
	v_lshlrev_b32_e32 v54, 16, v8
	v_add_f32_e32 v2, v58, v2
	v_and_b32_e32 v51, 0xffff0000, v9
	v_lshlrev_b32_e32 v50, 16, v9
	v_pk_mul_f32 v[8:9], v[54:55], v[54:55]
	v_add_f32_e32 v2, v59, v2
	v_add_f32_e32 v2, v8, v2
	v_pk_mul_f32 v[52:53], v[50:51], v[50:51]
	v_add_f32_e32 v2, v9, v2
	v_and_b32_e32 v49, 0xffff0000, v10
	v_lshlrev_b32_e32 v48, 16, v10
	v_add_f32_e32 v2, v52, v2
	v_and_b32_e32 v45, 0xffff0000, v11
	v_lshlrev_b32_e32 v44, 16, v11
	v_pk_mul_f32 v[10:11], v[48:49], v[48:49]
	v_add_f32_e32 v2, v53, v2
	v_add_f32_e32 v2, v10, v2
	v_pk_mul_f32 v[46:47], v[44:45], v[44:45]
	v_add_f32_e32 v2, v11, v2
	s_waitcnt vmcnt(1)
	v_and_b32_e32 v39, 0xffff0000, v13
	v_lshlrev_b32_e32 v38, 16, v13
	v_and_b32_e32 v13, 0xffff0000, v12
	v_lshlrev_b32_e32 v12, 16, v12
	v_add_f32_e32 v2, v46, v2
	v_pk_mul_f32 v[42:43], v[12:13], v[12:13]
	v_add_f32_e32 v2, v47, v2
	v_add_f32_e32 v2, v42, v2
	v_pk_mul_f32 v[40:41], v[38:39], v[38:39]
	v_add_f32_e32 v2, v43, v2
	v_and_b32_e32 v33, 0xffff0000, v15
	v_lshlrev_b32_e32 v32, 16, v15
	v_and_b32_e32 v15, 0xffff0000, v14
	v_lshlrev_b32_e32 v14, 16, v14
	v_add_f32_e32 v2, v40, v2
	v_pk_mul_f32 v[36:37], v[14:15], v[14:15]
	v_add_f32_e32 v2, v41, v2
	v_add_f32_e32 v2, v36, v2
	v_pk_mul_f32 v[34:35], v[32:33], v[32:33]
	v_add_f32_e32 v2, v37, v2
	s_waitcnt vmcnt(0)
	v_and_b32_e32 v27, 0xffff0000, v17
	v_lshlrev_b32_e32 v26, 16, v17
	v_and_b32_e32 v17, 0xffff0000, v16
	v_lshlrev_b32_e32 v16, 16, v16
	v_add_f32_e32 v2, v34, v2
	v_pk_mul_f32 v[30:31], v[16:17], v[16:17]
	v_add_f32_e32 v2, v35, v2
	v_add_f32_e32 v2, v30, v2
	v_pk_mul_f32 v[28:29], v[26:27], v[26:27]
	v_add_f32_e32 v2, v31, v2
	v_and_b32_e32 v21, 0xffff0000, v19
	v_lshlrev_b32_e32 v20, 16, v19
	v_and_b32_e32 v19, 0xffff0000, v18
	v_lshlrev_b32_e32 v18, 16, v18
	v_add_f32_e32 v2, v28, v2
	v_pk_mul_f32 v[24:25], v[18:19], v[18:19]
	v_add_f32_e32 v2, v29, v2
	v_add_f32_e32 v2, v24, v2
	v_pk_mul_f32 v[22:23], v[20:21], v[20:21]
	v_add_f32_e32 v2, v25, v2
	v_add_f32_e32 v2, v22, v2
	v_add_f32_e32 v2, v23, v2
	v_mov_b32_e32 v3, v2
	v_nop
	v_nop
	v_permlane32_swap_b32 v2, v3
	s_nop 0
	v_add_f32_e32 v2, v2, v3
	v_fmamk_f32 v2, v2, 0x3c800000, v252
	v_cmp_gt_f32_e32 vcc, s67, v2
	v_mul_f32_e32 v3, 0x4b800000, v2
	s_nop 0
	v_cndmask_b32_e32 v2, v2, v3, vcc
	v_rsq_f32_e32 v2, v2
	s_nop 0
	v_mul_f32_e32 v3, 0x45800000, v2
	v_cndmask_b32_e32 v6, v2, v3, vcc
	s_waitcnt lgkmcnt(0)
	global_load_dwordx4 v[2:5], v69, s[8:9] offset:16
	global_load_dwordx4 v[8:11], v69, s[8:9]
	s_waitcnt vmcnt(1)
	v_pk_mul_f32 v[2:3], v[2:3], v[6:7] op_sel_hi:[1,0]
	s_waitcnt vmcnt(0)
	v_pk_mul_f32 v[8:9], v[8:9], v[6:7] op_sel_hi:[1,0]
	v_pk_mul_f32 v[28:29], v[2:3], v[60:61]
	v_pk_mul_f32 v[22:23], v[8:9], v[66:67]
	v_pk_mul_f32 v[8:9], v[10:11], v[6:7] op_sel_hi:[1,0]
	v_pk_mul_f32 v[2:3], v[4:5], v[6:7] op_sel_hi:[1,0]
	v_pk_mul_f32 v[24:25], v[8:9], v[62:63]
	v_pk_mul_f32 v[30:31], v[2:3], v[56:57]
	global_load_dwordx4 v[2:5], v69, s[8:9] offset:80
	global_load_dwordx4 v[8:11], v69, s[8:9] offset:64
	s_waitcnt vmcnt(1)
	v_pk_mul_f32 v[2:3], v[6:7], v[2:3] op_sel_hi:[0,1]
	s_waitcnt vmcnt(0)
	v_pk_mul_f32 v[8:9], v[6:7], v[8:9] op_sel_hi:[0,1]
	v_pk_mul_f32 v[34:35], v[8:9], v[54:55]
	v_pk_mul_f32 v[8:9], v[6:7], v[10:11] op_sel_hi:[0,1]
	v_pk_mul_f32 v[40:41], v[2:3], v[48:49]
	v_pk_mul_f32 v[2:3], v[6:7], v[4:5] op_sel_hi:[0,1]
	v_pk_mul_f32 v[36:37], v[8:9], v[50:51]
	v_pk_mul_f32 v[42:43], v[2:3], v[44:45]
	global_load_dwordx4 v[2:5], v69, s[8:9] offset:144
	global_load_dwordx4 v[8:11], v69, s[8:9] offset:128
	s_waitcnt vmcnt(1)
	v_pk_mul_f32 v[2:3], v[6:7], v[2:3] op_sel_hi:[0,1]
	s_waitcnt vmcnt(0)
	v_pk_mul_f32 v[8:9], v[6:7], v[8:9] op_sel_hi:[0,1]
	v_pk_mul_f32 v[12:13], v[8:9], v[12:13]
	v_pk_mul_f32 v[8:9], v[6:7], v[10:11] op_sel_hi:[0,1]
	v_pk_mul_f32 v[14:15], v[2:3], v[14:15]
	v_pk_mul_f32 v[2:3], v[6:7], v[4:5] op_sel_hi:[0,1]
	v_pk_mul_f32 v[38:39], v[8:9], v[38:39]
	v_pk_mul_f32 v[32:33], v[2:3], v[32:33]
	global_load_dwordx4 v[2:5], v69, s[8:9] offset:208
	global_load_dwordx4 v[8:11], v69, s[8:9] offset:192
	v_pk_mul_f32 v[12:13], v[12:13], s[20:21] op_sel_hi:[1,0]
	s_waitcnt vmcnt(1)
	v_pk_mul_f32 v[2:3], v[6:7], v[2:3] op_sel_hi:[0,1]
	s_waitcnt vmcnt(0)
	v_pk_mul_f32 v[8:9], v[6:7], v[8:9] op_sel_hi:[0,1]
	v_pk_mul_f32 v[8:9], v[8:9], v[16:17]
	v_pk_mul_f32 v[16:17], v[22:23], s[20:21] op_sel_hi:[1,0]
	v_pk_mul_f32 v[2:3], v[2:3], v[18:19]
	v_pk_mul_f32 v[4:5], v[6:7], v[4:5] op_sel_hi:[0,1]
	v_cvt_pk_bf16_f32 v98, v16, v17
	v_pk_mul_f32 v[16:17], v[24:25], s[20:21] op_sel_hi:[1,0]
	v_pk_mul_f32 v[4:5], v[4:5], v[20:21]
	v_cvt_pk_bf16_f32 v99, v16, v17
	v_pk_mul_f32 v[16:17], v[28:29], s[20:21] op_sel_hi:[1,0]
	v_pk_mul_f32 v[2:3], v[2:3], s[20:21] op_sel_hi:[1,0]
	v_cvt_pk_bf16_f32 v100, v16, v17
	v_pk_mul_f32 v[16:17], v[30:31], s[20:21] op_sel_hi:[1,0]
	v_cvt_pk_bf16_f32 v106, v12, v13
	v_pk_mul_f32 v[12:13], v[38:39], s[20:21] op_sel_hi:[1,0]
	v_cvt_pk_bf16_f32 v112, v2, v3
	v_pk_mul_f32 v[2:3], v[4:5], s[20:21] op_sel_hi:[1,0]
	v_ashrrev_i32_e32 v4, 3, v68
	v_cvt_pk_bf16_f32 v101, v16, v17
	v_pk_mul_f32 v[16:17], v[34:35], s[20:21] op_sel_hi:[1,0]
	v_cvt_pk_bf16_f32 v107, v12, v13
	v_pk_mul_f32 v[12:13], v[14:15], s[20:21] op_sel_hi:[1,0]
	v_cvt_pk_bf16_f32 v113, v2, v3
	v_add_u32_e32 v2, s0, v4
	v_pk_mul_f32 v[10:11], v[6:7], v[10:11] op_sel_hi:[0,1]
	v_cvt_pk_bf16_f32 v102, v16, v17
	v_pk_mul_f32 v[16:17], v[36:37], s[20:21] op_sel_hi:[1,0]
	v_cvt_pk_bf16_f32 v108, v12, v13
	v_pk_mul_f32 v[12:13], v[32:33], s[20:21] op_sel_hi:[1,0]
	v_ashrrev_i32_e32 v3, 31, v2
	v_lshlrev_b32_e32 v6, 4, v68
	v_pk_mul_f32 v[10:11], v[10:11], v[26:27]
	v_cvt_pk_bf16_f32 v103, v16, v17
	v_pk_mul_f32 v[16:17], v[40:41], s[20:21] op_sel_hi:[1,0]
	v_cvt_pk_bf16_f32 v109, v12, v13
	v_pk_mul_f32 v[8:9], v[8:9], s[20:21] op_sel_hi:[1,0]
	v_and_b32_e32 v12, 0x70, v6
	v_lshlrev_b64 v[2:3], 9, v[2:3]
	v_cvt_pk_bf16_f32 v104, v16, v17
	v_pk_mul_f32 v[16:17], v[42:43], s[20:21] op_sel_hi:[1,0]
	v_cvt_pk_bf16_f32 v110, v8, v9
	v_pk_mul_f32 v[8:9], v[10:11], s[20:21] op_sel_hi:[1,0]
	v_mad_u64_u32 v[4:5], s[20:21], v4, s42, v[12:13]
	v_lshl_add_u64 v[2:3], s[10:11], 0, v[2:3]
	v_ashrrev_i32_e32 v10, 4, v68
	v_lshlrev_b32_e32 v5, 3, v68
	v_lshl_add_u64 v[2:3], v[2:3], 0, s[80:81]
	v_mov_b32_e32 v13, v1
	v_cvt_pk_bf16_f32 v111, v8, v9
	v_add_u32_e32 v8, s28, v10
	v_and_b32_e32 v5, 8, v5
	s_movk_i32 s20, 0xe0
	v_lshl_add_u64 v[2:3], v[2:3], 0, v[12:13]
	v_mov_b64_e32 v[12:13], s[18:19]
	v_and_or_b32 v6, v6, s20, v5
	v_mad_i64_i32 v[8:9], s[20:21], v8, s68, v[12:13]
	v_and_b32_e32 v11, 15, v68
	v_lshl_add_u64 v[8:9], s[0:1], 1, v[8:9]
	s_mov_b32 s0, 0x8000
	v_cvt_pk_bf16_f32 v105, v16, v17
	v_lshlrev_b32_e32 v12, 4, v11
	v_mov_b32_e32 v13, v1
	v_add_co_u32_e32 v16, vcc, s0, v2
	v_lshl_add_u64 v[8:9], v[8:9], 0, v[12:13]
	s_nop 0
	v_addc_co_u32_e32 v17, vcc, 0, v3, vcc
	v_add_co_u32_e32 v28, vcc, s41, v8
	global_load_dwordx4 v[12:15], v[2:3], off
	s_nop 0
	global_load_dwordx4 v[16:19], v[16:17], off
	s_nop 0
	global_load_dwordx4 v[20:23], v[8:9], off
	v_addc_co_u32_e32 v29, vcc, 0, v9, vcc
	global_load_dwordx4 v[24:27], v[28:29], off
	v_mad_u64_u32 v[10:11], s[0:1], v10, s43, v[6:7]
	v_add_u32_e32 v135, 0, v10
	v_add_u32_e32 v136, 0, v4
	v_add_u32_e32 v4, 0x9000, v135
	s_waitcnt vmcnt(3)
	ds_write_b128 v136, v[12:15]
	s_waitcnt vmcnt(2)
	ds_write_b128 v136, v[16:19] offset:9216
	s_waitcnt vmcnt(1)
	ds_write2_b64 v4, v[20:21], v[22:23] offset1:2
	v_add_u32_e32 v4, 0xb000, v135
	s_mov_b32 s0, 0x10000
	s_waitcnt vmcnt(0)
	ds_write2_b64 v4, v[24:25], v[26:27] offset0:64 offset1:66
	v_mad_u32_u24 v4, v7, s42, 0
	v_add_u32_e32 v132, v4, v0
	v_lshl_add_u32 v4, v7, 7, v4
	v_add_u32_e32 v134, v4, v0
	v_add_co_u32_e32 v4, vcc, s0, v2
	s_mov_b32 s0, 0x18000
	s_nop 0
	v_addc_co_u32_e32 v5, vcc, 0, v3, vcc
	v_add_co_u32_e32 v2, vcc, s0, v2
	s_waitcnt lgkmcnt(0)
	s_nop 0
	v_addc_co_u32_e32 v3, vcc, 0, v3, vcc
	s_barrier
	global_load_dwordx4 v[66:69], v[4:5], off
	global_load_dwordx4 v[78:81], v[2:3], off
	global_load_dwordx4 v[74:77], v[8:9], off offset:256
	global_load_dwordx4 v[70:73], v[28:29], off offset:256
	ds_read_b128 v[2:5], v132 offset:4608
	ds_read_b128 v[6:9], v132
	ds_read_b128 v[34:37], v132 offset:32
	ds_read_b128 v[38:41], v132 offset:4640
	ds_read_b128 v[42:45], v132 offset:64
	ds_read_b128 v[46:49], v132 offset:4672
	ds_read_b128 v[50:53], v132 offset:96
	ds_read_b128 v[54:57], v132 offset:4704
	s_waitcnt lgkmcnt(6)
	v_mfma_f32_32x32x16_bf16 v[18:33], v[6:9], v[98:101], 0
	v_mfma_f32_32x32x16_bf16 v[2:17], v[2:5], v[98:101], 0
	s_waitcnt lgkmcnt(5)
	v_mfma_f32_32x32x16_bf16 v[18:33], v[34:37], v[102:105], v[18:33]
	s_waitcnt lgkmcnt(4)
	v_mfma_f32_32x32x16_bf16 v[2:17], v[38:41], v[102:105], v[2:17]
	s_waitcnt lgkmcnt(3)
	v_mfma_f32_32x32x16_bf16 v[18:33], v[42:45], v[106:109], v[18:33]
	s_waitcnt lgkmcnt(2)
	v_mfma_f32_32x32x16_bf16 v[2:17], v[46:49], v[106:109], v[2:17]
	s_waitcnt lgkmcnt(1)
	v_mfma_f32_32x32x16_bf16 v[18:33], v[50:53], v[110:113], v[18:33]
	s_waitcnt lgkmcnt(0)
	v_mfma_f32_32x32x16_bf16 v[2:17], v[54:57], v[110:113], v[2:17]
	ds_read_b128 v[34:37], v132 offset:9216
	ds_read_b128 v[82:85], v132 offset:9248
	ds_read_b128 v[38:41], v132 offset:13824
	ds_read_b128 v[86:89], v132 offset:13856
	ds_read_b128 v[90:93], v132 offset:9280
	ds_read_b128 v[94:97], v132 offset:9312
	ds_read_b128 v[114:117], v132 offset:13888
	ds_read_b128 v[118:121], v132 offset:13920
	s_waitcnt lgkmcnt(7)
	v_mfma_f32_32x32x16_bf16 v[50:65], v[34:37], v[98:101], 0
	s_waitcnt lgkmcnt(5)
	v_mfma_f32_32x32x16_bf16 v[34:49], v[38:41], v[98:101], 0
	v_mfma_f32_32x32x16_bf16 v[50:65], v[82:85], v[102:105], v[50:65]
	s_waitcnt lgkmcnt(4)
	v_mfma_f32_32x32x16_bf16 v[34:49], v[86:89], v[102:105], v[34:49]
	s_waitcnt lgkmcnt(3)
	v_mfma_f32_32x32x16_bf16 v[50:65], v[90:93], v[106:109], v[50:65]
	s_waitcnt lgkmcnt(1)
	v_mfma_f32_32x32x16_bf16 v[34:49], v[114:117], v[106:109], v[34:49]
	v_mfma_f32_32x32x16_bf16 v[50:65], v[94:97], v[110:113], v[50:65]
	s_waitcnt lgkmcnt(0)
	v_mfma_f32_32x32x16_bf16 v[34:49], v[118:121], v[110:113], v[34:49]
	ds_read_b128 v[82:85], v134 offset:36864
	ds_read_b128 v[86:89], v134 offset:36896
	ds_read_b128 v[90:93], v134 offset:36928
	ds_read_b128 v[94:97], v134 offset:36960
	ds_read_b128 v[114:117], v134 offset:45568
	ds_read_b128 v[118:121], v134 offset:45600
	ds_read_b128 v[122:125], v134 offset:45632
	ds_read_b128 v[126:129], v134 offset:45664
	v_max3_f32 v0, v18, v2, v19
	v_max_f32_e32 v137, v17, v17
	v_max3_f32 v0, v0, v3, v20
	s_mov_b32 s0, 0xf149f2ca
	v_max3_f32 v0, v0, v4, v21
	v_max3_f32 v0, v0, v5, v22
	v_max3_f32 v0, v0, v6, v23
	v_max3_f32 v0, v0, v7, v24
	v_max3_f32 v0, v0, v8, v25
	v_max3_f32 v0, v0, v9, v26
	v_max3_f32 v0, v0, v10, v27
	v_max3_f32 v0, v0, v11, v28
	v_max3_f32 v0, v0, v12, v29
	v_max3_f32 v0, v0, v13, v30
	v_max3_f32 v0, v0, v14, v31
	v_max3_f32 v0, v0, v15, v32
	v_max3_f32 v0, v0, v16, v33
	s_nop 0
	v_max_f32_e32 v0, v0, v0
	v_max_f32_e32 v0, v0, v137
	v_mov_b32_e32 v137, v0
	v_nop
	v_nop
	v_permlane32_swap_b32 v0, v137
	s_nop 0
	v_max3_f32 v0, v0, v137, s0
	v_sub_f32_e32 v2, v2, v0
	v_exp_f32_e32 v138, v2
	v_sub_f32_e32 v2, v19, v0
	v_exp_f32_e32 v139, v2
	v_sub_f32_e32 v2, v3, v0
	v_exp_f32_e32 v140, v2
	v_sub_f32_e32 v2, v20, v0
	v_exp_f32_e32 v141, v2
	v_sub_f32_e32 v2, v4, v0
	v_exp_f32_e32 v142, v2
	v_sub_f32_e32 v2, v21, v0
	v_exp_f32_e32 v143, v2
	v_sub_f32_e32 v2, v5, v0
	v_exp_f32_e32 v144, v2
	v_sub_f32_e32 v2, v22, v0
	v_exp_f32_e32 v145, v2
	v_sub_f32_e32 v2, v6, v0
	v_exp_f32_e32 v146, v2
	v_sub_f32_e32 v2, v23, v0
	v_exp_f32_e32 v147, v2
	v_sub_f32_e32 v2, v7, v0
	v_exp_f32_e32 v148, v2
	v_sub_f32_e32 v2, v24, v0
	v_exp_f32_e32 v149, v2
	v_sub_f32_e32 v2, v8, v0
	v_exp_f32_e32 v150, v2
	v_sub_f32_e32 v2, v25, v0
	v_exp_f32_e32 v151, v2
	v_sub_f32_e32 v2, v9, v0
	v_exp_f32_e32 v152, v2
	v_sub_f32_e32 v2, v26, v0
	v_exp_f32_e32 v153, v2
	v_sub_f32_e32 v2, v10, v0
	v_exp_f32_e32 v154, v2
	v_sub_f32_e32 v2, v27, v0
	v_exp_f32_e32 v155, v2
	v_sub_f32_e32 v2, v11, v0
	v_exp_f32_e32 v156, v2
	v_sub_f32_e32 v2, v28, v0
	v_exp_f32_e32 v157, v2
	v_sub_f32_e32 v2, v12, v0
	v_exp_f32_e32 v158, v2
	v_sub_f32_e32 v2, v29, v0
	v_exp_f32_e32 v159, v2
	v_sub_f32_e32 v2, v13, v0
	v_exp_f32_e32 v160, v2
	v_sub_f32_e32 v2, v30, v0
	v_exp_f32_e32 v161, v2
	v_sub_f32_e32 v2, v14, v0
	v_sub_f32_e32 v167, 0xf149f2ca, v0
	v_exp_f32_e32 v162, v2
	v_sub_f32_e32 v2, v31, v0
	v_exp_f32_e32 v163, v2
	v_sub_f32_e32 v2, v15, v0
	v_exp_f32_e32 v3, v167
	v_exp_f32_e32 v164, v2
	v_sub_f32_e32 v2, v32, v0
	v_exp_f32_e32 v165, v2
	v_sub_f32_e32 v2, v16, v0
	v_exp_f32_e32 v166, v2
	v_sub_f32_e32 v2, v33, v0
	v_sub_f32_e32 v18, v18, v0
	v_exp_f32_e32 v167, v2
	v_sub_f32_e32 v2, v17, v0
	v_cmp_neq_f32_e32 vcc, 1.0, v3
	v_exp_f32_e32 v137, v18
	v_exp_f32_e32 v169, v2
	s_cmp_lg_u64 vcc, 0
	v_mul_f32_e32 v168, 0, v3
	s_cselect_b64 vcc, -1, 0
	v_cndmask_b32_e32 v2, 0, v168, vcc
	v_mov_b32_e32 v3, v2
	v_mov_b32_e32 v4, v2
	v_mov_b32_e32 v5, v2
	v_mov_b32_e32 v6, v2
	v_mov_b32_e32 v7, v2
	v_mov_b32_e32 v8, v2
	v_mov_b32_e32 v9, v2
	v_mov_b32_e32 v10, v2
	v_mov_b32_e32 v11, v2
	v_mov_b32_e32 v12, v2
	v_mov_b32_e32 v13, v2
	v_mov_b32_e32 v14, v2
	v_mov_b32_e32 v15, v2
	v_mov_b32_e32 v16, v2
	v_mov_b32_e32 v17, v2
	v_cvt_pk_bf16_f32 v170, v154, v156
	v_cvt_pk_bf16_f32 v171, v158, v160
	v_cvt_pk_bf16_f32 v172, v162, v164
	v_cvt_pk_bf16_f32 v173, v166, v169
	v_cvt_pk_bf16_f32 v174, v138, v140
	v_cvt_pk_bf16_f32 v175, v142, v144
	v_cvt_pk_bf16_f32 v176, v146, v148
	v_cvt_pk_bf16_f32 v177, v150, v152
	v_cvt_pk_bf16_f32 v178, v153, v155
	v_cvt_pk_bf16_f32 v179, v157, v159
	v_cvt_pk_bf16_f32 v180, v161, v163
	v_cvt_pk_bf16_f32 v181, v165, v167
	v_cvt_pk_bf16_f32 v182, v137, v139
	v_cvt_pk_bf16_f32 v183, v141, v143
	v_cvt_pk_bf16_f32 v184, v145, v147
	v_cvt_pk_bf16_f32 v185, v149, v151
	s_waitcnt lgkmcnt(7)
	s_nop 0
	v_mfma_f32_32x32x16_bf16 v[18:33], v[82:85], v[182:185], v[2:17]
	s_waitcnt lgkmcnt(3)
	v_mfma_f32_32x32x16_bf16 v[2:17], v[114:117], v[182:185], v[2:17]
	v_mfma_f32_32x32x16_bf16 v[18:33], v[86:89], v[178:181], v[18:33]
	s_waitcnt lgkmcnt(2)
	v_mfma_f32_32x32x16_bf16 v[2:17], v[118:121], v[178:181], v[2:17]
	v_mfma_f32_32x32x16_bf16 v[18:33], v[90:93], v[174:177], v[18:33]
	s_waitcnt lgkmcnt(1)
	v_mfma_f32_32x32x16_bf16 v[2:17], v[122:125], v[174:177], v[2:17]
	v_mfma_f32_32x32x16_bf16 v[18:33], v[94:97], v[170:173], v[18:33]
	s_waitcnt lgkmcnt(0)
	v_mfma_f32_32x32x16_bf16 v[2:17], v[126:129], v[170:173], v[2:17]
	ds_read_b128 v[126:129], v134 offset:36992
	ds_read_b128 v[122:125], v134 offset:37024
	ds_read_b128 v[118:121], v134 offset:37056
	ds_read_b128 v[114:117], v134 offset:37088
	ds_read_b128 v[94:97], v134 offset:45696
	ds_read_b128 v[90:93], v134 offset:45728
	ds_read_b128 v[86:89], v134 offset:45760
	ds_read_b128 v[82:85], v134 offset:45792
	v_max3_f32 v170, v50, v34, v51
	v_max_f32_e32 v171, v49, v49
	v_max3_f32 v170, v170, v35, v52
	v_max3_f32 v170, v170, v36, v53
	v_max3_f32 v170, v170, v37, v54
	v_max3_f32 v170, v170, v38, v55
	v_max3_f32 v170, v170, v39, v56
	v_max3_f32 v170, v170, v40, v57
	v_max3_f32 v170, v170, v41, v58
	v_max3_f32 v170, v170, v42, v59
	v_max3_f32 v170, v170, v43, v60
	v_max3_f32 v170, v170, v44, v61
	v_max3_f32 v170, v170, v45, v62
	v_max3_f32 v170, v170, v46, v63
	v_max3_f32 v170, v170, v47, v64
	v_max3_f32 v170, v170, v48, v65
	s_nop 0
	v_max_f32_e32 v170, v170, v170
	v_max_f32_e32 v170, v170, v171
	v_mov_b32_e32 v171, v170
	v_nop
	v_nop
	v_permlane32_swap_b32 v170, v171
	s_nop 0
	v_max3_f32 v208, v0, v170, v171
	v_sub_f32_e32 v0, v0, v208
	v_exp_f32_e32 v0, v0
	s_nop 0
	v_cmp_neq_f32_e32 vcc, 1.0, v0
	s_cbranch_vccz .LBB0_125
	v_pk_mul_f32 v[32:33], v[32:33], v[0:1] op_sel_hi:[1,0]
	v_pk_mul_f32 v[30:31], v[30:31], v[0:1] op_sel_hi:[1,0]
	v_pk_mul_f32 v[28:29], v[28:29], v[0:1] op_sel_hi:[1,0]
	v_pk_mul_f32 v[26:27], v[26:27], v[0:1] op_sel_hi:[1,0]
	v_pk_mul_f32 v[24:25], v[24:25], v[0:1] op_sel_hi:[1,0]
	v_pk_mul_f32 v[22:23], v[22:23], v[0:1] op_sel_hi:[1,0]
	v_pk_mul_f32 v[20:21], v[20:21], v[0:1] op_sel_hi:[1,0]
	v_pk_mul_f32 v[18:19], v[18:19], v[0:1] op_sel_hi:[1,0]
	v_pk_mul_f32 v[16:17], v[16:17], v[0:1] op_sel_hi:[1,0]
	v_pk_mul_f32 v[14:15], v[14:15], v[0:1] op_sel_hi:[1,0]
	v_pk_mul_f32 v[12:13], v[12:13], v[0:1] op_sel_hi:[1,0]
	v_pk_mul_f32 v[10:11], v[10:11], v[0:1] op_sel_hi:[1,0]
	v_pk_mul_f32 v[8:9], v[8:9], v[0:1] op_sel_hi:[1,0]
	v_pk_mul_f32 v[6:7], v[6:7], v[0:1] op_sel_hi:[1,0]
	v_pk_mul_f32 v[4:5], v[4:5], v[0:1] op_sel_hi:[1,0]
	v_pk_mul_f32 v[2:3], v[2:3], v[0:1] op_sel_hi:[1,0]
.LBB0_125:
	v_sub_f32_e32 v34, v34, v208
	v_exp_f32_e32 v171, v34
	v_sub_f32_e32 v34, v51, v208
	v_exp_f32_e32 v172, v34
	v_sub_f32_e32 v34, v35, v208
	v_exp_f32_e32 v173, v34
	v_sub_f32_e32 v34, v52, v208
	v_exp_f32_e32 v174, v34
	v_sub_f32_e32 v34, v36, v208
	v_exp_f32_e32 v175, v34
	v_sub_f32_e32 v34, v53, v208
	v_exp_f32_e32 v176, v34
	v_sub_f32_e32 v34, v37, v208
	v_exp_f32_e32 v177, v34
	v_sub_f32_e32 v34, v54, v208
	v_exp_f32_e32 v178, v34
	v_sub_f32_e32 v34, v38, v208
	v_exp_f32_e32 v179, v34
	v_sub_f32_e32 v34, v55, v208
	v_exp_f32_e32 v180, v34
	v_sub_f32_e32 v34, v39, v208
	v_exp_f32_e32 v181, v34
	v_sub_f32_e32 v34, v56, v208
	v_exp_f32_e32 v182, v34
	v_sub_f32_e32 v34, v40, v208
	v_exp_f32_e32 v183, v34
	v_sub_f32_e32 v34, v57, v208
	v_exp_f32_e32 v184, v34
	v_sub_f32_e32 v34, v41, v208
	v_exp_f32_e32 v185, v34
	v_sub_f32_e32 v34, v58, v208
	v_exp_f32_e32 v186, v34
	v_sub_f32_e32 v34, v42, v208
	v_exp_f32_e32 v187, v34
	v_sub_f32_e32 v34, v59, v208
	v_exp_f32_e32 v188, v34
	v_sub_f32_e32 v34, v43, v208
	v_exp_f32_e32 v189, v34
	v_sub_f32_e32 v34, v60, v208
	v_exp_f32_e32 v190, v34
	v_sub_f32_e32 v34, v44, v208
	v_exp_f32_e32 v191, v34
	v_sub_f32_e32 v34, v61, v208
	v_exp_f32_e32 v192, v34
	v_sub_f32_e32 v34, v45, v208
	v_exp_f32_e32 v193, v34
	v_sub_f32_e32 v34, v62, v208
	v_exp_f32_e32 v194, v34
	v_sub_f32_e32 v34, v46, v208
	v_exp_f32_e32 v195, v34
	v_sub_f32_e32 v34, v63, v208
	v_exp_f32_e32 v202, v34
	v_sub_f32_e32 v34, v47, v208
	v_exp_f32_e32 v203, v34
	v_sub_f32_e32 v34, v64, v208
	v_exp_f32_e32 v204, v34
	v_sub_f32_e32 v34, v48, v208
	v_exp_f32_e32 v205, v34
	v_sub_f32_e32 v34, v65, v208
	v_sub_f32_e32 v50, v50, v208
	v_exp_f32_e32 v206, v34
	v_sub_f32_e32 v34, v49, v208
	v_exp_f32_e32 v170, v50
	v_exp_f32_e32 v207, v34
	v_cvt_pk_bf16_f32 v34, v187, v189
	v_cvt_pk_bf16_f32 v35, v191, v193
	v_cvt_pk_bf16_f32 v36, v195, v203
	v_cvt_pk_bf16_f32 v37, v205, v207
	v_cvt_pk_bf16_f32 v38, v171, v173
	v_cvt_pk_bf16_f32 v39, v175, v177
	v_cvt_pk_bf16_f32 v40, v179, v181
	v_cvt_pk_bf16_f32 v41, v183, v185
	v_cvt_pk_bf16_f32 v42, v186, v188
	v_cvt_pk_bf16_f32 v43, v190, v192
	v_cvt_pk_bf16_f32 v44, v194, v202
	v_cvt_pk_bf16_f32 v45, v204, v206
	v_cvt_pk_bf16_f32 v46, v170, v172
	v_cvt_pk_bf16_f32 v47, v174, v176
	v_cvt_pk_bf16_f32 v48, v178, v180
	v_cvt_pk_bf16_f32 v49, v182, v184
	s_waitcnt lgkmcnt(7)
	s_nop 0
	v_mfma_f32_32x32x16_bf16 v[18:33], v[126:129], v[46:49], v[18:33]
	s_waitcnt lgkmcnt(3)
	v_mfma_f32_32x32x16_bf16 v[2:17], v[94:97], v[46:49], v[2:17]
	v_mfma_f32_32x32x16_bf16 v[18:33], v[122:125], v[42:45], v[18:33]
	s_waitcnt lgkmcnt(2)
	v_mfma_f32_32x32x16_bf16 v[2:17], v[90:93], v[42:45], v[2:17]
	v_mfma_f32_32x32x16_bf16 v[18:33], v[118:121], v[38:41], v[18:33]
	s_waitcnt lgkmcnt(1)
	v_mfma_f32_32x32x16_bf16 v[2:17], v[86:89], v[38:41], v[2:17]
	v_mfma_f32_32x32x16_bf16 v[18:33], v[114:117], v[34:37], v[18:33]
	s_waitcnt lgkmcnt(0)
	v_mfma_f32_32x32x16_bf16 v[2:17], v[82:85], v[34:37], v[2:17]
	v_add_u32_e32 v34, 0xd000, v135
	s_waitcnt vmcnt(3)
	ds_write_b128 v136, v[66:69] offset:18432
	s_waitcnt vmcnt(2)
	ds_write_b128 v136, v[78:81] offset:27648
	s_waitcnt vmcnt(1)
	ds_write2_b64 v34, v[74:75], v[76:77] offset0:128 offset1:130
	v_add_u32_e32 v34, 0xf000, v135
	s_waitcnt vmcnt(0)
	ds_write2_b64 v34, v[70:71], v[72:73] offset0:192 offset1:194
	s_waitcnt lgkmcnt(0)
	s_barrier
	ds_read_b128 v[34:37], v132 offset:18432
	ds_read_b128 v[38:41], v132 offset:18464
	ds_read_b128 v[42:45], v132 offset:23040
	ds_read_b128 v[46:49], v132 offset:23072
	ds_read_b128 v[50:53], v132 offset:18496
	ds_read_b128 v[54:57], v132 offset:18528
	ds_read_b128 v[58:61], v132 offset:23104
	ds_read_b128 v[62:65], v132 offset:23136
	s_waitcnt lgkmcnt(7)
	v_mfma_f32_32x32x16_bf16 v[82:97], v[34:37], v[98:101], 0
	s_waitcnt lgkmcnt(5)
	v_mfma_f32_32x32x16_bf16 v[66:81], v[42:45], v[98:101], 0
	v_mfma_f32_32x32x16_bf16 v[82:97], v[38:41], v[102:105], v[82:97]
	s_waitcnt lgkmcnt(4)
	v_mfma_f32_32x32x16_bf16 v[66:81], v[46:49], v[102:105], v[66:81]
	s_waitcnt lgkmcnt(3)
	v_mfma_f32_32x32x16_bf16 v[82:97], v[50:53], v[106:109], v[82:97]
	s_waitcnt lgkmcnt(1)
	v_mfma_f32_32x32x16_bf16 v[66:81], v[58:61], v[106:109], v[66:81]
	v_mfma_f32_32x32x16_bf16 v[82:97], v[54:57], v[110:113], v[82:97]
	s_waitcnt lgkmcnt(0)
	v_mfma_f32_32x32x16_bf16 v[66:81], v[62:65], v[110:113], v[66:81]
	ds_read_b128 v[34:37], v132 offset:27648
	ds_read_b128 v[114:117], v132 offset:27680
	ds_read_b128 v[38:41], v132 offset:32256
	ds_read_b128 v[118:121], v132 offset:32288
	ds_read_b128 v[122:125], v132 offset:27712
	ds_read_b128 v[126:129], v132 offset:27744
	ds_read_b128 v[198:201], v132 offset:32320
	ds_read_b128 v[210:213], v132 offset:32352
	s_waitcnt lgkmcnt(7)
	v_mfma_f32_32x32x16_bf16 v[50:65], v[34:37], v[98:101], 0
	s_waitcnt lgkmcnt(5)
	v_mfma_f32_32x32x16_bf16 v[34:49], v[38:41], v[98:101], 0
	v_mfma_f32_32x32x16_bf16 v[50:65], v[114:117], v[102:105], v[50:65]
	s_waitcnt lgkmcnt(4)
	v_mfma_f32_32x32x16_bf16 v[34:49], v[118:121], v[102:105], v[34:49]
	s_waitcnt lgkmcnt(3)
	v_mfma_f32_32x32x16_bf16 v[50:65], v[122:125], v[106:109], v[50:65]
	s_waitcnt lgkmcnt(1)
	v_mfma_f32_32x32x16_bf16 v[34:49], v[198:201], v[106:109], v[34:49]
	v_mfma_f32_32x32x16_bf16 v[50:65], v[126:129], v[110:113], v[50:65]
	s_waitcnt lgkmcnt(0)
	v_mfma_f32_32x32x16_bf16 v[34:49], v[210:213], v[110:113], v[34:49]
	ds_read_b128 v[126:129], v134 offset:54272
	ds_read_b128 v[122:125], v134 offset:54304
	ds_read_b128 v[118:121], v134 offset:54336
	ds_read_b128 v[114:117], v134 offset:54368
	ds_read_b128 v[110:113], v134 offset:62976
	ds_read_b128 v[106:109], v134 offset:63008
	ds_read_b128 v[102:105], v134 offset:63040
	ds_read_b128 v[98:101], v134 offset:63072
	v_max3_f32 v132, v82, v66, v83
	v_max_f32_e32 v135, v81, v81
	v_max3_f32 v132, v132, v67, v84
	v_max3_f32 v132, v132, v68, v85
	v_max3_f32 v132, v132, v69, v86
	v_max3_f32 v132, v132, v70, v87
	v_max3_f32 v132, v132, v71, v88
	v_max3_f32 v132, v132, v72, v89
	v_max3_f32 v132, v132, v73, v90
	v_max3_f32 v132, v132, v74, v91
	v_max3_f32 v132, v132, v75, v92
	v_max3_f32 v132, v132, v76, v93
	v_max3_f32 v132, v132, v77, v94
	v_max3_f32 v132, v132, v78, v95
	v_max3_f32 v132, v132, v79, v96
	v_max3_f32 v132, v132, v80, v97
	s_nop 0
	v_max_f32_e32 v132, v132, v132
	v_max_f32_e32 v132, v132, v135
	v_mov_b32_e32 v135, v132
	v_nop
	v_nop
	v_permlane32_swap_b32 v132, v135
	s_nop 0
	v_max3_f32 v247, v208, v132, v135
	v_sub_f32_e32 v132, v208, v247
	v_exp_f32_e32 v132, v132
	s_nop 0
	v_cmp_neq_f32_e32 vcc, 1.0, v132
	s_cbranch_vccz .LBB0_127
	v_pk_mul_f32 v[32:33], v[32:33], v[132:133] op_sel_hi:[1,0]
	v_pk_mul_f32 v[30:31], v[30:31], v[132:133] op_sel_hi:[1,0]
	v_pk_mul_f32 v[28:29], v[28:29], v[132:133] op_sel_hi:[1,0]
	v_pk_mul_f32 v[26:27], v[26:27], v[132:133] op_sel_hi:[1,0]
	v_pk_mul_f32 v[24:25], v[24:25], v[132:133] op_sel_hi:[1,0]
	v_pk_mul_f32 v[22:23], v[22:23], v[132:133] op_sel_hi:[1,0]
	v_pk_mul_f32 v[20:21], v[20:21], v[132:133] op_sel_hi:[1,0]
	v_pk_mul_f32 v[18:19], v[18:19], v[132:133] op_sel_hi:[1,0]
	v_pk_mul_f32 v[16:17], v[16:17], v[132:133] op_sel_hi:[1,0]
	v_pk_mul_f32 v[14:15], v[14:15], v[132:133] op_sel_hi:[1,0]
	v_pk_mul_f32 v[12:13], v[12:13], v[132:133] op_sel_hi:[1,0]
	v_pk_mul_f32 v[10:11], v[10:11], v[132:133] op_sel_hi:[1,0]
	v_pk_mul_f32 v[8:9], v[8:9], v[132:133] op_sel_hi:[1,0]
	v_pk_mul_f32 v[6:7], v[6:7], v[132:133] op_sel_hi:[1,0]
	v_pk_mul_f32 v[4:5], v[4:5], v[132:133] op_sel_hi:[1,0]
	v_pk_mul_f32 v[2:3], v[2:3], v[132:133] op_sel_hi:[1,0]
.LBB0_127:
	v_sub_f32_e32 v66, v66, v247
	v_exp_f32_e32 v136, v66
	v_sub_f32_e32 v66, v83, v247
	v_exp_f32_e32 v208, v66
	v_sub_f32_e32 v66, v67, v247
	v_exp_f32_e32 v209, v66
	v_sub_f32_e32 v66, v84, v247
	v_exp_f32_e32 v219, v66
	v_sub_f32_e32 v66, v68, v247
	v_exp_f32_e32 v220, v66
	v_sub_f32_e32 v66, v85, v247
	v_exp_f32_e32 v221, v66
	v_sub_f32_e32 v66, v69, v247
	v_exp_f32_e32 v222, v66
	v_sub_f32_e32 v66, v86, v247
	v_exp_f32_e32 v223, v66
	v_sub_f32_e32 v66, v70, v247
	v_exp_f32_e32 v224, v66
	v_sub_f32_e32 v66, v87, v247
	v_exp_f32_e32 v225, v66
	v_sub_f32_e32 v66, v71, v247
	v_exp_f32_e32 v226, v66
	v_sub_f32_e32 v66, v88, v247
	v_exp_f32_e32 v227, v66
	v_sub_f32_e32 v66, v72, v247
	v_exp_f32_e32 v228, v66
	v_sub_f32_e32 v66, v89, v247
	v_exp_f32_e32 v229, v66
	v_sub_f32_e32 v66, v73, v247
	v_exp_f32_e32 v230, v66
	v_sub_f32_e32 v66, v90, v247
	v_exp_f32_e32 v231, v66
	v_sub_f32_e32 v66, v74, v247
	v_exp_f32_e32 v232, v66
	v_sub_f32_e32 v66, v91, v247
	v_exp_f32_e32 v233, v66
	v_sub_f32_e32 v66, v75, v247
	v_exp_f32_e32 v234, v66
	v_sub_f32_e32 v66, v92, v247
	v_exp_f32_e32 v235, v66
	v_sub_f32_e32 v66, v76, v247
	v_exp_f32_e32 v236, v66
	v_sub_f32_e32 v66, v93, v247
	v_exp_f32_e32 v237, v66
	v_sub_f32_e32 v66, v77, v247
	v_exp_f32_e32 v238, v66
	v_sub_f32_e32 v66, v94, v247
	v_exp_f32_e32 v239, v66
	v_sub_f32_e32 v66, v78, v247
	v_exp_f32_e32 v240, v66
	v_sub_f32_e32 v66, v95, v247
	v_exp_f32_e32 v241, v66
	v_sub_f32_e32 v66, v79, v247
	v_exp_f32_e32 v242, v66
	v_sub_f32_e32 v66, v96, v247
	v_exp_f32_e32 v243, v66
	v_sub_f32_e32 v66, v80, v247
	v_exp_f32_e32 v244, v66
	v_sub_f32_e32 v66, v97, v247
	v_sub_f32_e32 v82, v82, v247
	v_exp_f32_e32 v245, v66
	v_sub_f32_e32 v66, v81, v247
	v_exp_f32_e32 v135, v82
	v_exp_f32_e32 v246, v66
	v_cvt_pk_bf16_f32 v66, v232, v234
	v_cvt_pk_bf16_f32 v67, v236, v238
	v_cvt_pk_bf16_f32 v68, v240, v242
	v_cvt_pk_bf16_f32 v69, v244, v246
	v_cvt_pk_bf16_f32 v70, v136, v209
	v_cvt_pk_bf16_f32 v71, v220, v222
	v_cvt_pk_bf16_f32 v72, v224, v226
	v_cvt_pk_bf16_f32 v73, v228, v230
	v_cvt_pk_bf16_f32 v74, v231, v233
	v_cvt_pk_bf16_f32 v75, v235, v237
	v_cvt_pk_bf16_f32 v76, v239, v241
	v_cvt_pk_bf16_f32 v77, v243, v245
	v_cvt_pk_bf16_f32 v78, v135, v208
	v_cvt_pk_bf16_f32 v79, v219, v221
	v_cvt_pk_bf16_f32 v80, v223, v225
	v_cvt_pk_bf16_f32 v81, v227, v229
	s_waitcnt lgkmcnt(7)
	s_nop 0
	v_mfma_f32_32x32x16_bf16 v[18:33], v[126:129], v[78:81], v[18:33]
	s_waitcnt lgkmcnt(3)
	v_mfma_f32_32x32x16_bf16 v[2:17], v[110:113], v[78:81], v[2:17]
	v_mfma_f32_32x32x16_bf16 v[18:33], v[122:125], v[74:77], v[18:33]
	s_waitcnt lgkmcnt(2)
	v_mfma_f32_32x32x16_bf16 v[2:17], v[106:109], v[74:77], v[2:17]
	v_mfma_f32_32x32x16_bf16 v[18:33], v[118:121], v[70:73], v[18:33]
	s_waitcnt lgkmcnt(1)
	v_mfma_f32_32x32x16_bf16 v[2:17], v[102:105], v[70:73], v[2:17]
	v_mfma_f32_32x32x16_bf16 v[18:33], v[114:117], v[66:69], v[18:33]
	s_waitcnt lgkmcnt(0)
	v_mfma_f32_32x32x16_bf16 v[2:17], v[98:101], v[66:69], v[2:17]
	ds_read_b128 v[94:97], v134 offset:54400
	ds_read_b128 v[90:93], v134 offset:54432
	ds_read_b128 v[86:89], v134 offset:54464
	ds_read_b128 v[82:85], v134 offset:54496
	ds_read_b128 v[78:81], v134 offset:63104
	ds_read_b128 v[74:77], v134 offset:63136
	ds_read_b128 v[70:73], v134 offset:63168
	ds_read_b128 v[66:69], v134 offset:63200
	v_max3_f32 v98, v50, v34, v51
	v_max_f32_e32 v99, v49, v49
	v_max3_f32 v98, v98, v35, v52
	v_max3_f32 v98, v98, v36, v53
	v_max3_f32 v98, v98, v37, v54
	v_max3_f32 v98, v98, v38, v55
	v_max3_f32 v98, v98, v39, v56
	v_max3_f32 v98, v98, v40, v57
	v_max3_f32 v98, v98, v41, v58
	v_max3_f32 v98, v98, v42, v59
	v_max3_f32 v98, v98, v43, v60
	v_max3_f32 v98, v98, v44, v61
	v_max3_f32 v98, v98, v45, v62
	v_max3_f32 v98, v98, v46, v63
	v_max3_f32 v98, v98, v47, v64
	v_max3_f32 v98, v98, v48, v65
	s_nop 0
	v_max_f32_e32 v98, v98, v98
	v_max_f32_e32 v98, v98, v99
	v_mov_b32_e32 v99, v98
	v_nop
	v_nop
	v_permlane32_swap_b32 v99, v98
	s_nop 0
	v_max3_f32 v99, v247, v99, v98
	v_sub_f32_e32 v98, v247, v99
	v_exp_f32_e32 v98, v98
	s_nop 0
	v_cmp_neq_f32_e32 vcc, 1.0, v98
	s_cbranch_vccz .LBB0_122
	v_pk_mul_f32 v[32:33], v[32:33], v[98:99] op_sel_hi:[1,0]
	v_pk_mul_f32 v[30:31], v[30:31], v[98:99] op_sel_hi:[1,0]
	v_pk_mul_f32 v[28:29], v[28:29], v[98:99] op_sel_hi:[1,0]
	v_pk_mul_f32 v[26:27], v[26:27], v[98:99] op_sel_hi:[1,0]
	v_pk_mul_f32 v[24:25], v[24:25], v[98:99] op_sel_hi:[1,0]
	v_pk_mul_f32 v[22:23], v[22:23], v[98:99] op_sel_hi:[1,0]
	v_pk_mul_f32 v[20:21], v[20:21], v[98:99] op_sel_hi:[1,0]
	v_pk_mul_f32 v[18:19], v[18:19], v[98:99] op_sel_hi:[1,0]
	v_pk_mul_f32 v[16:17], v[16:17], v[98:99] op_sel_hi:[1,0]
	v_pk_mul_f32 v[14:15], v[14:15], v[98:99] op_sel_hi:[1,0]
	v_pk_mul_f32 v[12:13], v[12:13], v[98:99] op_sel_hi:[1,0]
	v_pk_mul_f32 v[10:11], v[10:11], v[98:99] op_sel_hi:[1,0]
	v_pk_mul_f32 v[8:9], v[8:9], v[98:99] op_sel_hi:[1,0]
	v_pk_mul_f32 v[6:7], v[6:7], v[98:99] op_sel_hi:[1,0]
	v_pk_mul_f32 v[4:5], v[4:5], v[98:99] op_sel_hi:[1,0]
	v_pk_mul_f32 v[2:3], v[2:3], v[98:99] op_sel_hi:[1,0]
	s_branch .LBB0_122

.LBB0_141:
	s_and_b32 s38, s37, 1
	s_mul_i32 s39, s38, 0x4800
	v_add_u32_e32 v0, s39, v203
	ds_read_b128 v[2:5], v0
	ds_read_b128 v[6:9], v0 offset:32
	ds_read_b128 v[10:13], v0 offset:4608
	ds_read_b128 v[80:83], v0 offset:4640
	ds_read_b128 v[84:87], v0 offset:64
	ds_read_b128 v[88:91], v0 offset:96
	ds_read_b128 v[92:95], v0 offset:4672
	ds_read_b128 v[96:99], v0 offset:4704
	s_waitcnt lgkmcnt(7)
	v_mfma_f32_32x32x16_bf16 v[128:143], v[2:5], v[144:147], 0
	s_waitcnt lgkmcnt(5)
	v_mfma_f32_32x32x16_bf16 v[112:127], v[10:13], v[144:147], 0
	v_mfma_f32_32x32x16_bf16 v[128:143], v[6:9], v[168:171], v[128:143]
	s_waitcnt lgkmcnt(4)
	v_mfma_f32_32x32x16_bf16 v[112:127], v[80:83], v[168:171], v[112:127]
	s_waitcnt lgkmcnt(3)
	v_mfma_f32_32x32x16_bf16 v[128:143], v[84:87], v[148:151], v[128:143]
	s_waitcnt lgkmcnt(1)
	v_mfma_f32_32x32x16_bf16 v[112:127], v[92:95], v[148:151], v[112:127]
	v_mfma_f32_32x32x16_bf16 v[128:143], v[88:91], v[172:175], v[128:143]
	s_waitcnt lgkmcnt(0)
	v_mfma_f32_32x32x16_bf16 v[112:127], v[96:99], v[172:175], v[112:127]
	ds_read_b128 v[2:5], v0 offset:9216
	ds_read_b128 v[6:9], v0 offset:9248
	ds_read_b128 v[10:13], v0 offset:13824
	ds_read_b128 v[184:187], v0 offset:13856
	ds_read_b128 v[198:201], v0 offset:9280
	ds_read_b128 v[208:211], v0 offset:9312
	ds_read_b128 v[212:215], v0 offset:13888
	ds_read_b128 v[220:223], v0 offset:13920
	s_waitcnt lgkmcnt(7)
	v_mfma_f32_32x32x16_bf16 v[96:111], v[2:5], v[144:147], 0
	s_waitcnt lgkmcnt(5)
	v_mfma_f32_32x32x16_bf16 v[80:95], v[10:13], v[144:147], 0
	v_mfma_f32_32x32x16_bf16 v[96:111], v[6:9], v[168:171], v[96:111]
	s_waitcnt lgkmcnt(4)
	v_mfma_f32_32x32x16_bf16 v[80:95], v[184:187], v[168:171], v[80:95]
	s_waitcnt lgkmcnt(3)
	v_mfma_f32_32x32x16_bf16 v[96:111], v[198:201], v[148:151], v[96:111]
	s_waitcnt lgkmcnt(1)
	v_mfma_f32_32x32x16_bf16 v[80:95], v[212:215], v[148:151], v[80:95]
	v_mfma_f32_32x32x16_bf16 v[96:111], v[208:211], v[172:175], v[96:111]
	s_waitcnt lgkmcnt(0)
	v_mfma_f32_32x32x16_bf16 v[80:95], v[220:223], v[172:175], v[80:95]
	s_mul_i32 s39, s38, 0x8800
	v_add_u32_e32 v15, s39, v204
	ds_read_b128 v[184:187], v15 offset:36864
	ds_read_b128 v[10:13], v15 offset:36896
	ds_read_b128 v[2:5], v15 offset:36928
	ds_read_b128 v[6:9], v15 offset:36960
	v_max3_f32 v0, v128, v112, v129
	v_max_f32_e32 v14, v127, v127
	v_max3_f32 v0, v0, v113, v130
	v_max3_f32 v0, v0, v114, v131
	v_max3_f32 v0, v0, v115, v132
	v_max3_f32 v0, v0, v116, v133
	v_max3_f32 v0, v0, v117, v134
	v_max3_f32 v0, v0, v118, v135
	v_max3_f32 v0, v0, v119, v136
	v_max3_f32 v0, v0, v120, v137
	v_max3_f32 v0, v0, v121, v138
	v_max3_f32 v0, v0, v122, v139
	v_max3_f32 v0, v0, v123, v140
	v_max3_f32 v0, v0, v124, v141
	v_max3_f32 v0, v0, v125, v142
	v_max3_f32 v0, v0, v126, v143
	s_nop 0
	v_max_f32_e32 v0, v0, v0
	v_max_f32_e32 v0, v0, v14
	v_mov_b32_e32 v14, v0
	v_nop
	v_nop
	v_permlane32_swap_b32 v14, v0
	s_nop 0
	v_max3_f32 v14, v206, v14, v0
	v_sub_f32_e32 v0, v206, v14
	v_exp_f32_e32 v0, v0
	s_nop 0
	v_cmp_neq_f32_e32 vcc, 1.0, v0
	s_cbranch_vccz .LBB0_143
	v_pk_mul_f32 v[78:79], v[78:79], v[0:1] op_sel_hi:[1,0]
	v_pk_mul_f32 v[76:77], v[76:77], v[0:1] op_sel_hi:[1,0]
	v_pk_mul_f32 v[74:75], v[74:75], v[0:1] op_sel_hi:[1,0]
	v_pk_mul_f32 v[72:73], v[72:73], v[0:1] op_sel_hi:[1,0]
	v_pk_mul_f32 v[70:71], v[70:71], v[0:1] op_sel_hi:[1,0]
	v_pk_mul_f32 v[68:69], v[68:69], v[0:1] op_sel_hi:[1,0]
	v_pk_mul_f32 v[66:67], v[66:67], v[0:1] op_sel_hi:[1,0]
	v_pk_mul_f32 v[64:65], v[64:65], v[0:1] op_sel_hi:[1,0]
	v_pk_mul_f32 v[62:63], v[62:63], v[0:1] op_sel_hi:[1,0]
	v_pk_mul_f32 v[60:61], v[60:61], v[0:1] op_sel_hi:[1,0]
	v_pk_mul_f32 v[58:59], v[58:59], v[0:1] op_sel_hi:[1,0]
	v_pk_mul_f32 v[56:57], v[56:57], v[0:1] op_sel_hi:[1,0]
	v_pk_mul_f32 v[54:55], v[54:55], v[0:1] op_sel_hi:[1,0]
	v_pk_mul_f32 v[52:53], v[52:53], v[0:1] op_sel_hi:[1,0]
	v_pk_mul_f32 v[50:51], v[50:51], v[0:1] op_sel_hi:[1,0]
	v_pk_mul_f32 v[48:49], v[48:49], v[0:1] op_sel_hi:[1,0]
	v_pk_mul_f32 v[46:47], v[46:47], v[0:1] op_sel_hi:[1,0]
	v_pk_mul_f32 v[44:45], v[44:45], v[0:1] op_sel_hi:[1,0]
	v_pk_mul_f32 v[42:43], v[42:43], v[0:1] op_sel_hi:[1,0]
	v_pk_mul_f32 v[40:41], v[40:41], v[0:1] op_sel_hi:[1,0]
	v_pk_mul_f32 v[38:39], v[38:39], v[0:1] op_sel_hi:[1,0]
	v_pk_mul_f32 v[36:37], v[36:37], v[0:1] op_sel_hi:[1,0]
	v_pk_mul_f32 v[34:35], v[34:35], v[0:1] op_sel_hi:[1,0]
	v_pk_mul_f32 v[32:33], v[32:33], v[0:1] op_sel_hi:[1,0]
	v_pk_mul_f32 v[30:31], v[30:31], v[0:1] op_sel_hi:[1,0]
	v_pk_mul_f32 v[28:29], v[28:29], v[0:1] op_sel_hi:[1,0]
	v_pk_mul_f32 v[26:27], v[26:27], v[0:1] op_sel_hi:[1,0]
	v_pk_mul_f32 v[24:25], v[24:25], v[0:1] op_sel_hi:[1,0]
	v_pk_mul_f32 v[22:23], v[22:23], v[0:1] op_sel_hi:[1,0]
	v_pk_mul_f32 v[20:21], v[20:21], v[0:1] op_sel_hi:[1,0]
	v_pk_mul_f32 v[18:19], v[18:19], v[0:1] op_sel_hi:[1,0]
	v_pk_mul_f32 v[16:17], v[16:17], v[0:1] op_sel_hi:[1,0]
.LBB0_143:
	v_sub_f32_e32 v112, v112, v14
	v_exp_f32_e32 v207, v112
	v_sub_f32_e32 v112, v129, v14
	v_exp_f32_e32 v129, v112
	v_sub_f32_e32 v112, v113, v14
	v_exp_f32_e32 v208, v112
	v_sub_f32_e32 v112, v130, v14
	v_exp_f32_e32 v130, v112
	v_sub_f32_e32 v112, v114, v14
	v_exp_f32_e32 v209, v112
	v_sub_f32_e32 v112, v131, v14
	v_exp_f32_e32 v131, v112
	v_sub_f32_e32 v112, v115, v14
	v_exp_f32_e32 v220, v112
	v_sub_f32_e32 v112, v132, v14
	v_exp_f32_e32 v132, v112
	v_sub_f32_e32 v112, v116, v14
	v_exp_f32_e32 v116, v112
	v_sub_f32_e32 v112, v133, v14
	v_exp_f32_e32 v133, v112
	v_sub_f32_e32 v112, v117, v14
	v_exp_f32_e32 v117, v112
	v_sub_f32_e32 v112, v134, v14
	v_exp_f32_e32 v134, v112
	v_sub_f32_e32 v112, v118, v14
	v_exp_f32_e32 v118, v112
	v_sub_f32_e32 v112, v135, v14
	v_exp_f32_e32 v135, v112
	v_sub_f32_e32 v112, v119, v14
	v_exp_f32_e32 v119, v112
	v_sub_f32_e32 v112, v136, v14
	v_exp_f32_e32 v136, v112
	v_sub_f32_e32 v112, v120, v14
	v_exp_f32_e32 v120, v112
	v_sub_f32_e32 v112, v137, v14
	v_exp_f32_e32 v137, v112
	v_sub_f32_e32 v112, v121, v14
	v_exp_f32_e32 v121, v112
	v_sub_f32_e32 v112, v138, v14
	v_exp_f32_e32 v138, v112
	v_sub_f32_e32 v112, v122, v14
	v_exp_f32_e32 v122, v112
	v_sub_f32_e32 v112, v139, v14
	v_exp_f32_e32 v139, v112
	v_sub_f32_e32 v112, v123, v14
	v_exp_f32_e32 v123, v112
	v_sub_f32_e32 v112, v140, v14
	v_exp_f32_e32 v140, v112
	v_sub_f32_e32 v112, v124, v14
	v_exp_f32_e32 v124, v112
	v_sub_f32_e32 v112, v141, v14
	v_exp_f32_e32 v141, v112
	v_sub_f32_e32 v112, v125, v14
	v_exp_f32_e32 v125, v112
	v_sub_f32_e32 v112, v142, v14
	v_exp_f32_e32 v142, v112
	v_sub_f32_e32 v112, v126, v14
	v_exp_f32_e32 v126, v112
	v_sub_f32_e32 v112, v143, v14
	v_exp_f32_e32 v143, v112
	v_sub_f32_e32 v112, v127, v14
	v_sub_f32_e32 v128, v128, v14
	v_exp_f32_e32 v127, v112
	v_exp_f32_e32 v128, v128
	v_cvt_pk_bf16_f32 v112, v120, v121
	v_cvt_pk_bf16_f32 v113, v122, v123
	v_cvt_pk_bf16_f32 v114, v124, v125
	v_cvt_pk_bf16_f32 v115, v126, v127
	v_cvt_pk_bf16_f32 v198, v207, v208
	v_cvt_pk_bf16_f32 v199, v209, v220
	v_cvt_pk_bf16_f32 v200, v116, v117
	v_cvt_pk_bf16_f32 v201, v118, v119
	v_cvt_pk_bf16_f32 v210, v136, v137
	v_cvt_pk_bf16_f32 v211, v138, v139
	v_cvt_pk_bf16_f32 v212, v140, v141
	v_cvt_pk_bf16_f32 v213, v142, v143
	v_cvt_pk_bf16_f32 v214, v128, v129
	v_cvt_pk_bf16_f32 v215, v130, v131
	v_cvt_pk_bf16_f32 v216, v132, v133
	v_cvt_pk_bf16_f32 v217, v134, v135
	s_waitcnt lgkmcnt(3)
	s_nop 0
	v_mfma_f32_32x32x16_bf16 v[64:79], v[184:187], v[214:217], v[64:79]
	s_waitcnt lgkmcnt(2)
	v_mfma_f32_32x32x16_bf16 v[64:79], v[10:13], v[210:213], v[64:79]
	s_waitcnt lgkmcnt(1)
	v_mfma_f32_32x32x16_bf16 v[64:79], v[2:5], v[198:201], v[64:79]
	s_waitcnt lgkmcnt(0)
	v_mfma_f32_32x32x16_bf16 v[64:79], v[6:9], v[112:115], v[64:79]
	ds_read_b128 v[2:5], v15 offset:45664
	ds_read_b128 v[6:9], v15 offset:45632
	ds_read_b128 v[10:13], v15 offset:45568
	ds_read_b128 v[184:187], v15 offset:45600
	s_waitcnt lgkmcnt(1)
	v_mfma_f32_32x32x16_bf16 v[48:63], v[10:13], v[214:217], v[48:63]
	s_waitcnt lgkmcnt(0)
	v_mfma_f32_32x32x16_bf16 v[48:63], v[184:187], v[210:213], v[48:63]
	v_mfma_f32_32x32x16_bf16 v[48:63], v[6:9], v[198:201], v[48:63]
	v_mfma_f32_32x32x16_bf16 v[48:63], v[2:5], v[112:115], v[48:63]
	ds_read_b128 v[2:5], v15 offset:54368
	ds_read_b128 v[6:9], v15 offset:54336
	ds_read_b128 v[10:13], v15 offset:54272
	ds_read_b128 v[184:187], v15 offset:54304
	s_waitcnt lgkmcnt(1)
	v_mfma_f32_32x32x16_bf16 v[32:47], v[10:13], v[214:217], v[32:47]
	s_waitcnt lgkmcnt(0)
	v_mfma_f32_32x32x16_bf16 v[32:47], v[184:187], v[210:213], v[32:47]
	v_mfma_f32_32x32x16_bf16 v[32:47], v[6:9], v[198:201], v[32:47]
	v_mfma_f32_32x32x16_bf16 v[32:47], v[2:5], v[112:115], v[32:47]
	ds_read_b128 v[2:5], v15 offset:63072
	ds_read_b128 v[6:9], v15 offset:63040
	ds_read_b128 v[10:13], v15 offset:62976
	ds_read_b128 v[184:187], v15 offset:63008
	s_waitcnt lgkmcnt(1)
	v_mfma_f32_32x32x16_bf16 v[16:31], v[10:13], v[214:217], v[16:31]
	s_waitcnt lgkmcnt(0)
	v_mfma_f32_32x32x16_bf16 v[16:31], v[184:187], v[210:213], v[16:31]
	v_mfma_f32_32x32x16_bf16 v[16:31], v[6:9], v[198:201], v[16:31]
	v_mfma_f32_32x32x16_bf16 v[16:31], v[2:5], v[112:115], v[16:31]
	ds_read_b128 v[112:115], v15 offset:36992
	ds_read_b128 v[10:13], v15 offset:37024
	ds_read_b128 v[2:5], v15 offset:37056
	ds_read_b128 v[6:9], v15 offset:37088
	v_max3_f32 v184, v96, v80, v97
	v_max_f32_e32 v185, v95, v95
	v_max3_f32 v184, v184, v81, v98
	v_max3_f32 v184, v184, v82, v99
	v_max3_f32 v184, v184, v83, v100
	v_max3_f32 v184, v184, v84, v101
	v_max3_f32 v184, v184, v85, v102
	v_max3_f32 v184, v184, v86, v103
	v_max3_f32 v184, v184, v87, v104
	v_max3_f32 v184, v184, v88, v105
	v_max3_f32 v184, v184, v89, v106
	v_max3_f32 v184, v184, v90, v107
	v_max3_f32 v184, v184, v91, v108
	v_max3_f32 v184, v184, v92, v109
	v_max3_f32 v184, v184, v93, v110
	v_max3_f32 v184, v184, v94, v111
	s_nop 0
	v_max_f32_e32 v184, v184, v184
	v_max_f32_e32 v184, v184, v185
	v_mov_b32_e32 v185, v184
	v_nop
	v_nop
	v_permlane32_swap_b32 v184, v185
	s_nop 0
	v_max3_f32 v206, v14, v184, v185
	v_sub_f32_e32 v14, v14, v206
	v_exp_f32_e32 v14, v14
	s_nop 0
	v_cmp_neq_f32_e32 vcc, 1.0, v14
	s_cbranch_vccz .LBB0_145
	v_pk_mul_f32 v[78:79], v[78:79], v[14:15] op_sel_hi:[1,0]
	v_pk_mul_f32 v[76:77], v[76:77], v[14:15] op_sel_hi:[1,0]
	v_pk_mul_f32 v[74:75], v[74:75], v[14:15] op_sel_hi:[1,0]
	v_pk_mul_f32 v[72:73], v[72:73], v[14:15] op_sel_hi:[1,0]
	v_pk_mul_f32 v[70:71], v[70:71], v[14:15] op_sel_hi:[1,0]
	v_pk_mul_f32 v[68:69], v[68:69], v[14:15] op_sel_hi:[1,0]
	v_pk_mul_f32 v[66:67], v[66:67], v[14:15] op_sel_hi:[1,0]
	v_pk_mul_f32 v[64:65], v[64:65], v[14:15] op_sel_hi:[1,0]
	v_pk_mul_f32 v[62:63], v[62:63], v[14:15] op_sel_hi:[1,0]
	v_pk_mul_f32 v[60:61], v[60:61], v[14:15] op_sel_hi:[1,0]
	v_pk_mul_f32 v[58:59], v[58:59], v[14:15] op_sel_hi:[1,0]
	v_pk_mul_f32 v[56:57], v[56:57], v[14:15] op_sel_hi:[1,0]
	v_pk_mul_f32 v[54:55], v[54:55], v[14:15] op_sel_hi:[1,0]
	v_pk_mul_f32 v[52:53], v[52:53], v[14:15] op_sel_hi:[1,0]
	v_pk_mul_f32 v[50:51], v[50:51], v[14:15] op_sel_hi:[1,0]
	v_pk_mul_f32 v[48:49], v[48:49], v[14:15] op_sel_hi:[1,0]
	v_pk_mul_f32 v[46:47], v[46:47], v[14:15] op_sel_hi:[1,0]
	v_pk_mul_f32 v[44:45], v[44:45], v[14:15] op_sel_hi:[1,0]
	v_pk_mul_f32 v[42:43], v[42:43], v[14:15] op_sel_hi:[1,0]
	v_pk_mul_f32 v[40:41], v[40:41], v[14:15] op_sel_hi:[1,0]
	v_pk_mul_f32 v[38:39], v[38:39], v[14:15] op_sel_hi:[1,0]
	v_pk_mul_f32 v[36:37], v[36:37], v[14:15] op_sel_hi:[1,0]
	v_pk_mul_f32 v[34:35], v[34:35], v[14:15] op_sel_hi:[1,0]
	v_pk_mul_f32 v[32:33], v[32:33], v[14:15] op_sel_hi:[1,0]
	v_pk_mul_f32 v[30:31], v[30:31], v[14:15] op_sel_hi:[1,0]
	v_pk_mul_f32 v[28:29], v[28:29], v[14:15] op_sel_hi:[1,0]
	v_pk_mul_f32 v[26:27], v[26:27], v[14:15] op_sel_hi:[1,0]
	v_pk_mul_f32 v[24:25], v[24:25], v[14:15] op_sel_hi:[1,0]
	v_pk_mul_f32 v[22:23], v[22:23], v[14:15] op_sel_hi:[1,0]
	v_pk_mul_f32 v[20:21], v[20:21], v[14:15] op_sel_hi:[1,0]
	v_pk_mul_f32 v[18:19], v[18:19], v[14:15] op_sel_hi:[1,0]
	v_pk_mul_f32 v[16:17], v[16:17], v[14:15] op_sel_hi:[1,0]

.LBB0_151:
	s_and_b32 s4, s3, 1
	s_mul_i32 s5, s4, 0x4800
	v_add_u32_e32 v192, s5, v202
	ds_read_b128 v[66:69], v192
	ds_read_b128 v[70:73], v192 offset:32
	ds_read_b128 v[74:77], v192 offset:4608
	ds_read_b128 v[78:81], v192 offset:4640
	ds_read_b128 v[82:85], v192 offset:64
	ds_read_b128 v[86:89], v192 offset:96
	ds_read_b128 v[90:93], v192 offset:4672
	ds_read_b128 v[94:97], v192 offset:4704
	s_waitcnt lgkmcnt(7)
	v_mfma_f32_32x32x16_bf16 v[114:129], v[66:69], v[130:133], 0
	s_waitcnt lgkmcnt(5)
	v_mfma_f32_32x32x16_bf16 v[98:113], v[74:77], v[130:133], 0
	v_mfma_f32_32x32x16_bf16 v[114:129], v[70:73], v[154:157], v[114:129]
	s_waitcnt lgkmcnt(4)
	v_mfma_f32_32x32x16_bf16 v[98:113], v[78:81], v[154:157], v[98:113]
	s_waitcnt lgkmcnt(3)
	v_mfma_f32_32x32x16_bf16 v[114:129], v[82:85], v[134:137], v[114:129]
	s_waitcnt lgkmcnt(1)
	v_mfma_f32_32x32x16_bf16 v[98:113], v[90:93], v[134:137], v[98:113]
	v_mfma_f32_32x32x16_bf16 v[114:129], v[86:89], v[158:161], v[114:129]
	s_waitcnt lgkmcnt(0)
	v_mfma_f32_32x32x16_bf16 v[98:113], v[94:97], v[158:161], v[98:113]
	ds_read_b128 v[66:69], v192 offset:9216
	ds_read_b128 v[170:173], v192 offset:9248
	ds_read_b128 v[70:73], v192 offset:13824
	ds_read_b128 v[174:177], v192 offset:13856
	ds_read_b128 v[178:181], v192 offset:9280
	ds_read_b128 v[182:185], v192 offset:9312
	ds_read_b128 v[198:201], v192 offset:13888
	ds_read_b128 v[208:211], v192 offset:13920
	s_waitcnt lgkmcnt(7)
	v_mfma_f32_32x32x16_bf16 v[82:97], v[66:69], v[130:133], 0
	s_waitcnt lgkmcnt(5)
	v_mfma_f32_32x32x16_bf16 v[66:81], v[70:73], v[130:133], 0
	v_mfma_f32_32x32x16_bf16 v[82:97], v[170:173], v[154:157], v[82:97]
	s_waitcnt lgkmcnt(4)
	v_mfma_f32_32x32x16_bf16 v[66:81], v[174:177], v[154:157], v[66:81]
	s_waitcnt lgkmcnt(3)
	v_mfma_f32_32x32x16_bf16 v[82:97], v[178:181], v[134:137], v[82:97]
	s_waitcnt lgkmcnt(1)
	v_mfma_f32_32x32x16_bf16 v[66:81], v[198:201], v[134:137], v[66:81]
	v_mfma_f32_32x32x16_bf16 v[82:97], v[182:185], v[158:161], v[82:97]
	s_waitcnt lgkmcnt(0)
	v_mfma_f32_32x32x16_bf16 v[66:81], v[208:211], v[158:161], v[66:81]
	s_mul_i32 s5, s4, 0x8800
	v_add_u32_e32 v205, s5, v203
	ds_read_b128 v[182:185], v205 offset:36864
	ds_read_b128 v[178:181], v205 offset:36896
	ds_read_b128 v[170:173], v205 offset:36928
	ds_read_b128 v[174:177], v205 offset:36960
	v_max3_f32 v192, v114, v98, v115
	v_max_f32_e32 v198, v113, v113
	v_max3_f32 v192, v192, v99, v116
	v_max3_f32 v192, v192, v100, v117
	v_max3_f32 v192, v192, v101, v118
	v_max3_f32 v192, v192, v102, v119
	v_max3_f32 v192, v192, v103, v120
	v_max3_f32 v192, v192, v104, v121
	v_max3_f32 v192, v192, v105, v122
	v_max3_f32 v192, v192, v106, v123
	v_max3_f32 v192, v192, v107, v124
	v_max3_f32 v192, v192, v108, v125
	v_max3_f32 v192, v192, v109, v126
	v_max3_f32 v192, v192, v110, v127
	v_max3_f32 v192, v192, v111, v128
	v_max3_f32 v192, v192, v112, v129
	s_nop 0
	v_max_f32_e32 v192, v192, v192
	v_max_f32_e32 v192, v192, v198
	v_mov_b32_e32 v198, v192
	v_nop
	v_nop
	v_permlane32_swap_b32 v192, v198
	s_nop 0
	v_max3_f32 v234, v206, v192, v198
	v_sub_f32_e32 v192, v206, v234
	v_exp_f32_e32 v192, v192
	s_nop 0
	v_cmp_neq_f32_e32 vcc, 1.0, v192
	s_cbranch_vccz .LBB0_153
	v_pk_mul_f32 v[16:17], v[16:17], v[192:193] op_sel_hi:[1,0]
	v_pk_mul_f32 v[14:15], v[14:15], v[192:193] op_sel_hi:[1,0]
	v_pk_mul_f32 v[12:13], v[12:13], v[192:193] op_sel_hi:[1,0]
	v_pk_mul_f32 v[10:11], v[10:11], v[192:193] op_sel_hi:[1,0]
	v_pk_mul_f32 v[8:9], v[8:9], v[192:193] op_sel_hi:[1,0]
	v_pk_mul_f32 v[6:7], v[6:7], v[192:193] op_sel_hi:[1,0]
	v_pk_mul_f32 v[4:5], v[4:5], v[192:193] op_sel_hi:[1,0]
	v_pk_mul_f32 v[2:3], v[2:3], v[192:193] op_sel_hi:[1,0]
	v_pk_mul_f32 v[64:65], v[64:65], v[192:193] op_sel_hi:[1,0]
	v_pk_mul_f32 v[62:63], v[62:63], v[192:193] op_sel_hi:[1,0]
	v_pk_mul_f32 v[60:61], v[60:61], v[192:193] op_sel_hi:[1,0]
	v_pk_mul_f32 v[58:59], v[58:59], v[192:193] op_sel_hi:[1,0]
	v_pk_mul_f32 v[56:57], v[56:57], v[192:193] op_sel_hi:[1,0]
	v_pk_mul_f32 v[54:55], v[54:55], v[192:193] op_sel_hi:[1,0]
	v_pk_mul_f32 v[52:53], v[52:53], v[192:193] op_sel_hi:[1,0]
	v_pk_mul_f32 v[50:51], v[50:51], v[192:193] op_sel_hi:[1,0]
	v_pk_mul_f32 v[48:49], v[48:49], v[192:193] op_sel_hi:[1,0]
	v_pk_mul_f32 v[46:47], v[46:47], v[192:193] op_sel_hi:[1,0]
	v_pk_mul_f32 v[44:45], v[44:45], v[192:193] op_sel_hi:[1,0]
	v_pk_mul_f32 v[42:43], v[42:43], v[192:193] op_sel_hi:[1,0]
	v_pk_mul_f32 v[40:41], v[40:41], v[192:193] op_sel_hi:[1,0]
	v_pk_mul_f32 v[38:39], v[38:39], v[192:193] op_sel_hi:[1,0]
	v_pk_mul_f32 v[36:37], v[36:37], v[192:193] op_sel_hi:[1,0]
	v_pk_mul_f32 v[34:35], v[34:35], v[192:193] op_sel_hi:[1,0]
	v_pk_mul_f32 v[32:33], v[32:33], v[192:193] op_sel_hi:[1,0]
	v_pk_mul_f32 v[30:31], v[30:31], v[192:193] op_sel_hi:[1,0]
	v_pk_mul_f32 v[28:29], v[28:29], v[192:193] op_sel_hi:[1,0]
	v_pk_mul_f32 v[26:27], v[26:27], v[192:193] op_sel_hi:[1,0]
	v_pk_mul_f32 v[24:25], v[24:25], v[192:193] op_sel_hi:[1,0]
	v_pk_mul_f32 v[22:23], v[22:23], v[192:193] op_sel_hi:[1,0]
	v_pk_mul_f32 v[20:21], v[20:21], v[192:193] op_sel_hi:[1,0]
	v_pk_mul_f32 v[18:19], v[18:19], v[192:193] op_sel_hi:[1,0]
.LBB0_153:
	v_sub_f32_e32 v98, v98, v234
	v_exp_f32_e32 v208, v98
	v_sub_f32_e32 v98, v115, v234
	v_exp_f32_e32 v115, v98
	v_sub_f32_e32 v98, v99, v234
	v_exp_f32_e32 v209, v98
	v_sub_f32_e32 v98, v116, v234
	v_exp_f32_e32 v116, v98
	v_sub_f32_e32 v98, v100, v234
	v_exp_f32_e32 v220, v98
	v_sub_f32_e32 v98, v117, v234
	v_exp_f32_e32 v117, v98
	v_sub_f32_e32 v98, v101, v234
	v_exp_f32_e32 v221, v98
	v_sub_f32_e32 v98, v118, v234
	v_exp_f32_e32 v118, v98
	v_sub_f32_e32 v98, v102, v234
	v_exp_f32_e32 v222, v98
	v_sub_f32_e32 v98, v119, v234
	v_exp_f32_e32 v119, v98
	v_sub_f32_e32 v98, v103, v234
	v_exp_f32_e32 v223, v98
	v_sub_f32_e32 v98, v120, v234
	v_exp_f32_e32 v120, v98
	v_sub_f32_e32 v98, v104, v234
	v_exp_f32_e32 v224, v98
	v_sub_f32_e32 v98, v121, v234
	v_exp_f32_e32 v121, v98
	v_sub_f32_e32 v98, v105, v234
	v_exp_f32_e32 v225, v98
	v_sub_f32_e32 v98, v122, v234
	v_exp_f32_e32 v122, v98
	v_sub_f32_e32 v98, v106, v234
	v_exp_f32_e32 v226, v98
	v_sub_f32_e32 v98, v123, v234
	v_exp_f32_e32 v123, v98
	v_sub_f32_e32 v98, v107, v234
	v_exp_f32_e32 v227, v98
	v_sub_f32_e32 v98, v124, v234
	v_exp_f32_e32 v124, v98
	v_sub_f32_e32 v98, v108, v234
	v_exp_f32_e32 v228, v98
	v_sub_f32_e32 v98, v125, v234
	v_exp_f32_e32 v125, v98
	v_sub_f32_e32 v98, v109, v234
	v_exp_f32_e32 v229, v98
	v_sub_f32_e32 v98, v126, v234
	v_exp_f32_e32 v126, v98
	v_sub_f32_e32 v98, v110, v234
	v_exp_f32_e32 v230, v98
	v_sub_f32_e32 v98, v127, v234
	v_exp_f32_e32 v127, v98
	v_sub_f32_e32 v98, v111, v234
	v_exp_f32_e32 v231, v98
	v_sub_f32_e32 v98, v128, v234
	v_exp_f32_e32 v128, v98
	v_sub_f32_e32 v98, v112, v234
	v_exp_f32_e32 v232, v98
	v_sub_f32_e32 v98, v129, v234
	v_sub_f32_e32 v114, v114, v234
	v_exp_f32_e32 v129, v98
	v_sub_f32_e32 v98, v113, v234
	v_exp_f32_e32 v207, v114
	v_exp_f32_e32 v233, v98
	v_cvt_pk_bf16_f32 v98, v226, v227
	v_cvt_pk_bf16_f32 v99, v228, v229
	v_cvt_pk_bf16_f32 v100, v230, v231
	v_cvt_pk_bf16_f32 v101, v232, v233
	v_cvt_pk_bf16_f32 v102, v208, v209
	v_cvt_pk_bf16_f32 v103, v220, v221
	v_cvt_pk_bf16_f32 v104, v222, v223
	v_cvt_pk_bf16_f32 v105, v224, v225
	v_cvt_pk_bf16_f32 v106, v122, v123
	v_cvt_pk_bf16_f32 v107, v124, v125
	v_cvt_pk_bf16_f32 v108, v126, v127
	v_cvt_pk_bf16_f32 v109, v128, v129
	v_cvt_pk_bf16_f32 v110, v207, v115
	v_cvt_pk_bf16_f32 v111, v116, v117
	v_cvt_pk_bf16_f32 v112, v118, v119
	v_cvt_pk_bf16_f32 v113, v120, v121
	s_waitcnt lgkmcnt(3)
	s_nop 0
	v_mfma_f32_32x32x16_bf16 v[2:17], v[182:185], v[110:113], v[2:17]
	s_waitcnt lgkmcnt(2)
	v_mfma_f32_32x32x16_bf16 v[2:17], v[178:181], v[106:109], v[2:17]
	s_waitcnt lgkmcnt(1)
	v_mfma_f32_32x32x16_bf16 v[2:17], v[170:173], v[102:105], v[2:17]
	s_waitcnt lgkmcnt(0)
	v_mfma_f32_32x32x16_bf16 v[2:17], v[174:177], v[98:101], v[2:17]
	ds_read_b128 v[170:173], v205 offset:45664
	ds_read_b128 v[174:177], v205 offset:45632
	ds_read_b128 v[178:181], v205 offset:45568
	ds_read_b128 v[182:185], v205 offset:45600
	s_waitcnt lgkmcnt(1)
	v_mfma_f32_32x32x16_bf16 v[50:65], v[178:181], v[110:113], v[50:65]
	s_waitcnt lgkmcnt(0)
	v_mfma_f32_32x32x16_bf16 v[50:65], v[182:185], v[106:109], v[50:65]
	v_mfma_f32_32x32x16_bf16 v[50:65], v[174:177], v[102:105], v[50:65]
	v_mfma_f32_32x32x16_bf16 v[50:65], v[170:173], v[98:101], v[50:65]
	ds_read_b128 v[170:173], v205 offset:54368
	ds_read_b128 v[174:177], v205 offset:54336
	ds_read_b128 v[178:181], v205 offset:54272
	ds_read_b128 v[182:185], v205 offset:54304
	s_waitcnt lgkmcnt(1)
	v_mfma_f32_32x32x16_bf16 v[34:49], v[178:181], v[110:113], v[34:49]
	s_waitcnt lgkmcnt(0)
	v_mfma_f32_32x32x16_bf16 v[34:49], v[182:185], v[106:109], v[34:49]
	v_mfma_f32_32x32x16_bf16 v[34:49], v[174:177], v[102:105], v[34:49]
	v_mfma_f32_32x32x16_bf16 v[34:49], v[170:173], v[98:101], v[34:49]
	ds_read_b128 v[170:173], v205 offset:63072
	ds_read_b128 v[174:177], v205 offset:63040
	ds_read_b128 v[178:181], v205 offset:62976
	ds_read_b128 v[182:185], v205 offset:63008
	s_waitcnt lgkmcnt(1)
	v_mfma_f32_32x32x16_bf16 v[18:33], v[178:181], v[110:113], v[18:33]
	s_waitcnt lgkmcnt(0)
	v_mfma_f32_32x32x16_bf16 v[18:33], v[182:185], v[106:109], v[18:33]
	v_mfma_f32_32x32x16_bf16 v[18:33], v[174:177], v[102:105], v[18:33]
	v_mfma_f32_32x32x16_bf16 v[18:33], v[170:173], v[98:101], v[18:33]
	ds_read_b128 v[110:113], v205 offset:36992
	ds_read_b128 v[106:109], v205 offset:37024
	ds_read_b128 v[98:101], v205 offset:37056
	ds_read_b128 v[102:105], v205 offset:37088
	v_max3_f32 v114, v82, v66, v83
	v_max_f32_e32 v170, v81, v81
	v_max3_f32 v114, v114, v67, v84
	v_max3_f32 v114, v114, v68, v85
	v_max3_f32 v114, v114, v69, v86
	v_max3_f32 v114, v114, v70, v87
	v_max3_f32 v114, v114, v71, v88
	v_max3_f32 v114, v114, v72, v89
	v_max3_f32 v114, v114, v73, v90
	v_max3_f32 v114, v114, v74, v91
	v_max3_f32 v114, v114, v75, v92
	v_max3_f32 v114, v114, v76, v93
	v_max3_f32 v114, v114, v77, v94
	v_max3_f32 v114, v114, v78, v95
	v_max3_f32 v114, v114, v79, v96
	v_max3_f32 v114, v114, v80, v97
	s_nop 0
	v_max_f32_e32 v114, v114, v114
	v_max_f32_e32 v114, v114, v170
	v_mov_b32_e32 v170, v114
	v_nop
	v_nop
	v_permlane32_swap_b32 v114, v170
	s_nop 0
	v_max3_f32 v206, v234, v114, v170
	v_sub_f32_e32 v114, v234, v206
	v_exp_f32_e32 v114, v114
	s_nop 0
	v_cmp_neq_f32_e32 vcc, 1.0, v114
	s_cbranch_vccz .LBB0_155
	v_pk_mul_f32 v[16:17], v[16:17], v[114:115] op_sel_hi:[1,0]
	v_pk_mul_f32 v[14:15], v[14:15], v[114:115] op_sel_hi:[1,0]
	v_pk_mul_f32 v[12:13], v[12:13], v[114:115] op_sel_hi:[1,0]
	v_pk_mul_f32 v[10:11], v[10:11], v[114:115] op_sel_hi:[1,0]
	v_pk_mul_f32 v[8:9], v[8:9], v[114:115] op_sel_hi:[1,0]
	v_pk_mul_f32 v[6:7], v[6:7], v[114:115] op_sel_hi:[1,0]
	v_pk_mul_f32 v[4:5], v[4:5], v[114:115] op_sel_hi:[1,0]
	v_pk_mul_f32 v[2:3], v[2:3], v[114:115] op_sel_hi:[1,0]
	v_pk_mul_f32 v[64:65], v[64:65], v[114:115] op_sel_hi:[1,0]
	v_pk_mul_f32 v[62:63], v[62:63], v[114:115] op_sel_hi:[1,0]
	v_pk_mul_f32 v[60:61], v[60:61], v[114:115] op_sel_hi:[1,0]
	v_pk_mul_f32 v[58:59], v[58:59], v[114:115] op_sel_hi:[1,0]
	v_pk_mul_f32 v[56:57], v[56:57], v[114:115] op_sel_hi:[1,0]
	v_pk_mul_f32 v[54:55], v[54:55], v[114:115] op_sel_hi:[1,0]
	v_pk_mul_f32 v[52:53], v[52:53], v[114:115] op_sel_hi:[1,0]
	v_pk_mul_f32 v[50:51], v[50:51], v[114:115] op_sel_hi:[1,0]
	v_pk_mul_f32 v[48:49], v[48:49], v[114:115] op_sel_hi:[1,0]
	v_pk_mul_f32 v[46:47], v[46:47], v[114:115] op_sel_hi:[1,0]
	v_pk_mul_f32 v[44:45], v[44:45], v[114:115] op_sel_hi:[1,0]
	v_pk_mul_f32 v[42:43], v[42:43], v[114:115] op_sel_hi:[1,0]
	v_pk_mul_f32 v[40:41], v[40:41], v[114:115] op_sel_hi:[1,0]
	v_pk_mul_f32 v[38:39], v[38:39], v[114:115] op_sel_hi:[1,0]
	v_pk_mul_f32 v[36:37], v[36:37], v[114:115] op_sel_hi:[1,0]
	v_pk_mul_f32 v[34:35], v[34:35], v[114:115] op_sel_hi:[1,0]
	v_pk_mul_f32 v[32:33], v[32:33], v[114:115] op_sel_hi:[1,0]
	v_pk_mul_f32 v[30:31], v[30:31], v[114:115] op_sel_hi:[1,0]
	v_pk_mul_f32 v[28:29], v[28:29], v[114:115] op_sel_hi:[1,0]
	v_pk_mul_f32 v[26:27], v[26:27], v[114:115] op_sel_hi:[1,0]
	v_pk_mul_f32 v[24:25], v[24:25], v[114:115] op_sel_hi:[1,0]
	v_pk_mul_f32 v[22:23], v[22:23], v[114:115] op_sel_hi:[1,0]
	v_pk_mul_f32 v[20:21], v[20:21], v[114:115] op_sel_hi:[1,0]
	v_pk_mul_f32 v[18:19], v[18:19], v[114:115] op_sel_hi:[1,0]

.LBB0_159:
	v_mov_b32_e32 v7, v197
	s_and_b32 s2, s4, 0xffffff00
	s_and_b32 s21, s0, 0x380
	v_and_b32_e32 v6, 31, v7
	v_ashrrev_i32_e32 v0, 1, v7
	v_and_b32_e32 v0, 0xffffffe0, v0
	v_or_b32_e32 v2, s2, v6
	v_add_u32_e32 v154, v2, v0
	v_ashrrev_i32_e32 v155, 31, v154
	v_lshlrev_b64 v[2:3], 11, v[154:155]
	v_bfe_u32 v156, v7, 5, 1
	v_lshl_add_u64 v[2:3], s[48:49], 0, v[2:3]
	s_lshl_b32 s80, s21, 1
	v_lshl_add_u64 v[2:3], v[2:3], 0, s[80:81]
	v_lshlrev_b32_e32 v0, 4, v156
	v_lshl_add_u64 v[16:17], v[2:3], 0, v[0:1]
	global_load_dwordx4 v[2:5], v[16:17], off
	global_load_dwordx4 v[8:11], v[16:17], off offset:32
	global_load_dwordx4 v[12:15], v[16:17], off offset:64
	s_nop 0
	global_load_dwordx4 v[16:19], v[16:17], off offset:96
	s_mov_b32 s28, 0x3e38aa3b
	s_ashr_i32 s3, s2, 31
	s_waitcnt vmcnt(3)
	v_and_b32_e32 v21, 0xffff0000, v2
	v_lshlrev_b32_e32 v20, 16, v2
	v_pk_mul_f32 v[20:21], v[20:21], s[28:29] op_sel_hi:[1,0]
	s_nop 0
	v_cvt_pk_bf16_f32 v130, v20, v21
	v_and_b32_e32 v21, 0xffff0000, v3
	v_lshlrev_b32_e32 v20, 16, v3
	v_pk_mul_f32 v[2:3], v[20:21], s[28:29] op_sel_hi:[1,0]
	s_nop 0
	v_cvt_pk_bf16_f32 v131, v2, v3
	v_and_b32_e32 v3, 0xffff0000, v4
	v_lshlrev_b32_e32 v2, 16, v4
	v_pk_mul_f32 v[2:3], v[2:3], s[28:29] op_sel_hi:[1,0]
	s_nop 0
	v_cvt_pk_bf16_f32 v132, v2, v3
	v_and_b32_e32 v3, 0xffff0000, v5
	v_lshlrev_b32_e32 v2, 16, v5
	v_pk_mul_f32 v[2:3], v[2:3], s[28:29] op_sel_hi:[1,0]
	v_ashrrev_i32_e32 v5, 3, v7
	v_cvt_pk_bf16_f32 v133, v2, v3
	s_waitcnt vmcnt(2)
	v_and_b32_e32 v3, 0xffff0000, v8
	v_lshlrev_b32_e32 v2, 16, v8
	v_pk_mul_f32 v[2:3], v[2:3], s[28:29] op_sel_hi:[1,0]
	s_nop 0
	v_cvt_pk_bf16_f32 v134, v2, v3
	v_and_b32_e32 v3, 0xffff0000, v9
	v_lshlrev_b32_e32 v2, 16, v9
	v_pk_mul_f32 v[2:3], v[2:3], s[28:29] op_sel_hi:[1,0]
	v_and_b32_e32 v9, 15, v7
	v_cvt_pk_bf16_f32 v135, v2, v3
	v_and_b32_e32 v3, 0xffff0000, v10
	v_lshlrev_b32_e32 v2, 16, v10
	v_pk_mul_f32 v[2:3], v[2:3], s[28:29] op_sel_hi:[1,0]
	v_ashrrev_i32_e32 v10, 4, v7
	v_cvt_pk_bf16_f32 v136, v2, v3
	v_and_b32_e32 v3, 0xffff0000, v11
	v_lshlrev_b32_e32 v2, 16, v11
	v_pk_mul_f32 v[2:3], v[2:3], s[28:29] op_sel_hi:[1,0]
	v_lshlrev_b32_e32 v11, 4, v7
	v_cvt_pk_bf16_f32 v137, v2, v3
	s_waitcnt vmcnt(1)
	v_and_b32_e32 v3, 0xffff0000, v12
	v_lshlrev_b32_e32 v2, 16, v12
	v_pk_mul_f32 v[2:3], v[2:3], s[28:29] op_sel_hi:[1,0]
	v_and_b32_e32 v4, 0x70, v11
	v_cvt_pk_bf16_f32 v138, v2, v3
	v_and_b32_e32 v3, 0xffff0000, v13
	v_lshlrev_b32_e32 v2, 16, v13
	v_pk_mul_f32 v[2:3], v[2:3], s[28:29] op_sel_hi:[1,0]
	v_add_u32_e32 v8, s21, v10
	v_cvt_pk_bf16_f32 v139, v2, v3
	v_and_b32_e32 v3, 0xffff0000, v14
	v_lshlrev_b32_e32 v2, 16, v14
	v_pk_mul_f32 v[2:3], v[2:3], s[28:29] op_sel_hi:[1,0]
	v_mul_lo_u32 v40, v10, s43
	v_cvt_pk_bf16_f32 v140, v2, v3
	v_and_b32_e32 v3, 0xffff0000, v15
	v_lshlrev_b32_e32 v2, 16, v15
	v_pk_mul_f32 v[2:3], v[2:3], s[28:29] op_sel_hi:[1,0]
	s_nop 0
	v_cvt_pk_bf16_f32 v141, v2, v3
	s_waitcnt vmcnt(0)
	v_and_b32_e32 v3, 0xffff0000, v16
	v_lshlrev_b32_e32 v2, 16, v16
	v_pk_mul_f32 v[2:3], v[2:3], s[28:29] op_sel_hi:[1,0]
	s_nop 0
	v_cvt_pk_bf16_f32 v142, v2, v3
	v_and_b32_e32 v3, 0xffff0000, v17
	v_lshlrev_b32_e32 v2, 16, v17
	v_pk_mul_f32 v[2:3], v[2:3], s[28:29] op_sel_hi:[1,0]
	s_nop 0
	v_cvt_pk_bf16_f32 v143, v2, v3
	v_and_b32_e32 v3, 0xffff0000, v18
	v_lshlrev_b32_e32 v2, 16, v18
	v_pk_mul_f32 v[2:3], v[2:3], s[28:29] op_sel_hi:[1,0]
	s_nop 0
	v_cvt_pk_bf16_f32 v144, v2, v3
	v_and_b32_e32 v3, 0xffff0000, v19
	v_lshlrev_b32_e32 v2, 16, v19
	v_pk_mul_f32 v[2:3], v[2:3], s[28:29] op_sel_hi:[1,0]
	v_mad_u64_u32 v[32:33], s[28:29], v5, s42, v[4:5]
	v_cvt_pk_bf16_f32 v145, v2, v3
	v_add_u32_e32 v2, s2, v5
	v_ashrrev_i32_e32 v3, 31, v2
	v_lshlrev_b64 v[2:3], 11, v[2:3]
	v_lshl_add_u64 v[2:3], s[8:9], 0, v[2:3]
	v_lshlrev_b32_e32 v5, 3, v7
	v_and_b32_e32 v7, 8, v5
	v_lshl_add_u64 v[2:3], v[2:3], 0, s[80:81]
	v_mov_b32_e32 v5, v1
	v_lshl_add_u64 v[2:3], v[2:3], 0, v[4:5]
	v_mov_b64_e32 v[4:5], s[10:11]
	v_mad_i64_i32 v[4:5], s[28:29], v8, s68, v[4:5]
	s_mov_b32 s28, 0x20000
	v_lshl_add_u64 v[4:5], s[2:3], 1, v[4:5]
	v_lshlrev_b32_e32 v8, 4, v9
	v_mov_b32_e32 v9, v1
	v_add_co_u32_e32 v12, vcc, s28, v2
	v_lshl_add_u64 v[4:5], v[4:5], 0, v[8:9]
	s_nop 0
	v_addc_co_u32_e32 v13, vcc, 0, v3, vcc
	v_add_co_u32_e32 v34, vcc, s41, v4
	s_mov_b32 s28, 0x220000
	s_nop 0
	v_addc_co_u32_e32 v35, vcc, 0, v5, vcc
	v_and_b32_e32 v33, 0xe0, v11
	global_load_dwordx4 v[8:11], v[2:3], off
	v_add_co_u32_e32 v36, vcc, s28, v4
	global_load_dwordx4 v[12:15], v[12:13], off
	s_nop 0
	global_load_dwordx4 v[16:19], v[4:5], off
	v_addc_co_u32_e32 v37, vcc, 0, v5, vcc
	s_mov_b32 s28, 0x330000
	v_add_co_u32_e32 v38, vcc, s28, v4
	global_load_dwordx4 v[20:23], v[34:35], off
	global_load_dwordx4 v[24:27], v[36:37], off
	v_addc_co_u32_e32 v39, vcc, 0, v5, vcc
	global_load_dwordx4 v[28:31], v[38:39], off
	v_add_u32_e32 v190, 0, v32
	s_waitcnt vmcnt(5)
	ds_write_b128 v190, v[8:11]
	s_waitcnt vmcnt(4)
	ds_write_b128 v190, v[12:15] offset:9216
	v_add_u32_e32 v8, 0, v33
	v_add3_u32 v7, v8, v7, v40
	v_add_u32_e32 v8, 0xb000, v7
	v_add_u32_e32 v193, 0x9000, v7
	s_mov_b32 s28, 0x40000
	s_waitcnt vmcnt(3)
	ds_write2_b64 v193, v[16:17], v[18:19] offset1:2
	s_waitcnt vmcnt(2)
	ds_write2_b64 v8, v[20:21], v[22:23] offset0:64 offset1:66
	v_add_u32_e32 v8, 0xd000, v7
	v_add_u32_e32 v7, 0xf000, v7
	s_waitcnt vmcnt(1)
	ds_write2_b64 v8, v[24:25], v[26:27] offset0:128 offset1:130
	s_waitcnt vmcnt(0)
	ds_write2_b64 v7, v[28:29], v[30:31] offset0:192 offset1:194
	v_mad_u32_u24 v7, v6, s42, 0
	v_add_u32_e32 v192, v7, v0
	v_lshl_add_u32 v194, v6, 7, v192
	v_add_co_u32_e32 v6, vcc, s28, v2
	s_mov_b32 s28, 0x60000
	s_nop 0
	v_addc_co_u32_e32 v7, vcc, 0, v3, vcc
	v_add_co_u32_e32 v2, vcc, s28, v2
	s_waitcnt lgkmcnt(0)
	s_nop 0
	v_addc_co_u32_e32 v3, vcc, 0, v3, vcc
	s_barrier
	global_load_dwordx4 v[98:101], v[6:7], off
	global_load_dwordx4 v[118:121], v[2:3], off
	global_load_dwordx4 v[114:117], v[4:5], off offset:256
	global_load_dwordx4 v[110:113], v[34:35], off offset:256
	global_load_dwordx4 v[106:109], v[36:37], off offset:256
	global_load_dwordx4 v[102:105], v[38:39], off offset:256
	ds_read_b128 v[2:5], v192 offset:4608
	ds_read_b128 v[6:9], v192
	ds_read_b128 v[34:37], v192 offset:32
	ds_read_b128 v[38:41], v192 offset:4640
	ds_read_b128 v[42:45], v192 offset:64
	ds_read_b128 v[46:49], v192 offset:4672
	ds_read_b128 v[50:53], v192 offset:96
	ds_read_b128 v[54:57], v192 offset:4704
	s_waitcnt lgkmcnt(6)
	v_mfma_f32_32x32x16_bf16 v[18:33], v[6:9], v[130:133], 0
	v_mfma_f32_32x32x16_bf16 v[2:17], v[2:5], v[130:133], 0
	s_waitcnt lgkmcnt(5)
	v_mfma_f32_32x32x16_bf16 v[18:33], v[34:37], v[134:137], v[18:33]
	s_waitcnt lgkmcnt(4)
	v_mfma_f32_32x32x16_bf16 v[2:17], v[38:41], v[134:137], v[2:17]
	s_waitcnt lgkmcnt(3)
	v_mfma_f32_32x32x16_bf16 v[18:33], v[42:45], v[138:141], v[18:33]
	s_waitcnt lgkmcnt(2)
	v_mfma_f32_32x32x16_bf16 v[2:17], v[46:49], v[138:141], v[2:17]
	s_waitcnt lgkmcnt(1)
	v_mfma_f32_32x32x16_bf16 v[18:33], v[50:53], v[142:145], v[18:33]
	s_waitcnt lgkmcnt(0)
	v_mfma_f32_32x32x16_bf16 v[2:17], v[54:57], v[142:145], v[2:17]
	ds_read_b128 v[34:37], v192 offset:9216
	ds_read_b128 v[38:41], v192 offset:9248
	ds_read_b128 v[42:45], v192 offset:13824
	ds_read_b128 v[46:49], v192 offset:13856
	ds_read_b128 v[50:53], v192 offset:9280
	ds_read_b128 v[54:57], v192 offset:9312
	ds_read_b128 v[58:61], v192 offset:13888
	ds_read_b128 v[62:65], v192 offset:13920
	s_waitcnt lgkmcnt(7)
	v_mfma_f32_32x32x16_bf16 v[82:97], v[34:37], v[130:133], 0
	s_waitcnt lgkmcnt(5)
	v_mfma_f32_32x32x16_bf16 v[66:81], v[42:45], v[130:133], 0
	v_mfma_f32_32x32x16_bf16 v[82:97], v[38:41], v[134:137], v[82:97]
	s_waitcnt lgkmcnt(4)
	v_mfma_f32_32x32x16_bf16 v[66:81], v[46:49], v[134:137], v[66:81]
	s_waitcnt lgkmcnt(3)
	v_mfma_f32_32x32x16_bf16 v[82:97], v[50:53], v[138:141], v[82:97]
	s_waitcnt lgkmcnt(1)
	v_mfma_f32_32x32x16_bf16 v[66:81], v[58:61], v[138:141], v[66:81]
	v_mfma_f32_32x32x16_bf16 v[82:97], v[54:57], v[142:145], v[82:97]
	s_waitcnt lgkmcnt(0)
	v_mfma_f32_32x32x16_bf16 v[66:81], v[62:65], v[142:145], v[66:81]
	ds_read_b128 v[34:37], v194 offset:36864
	ds_read_b128 v[38:41], v194 offset:36896
	ds_read_b128 v[42:45], v194 offset:36928
	ds_read_b128 v[46:49], v194 offset:36960
	v_max3_f32 v0, v18, v2, v19
	v_max_f32_e32 v50, v17, v17
	v_max3_f32 v0, v0, v3, v20
	s_mov_b32 s28, 0xf149f2ca
	v_max3_f32 v0, v0, v4, v21
	v_max3_f32 v0, v0, v5, v22
	v_max3_f32 v0, v0, v6, v23
	v_max3_f32 v0, v0, v7, v24
	v_max3_f32 v0, v0, v8, v25
	v_max3_f32 v0, v0, v9, v26
	v_max3_f32 v0, v0, v10, v27
	v_max3_f32 v0, v0, v11, v28
	v_max3_f32 v0, v0, v12, v29
	v_max3_f32 v0, v0, v13, v30
	v_max3_f32 v0, v0, v14, v31
	v_max3_f32 v0, v0, v15, v32
	v_max3_f32 v0, v0, v16, v33
	s_nop 0
	v_max_f32_e32 v0, v0, v0
	v_max_f32_e32 v0, v0, v50
	v_mov_b32_e32 v50, v0
	v_nop
	v_nop
	v_permlane32_swap_b32 v50, v0
	s_nop 0
	v_max3_f32 v0, v50, v0, s28
	v_sub_f32_e32 v2, v2, v0
	v_exp_f32_e32 v158, v2
	v_sub_f32_e32 v2, v19, v0
	v_exp_f32_e32 v159, v2
	v_sub_f32_e32 v2, v3, v0
	v_exp_f32_e32 v160, v2
	v_sub_f32_e32 v2, v20, v0
	v_exp_f32_e32 v161, v2
	v_sub_f32_e32 v2, v4, v0
	v_exp_f32_e32 v162, v2
	v_sub_f32_e32 v2, v21, v0
	v_exp_f32_e32 v163, v2
	v_sub_f32_e32 v2, v5, v0
	v_exp_f32_e32 v164, v2
	v_sub_f32_e32 v2, v22, v0
	v_exp_f32_e32 v165, v2
	v_sub_f32_e32 v2, v6, v0
	v_exp_f32_e32 v166, v2
	v_sub_f32_e32 v2, v23, v0
	v_exp_f32_e32 v167, v2
	v_sub_f32_e32 v2, v7, v0
	v_exp_f32_e32 v168, v2
	v_sub_f32_e32 v2, v24, v0
	v_exp_f32_e32 v169, v2
	v_sub_f32_e32 v2, v8, v0
	v_exp_f32_e32 v170, v2
	v_sub_f32_e32 v2, v25, v0
	v_exp_f32_e32 v171, v2
	v_sub_f32_e32 v2, v9, v0
	v_exp_f32_e32 v172, v2
	v_sub_f32_e32 v2, v26, v0
	v_exp_f32_e32 v173, v2
	v_sub_f32_e32 v2, v10, v0
	v_exp_f32_e32 v174, v2
	v_sub_f32_e32 v2, v27, v0
	v_exp_f32_e32 v175, v2
	v_sub_f32_e32 v2, v11, v0
	v_exp_f32_e32 v176, v2
	v_sub_f32_e32 v2, v28, v0
	v_exp_f32_e32 v177, v2
	v_sub_f32_e32 v2, v12, v0
	v_exp_f32_e32 v178, v2
	v_sub_f32_e32 v2, v29, v0
	v_exp_f32_e32 v179, v2
	v_sub_f32_e32 v2, v13, v0
	v_exp_f32_e32 v180, v2
	v_sub_f32_e32 v2, v30, v0
	v_exp_f32_e32 v181, v2
	v_sub_f32_e32 v2, v14, v0
	v_exp_f32_e32 v182, v2
	v_sub_f32_e32 v2, v31, v0
	v_sub_f32_e32 v50, 0xf149f2ca, v0
	v_exp_f32_e32 v183, v2
	v_sub_f32_e32 v2, v15, v0
	v_exp_f32_e32 v184, v2
	v_sub_f32_e32 v2, v32, v0
	v_exp_f32_e32 v3, v50
	v_exp_f32_e32 v185, v2
	v_sub_f32_e32 v2, v16, v0
	v_exp_f32_e32 v186, v2
	v_sub_f32_e32 v2, v33, v0
	v_sub_f32_e32 v18, v18, v0
	v_exp_f32_e32 v187, v2
	v_sub_f32_e32 v2, v17, v0
	v_exp_f32_e32 v157, v18
	v_exp_f32_e32 v189, v2
	v_cmp_neq_f32_e32 vcc, 1.0, v3
	s_cmp_lg_u64 vcc, 0
	v_mul_f32_e32 v188, 0, v3
	s_cselect_b64 vcc, -1, 0
	v_cndmask_b32_e32 v2, 0, v188, vcc
	v_mov_b32_e32 v3, v2
	v_mov_b32_e32 v4, v2
	v_mov_b32_e32 v5, v2
	v_mov_b32_e32 v6, v2
	v_mov_b32_e32 v7, v2
	v_mov_b32_e32 v8, v2
	v_mov_b32_e32 v9, v2
	v_mov_b32_e32 v10, v2
	v_mov_b32_e32 v11, v2
	v_mov_b32_e32 v12, v2
	v_mov_b32_e32 v13, v2
	v_mov_b32_e32 v14, v2
	v_mov_b32_e32 v15, v2
	v_mov_b32_e32 v16, v2
	v_mov_b32_e32 v17, v2
	v_cvt_pk_bf16_f32 v122, v174, v176
	v_cvt_pk_bf16_f32 v123, v178, v180
	v_cvt_pk_bf16_f32 v124, v182, v184
	v_cvt_pk_bf16_f32 v125, v186, v189
	v_cvt_pk_bf16_f32 v126, v158, v160
	v_cvt_pk_bf16_f32 v127, v162, v164
	v_cvt_pk_bf16_f32 v128, v166, v168
	v_cvt_pk_bf16_f32 v129, v170, v172
	v_cvt_pk_bf16_f32 v146, v173, v175
	v_cvt_pk_bf16_f32 v147, v177, v179
	v_cvt_pk_bf16_f32 v148, v181, v183
	v_cvt_pk_bf16_f32 v149, v185, v187
	v_cvt_pk_bf16_f32 v150, v157, v159
	v_cvt_pk_bf16_f32 v151, v161, v163
	v_cvt_pk_bf16_f32 v152, v165, v167
	v_cvt_pk_bf16_f32 v153, v169, v171
	s_waitcnt lgkmcnt(3)
	s_nop 0
	v_mfma_f32_32x32x16_bf16 v[50:65], v[34:37], v[150:153], v[2:17]
	ds_read_b128 v[18:21], v194 offset:45664
	ds_read_b128 v[22:25], v194 offset:45632
	ds_read_b128 v[26:29], v194 offset:45568
	ds_read_b128 v[30:33], v194 offset:45600
	s_waitcnt lgkmcnt(6)
	v_mfma_f32_32x32x16_bf16 v[50:65], v[38:41], v[146:149], v[50:65]
	s_waitcnt lgkmcnt(5)
	v_mfma_f32_32x32x16_bf16 v[50:65], v[42:45], v[126:129], v[50:65]
	s_waitcnt lgkmcnt(4)
	v_mfma_f32_32x32x16_bf16 v[50:65], v[46:49], v[122:125], v[50:65]
	s_waitcnt lgkmcnt(1)
	v_mfma_f32_32x32x16_bf16 v[34:49], v[26:29], v[150:153], v[2:17]
	ds_read_b128 v[198:201], v194 offset:54368
	ds_read_b128 v[202:205], v194 offset:54336
	ds_read_b128 v[206:209], v194 offset:54272
	ds_read_b128 v[210:213], v194 offset:54304
	s_waitcnt lgkmcnt(4)
	v_mfma_f32_32x32x16_bf16 v[34:49], v[30:33], v[146:149], v[34:49]
	v_mfma_f32_32x32x16_bf16 v[34:49], v[22:25], v[126:129], v[34:49]
	v_mfma_f32_32x32x16_bf16 v[34:49], v[18:21], v[122:125], v[34:49]
	s_waitcnt lgkmcnt(1)
	v_mfma_f32_32x32x16_bf16 v[18:33], v[206:209], v[150:153], v[2:17]
	s_waitcnt lgkmcnt(0)
	v_mfma_f32_32x32x16_bf16 v[18:33], v[210:213], v[146:149], v[18:33]
	v_mfma_f32_32x32x16_bf16 v[18:33], v[202:205], v[126:129], v[18:33]
	v_mfma_f32_32x32x16_bf16 v[18:33], v[198:201], v[122:125], v[18:33]
	ds_read_b128 v[198:201], v194 offset:63072
	ds_read_b128 v[202:205], v194 offset:63040
	ds_read_b128 v[206:209], v194 offset:62976
	ds_read_b128 v[210:213], v194 offset:63008
	s_waitcnt lgkmcnt(1)
	v_mfma_f32_32x32x16_bf16 v[2:17], v[206:209], v[150:153], v[2:17]
	s_waitcnt lgkmcnt(0)
	v_mfma_f32_32x32x16_bf16 v[2:17], v[210:213], v[146:149], v[2:17]
	v_mfma_f32_32x32x16_bf16 v[2:17], v[202:205], v[126:129], v[2:17]
	v_mfma_f32_32x32x16_bf16 v[2:17], v[198:201], v[122:125], v[2:17]
	ds_read_b128 v[150:153], v194 offset:36992
	ds_read_b128 v[146:149], v194 offset:37024
	ds_read_b128 v[122:125], v194 offset:37056
	ds_read_b128 v[126:129], v194 offset:37088
	v_max3_f32 v191, v82, v66, v83
	v_max_f32_e32 v195, v81, v81
	v_max3_f32 v191, v191, v67, v84
	v_max3_f32 v191, v191, v68, v85
	v_max3_f32 v191, v191, v69, v86
	v_max3_f32 v191, v191, v70, v87
	v_max3_f32 v191, v191, v71, v88
	v_max3_f32 v191, v191, v72, v89
	v_max3_f32 v191, v191, v73, v90
	v_max3_f32 v191, v191, v74, v91
	v_max3_f32 v191, v191, v75, v92
	v_max3_f32 v191, v191, v76, v93
	v_max3_f32 v191, v191, v77, v94
	v_max3_f32 v191, v191, v78, v95
	v_max3_f32 v191, v191, v79, v96
	v_max3_f32 v191, v191, v80, v97
	s_nop 0
	v_max_f32_e32 v191, v191, v191
	v_max_f32_e32 v191, v191, v195
	v_mov_b32_e32 v195, v191
	v_nop
	v_nop
	v_permlane32_swap_b32 v195, v191
	s_nop 0
	v_max3_f32 v243, v0, v195, v191
	v_sub_f32_e32 v0, v0, v243
	v_exp_f32_e32 v0, v0
	s_nop 0
	v_cmp_neq_f32_e32 vcc, 1.0, v0
	s_cbranch_vccz .LBB0_161
	v_pk_mul_f32 v[64:65], v[64:65], v[0:1] op_sel_hi:[1,0]
	v_pk_mul_f32 v[62:63], v[62:63], v[0:1] op_sel_hi:[1,0]
	v_pk_mul_f32 v[60:61], v[60:61], v[0:1] op_sel_hi:[1,0]
	v_pk_mul_f32 v[58:59], v[58:59], v[0:1] op_sel_hi:[1,0]
	v_pk_mul_f32 v[56:57], v[56:57], v[0:1] op_sel_hi:[1,0]
	v_pk_mul_f32 v[54:55], v[54:55], v[0:1] op_sel_hi:[1,0]
	v_pk_mul_f32 v[52:53], v[52:53], v[0:1] op_sel_hi:[1,0]
	v_pk_mul_f32 v[50:51], v[50:51], v[0:1] op_sel_hi:[1,0]
	v_pk_mul_f32 v[48:49], v[48:49], v[0:1] op_sel_hi:[1,0]
	v_pk_mul_f32 v[46:47], v[46:47], v[0:1] op_sel_hi:[1,0]
	v_pk_mul_f32 v[44:45], v[44:45], v[0:1] op_sel_hi:[1,0]
	v_pk_mul_f32 v[42:43], v[42:43], v[0:1] op_sel_hi:[1,0]
	v_pk_mul_f32 v[40:41], v[40:41], v[0:1] op_sel_hi:[1,0]
	v_pk_mul_f32 v[38:39], v[38:39], v[0:1] op_sel_hi:[1,0]
	v_pk_mul_f32 v[36:37], v[36:37], v[0:1] op_sel_hi:[1,0]
	v_pk_mul_f32 v[34:35], v[34:35], v[0:1] op_sel_hi:[1,0]
	v_pk_mul_f32 v[32:33], v[32:33], v[0:1] op_sel_hi:[1,0]
	v_pk_mul_f32 v[30:31], v[30:31], v[0:1] op_sel_hi:[1,0]
	v_pk_mul_f32 v[28:29], v[28:29], v[0:1] op_sel_hi:[1,0]
	v_pk_mul_f32 v[26:27], v[26:27], v[0:1] op_sel_hi:[1,0]
	v_pk_mul_f32 v[24:25], v[24:25], v[0:1] op_sel_hi:[1,0]
	v_pk_mul_f32 v[22:23], v[22:23], v[0:1] op_sel_hi:[1,0]
	v_pk_mul_f32 v[20:21], v[20:21], v[0:1] op_sel_hi:[1,0]
	v_pk_mul_f32 v[18:19], v[18:19], v[0:1] op_sel_hi:[1,0]
	v_pk_mul_f32 v[16:17], v[16:17], v[0:1] op_sel_hi:[1,0]
	v_pk_mul_f32 v[14:15], v[14:15], v[0:1] op_sel_hi:[1,0]
	v_pk_mul_f32 v[12:13], v[12:13], v[0:1] op_sel_hi:[1,0]
	v_pk_mul_f32 v[10:11], v[10:11], v[0:1] op_sel_hi:[1,0]
	v_pk_mul_f32 v[8:9], v[8:9], v[0:1] op_sel_hi:[1,0]
	v_pk_mul_f32 v[6:7], v[6:7], v[0:1] op_sel_hi:[1,0]
	v_pk_mul_f32 v[4:5], v[4:5], v[0:1] op_sel_hi:[1,0]
	v_pk_mul_f32 v[2:3], v[2:3], v[0:1] op_sel_hi:[1,0]
.LBB0_161:
	v_sub_f32_e32 v66, v66, v243
	v_exp_f32_e32 v202, v66
	v_sub_f32_e32 v66, v83, v243
	v_exp_f32_e32 v203, v66
	v_sub_f32_e32 v66, v67, v243
	v_exp_f32_e32 v204, v66
	v_sub_f32_e32 v66, v84, v243
	v_exp_f32_e32 v205, v66
	v_sub_f32_e32 v66, v68, v243
	v_exp_f32_e32 v206, v66
	v_sub_f32_e32 v66, v85, v243
	v_exp_f32_e32 v207, v66
	v_sub_f32_e32 v66, v69, v243
	v_exp_f32_e32 v208, v66
	v_sub_f32_e32 v66, v86, v243
	v_exp_f32_e32 v209, v66
	v_sub_f32_e32 v66, v70, v243
	v_exp_f32_e32 v220, v66
	v_sub_f32_e32 v66, v87, v243
	v_exp_f32_e32 v221, v66
	v_sub_f32_e32 v66, v71, v243
	v_exp_f32_e32 v222, v66
	v_sub_f32_e32 v66, v88, v243
	v_exp_f32_e32 v223, v66
	v_sub_f32_e32 v66, v72, v243
	v_exp_f32_e32 v224, v66
	v_sub_f32_e32 v66, v89, v243
	v_exp_f32_e32 v225, v66
	v_sub_f32_e32 v66, v73, v243
	v_exp_f32_e32 v226, v66
	v_sub_f32_e32 v66, v90, v243
	v_exp_f32_e32 v227, v66
	v_sub_f32_e32 v66, v74, v243
	v_exp_f32_e32 v228, v66
	v_sub_f32_e32 v66, v91, v243
	v_exp_f32_e32 v229, v66
	v_sub_f32_e32 v66, v75, v243
	v_exp_f32_e32 v230, v66
	v_sub_f32_e32 v66, v92, v243
	v_exp_f32_e32 v231, v66
	v_sub_f32_e32 v66, v76, v243
	v_exp_f32_e32 v232, v66
	v_sub_f32_e32 v66, v93, v243
	v_exp_f32_e32 v233, v66
	v_sub_f32_e32 v66, v77, v243
	v_exp_f32_e32 v234, v66
	v_sub_f32_e32 v66, v94, v243
	v_exp_f32_e32 v235, v66
	v_sub_f32_e32 v66, v78, v243
	v_exp_f32_e32 v236, v66
	v_sub_f32_e32 v66, v95, v243
	v_exp_f32_e32 v237, v66
	v_sub_f32_e32 v66, v79, v243
	v_exp_f32_e32 v238, v66
	v_sub_f32_e32 v66, v96, v243
	v_exp_f32_e32 v239, v66
	v_sub_f32_e32 v66, v80, v243
	v_exp_f32_e32 v240, v66
	v_sub_f32_e32 v66, v97, v243
	v_sub_f32_e32 v82, v82, v243
	v_exp_f32_e32 v241, v66
	v_sub_f32_e32 v66, v81, v243
	v_exp_f32_e32 v195, v82
	v_exp_f32_e32 v242, v66
	v_add_u32_e32 v191, 0x9000, v194
	v_cvt_pk_bf16_f32 v66, v228, v230
	v_cvt_pk_bf16_f32 v67, v232, v234
	v_cvt_pk_bf16_f32 v68, v236, v238
	v_cvt_pk_bf16_f32 v69, v240, v242
	v_cvt_pk_bf16_f32 v70, v202, v204
	v_cvt_pk_bf16_f32 v71, v206, v208
	v_cvt_pk_bf16_f32 v72, v220, v222
	v_cvt_pk_bf16_f32 v73, v224, v226
	v_cvt_pk_bf16_f32 v74, v227, v229
	v_cvt_pk_bf16_f32 v75, v231, v233
	v_cvt_pk_bf16_f32 v76, v235, v237
	v_cvt_pk_bf16_f32 v77, v239, v241
	v_cvt_pk_bf16_f32 v78, v195, v203
	v_cvt_pk_bf16_f32 v79, v205, v207
	v_cvt_pk_bf16_f32 v80, v209, v221
	v_cvt_pk_bf16_f32 v81, v223, v225
	s_waitcnt lgkmcnt(3)
	s_nop 0
	v_mfma_f32_32x32x16_bf16 v[50:65], v[150:153], v[78:81], v[50:65]
	ds_read_b128 v[82:85], v194 offset:45792
	ds_read_b128 v[86:89], v194 offset:45760
	ds_read_b128 v[90:93], v194 offset:45696
	ds_read_b128 v[94:97], v194 offset:45728
	s_waitcnt lgkmcnt(6)
	v_mfma_f32_32x32x16_bf16 v[50:65], v[146:149], v[74:77], v[50:65]
	s_waitcnt lgkmcnt(5)
	v_mfma_f32_32x32x16_bf16 v[50:65], v[122:125], v[70:73], v[50:65]
	s_waitcnt lgkmcnt(4)
	v_mfma_f32_32x32x16_bf16 v[50:65], v[126:129], v[66:69], v[50:65]
	s_waitcnt lgkmcnt(1)
	v_mfma_f32_32x32x16_bf16 v[34:49], v[90:93], v[78:81], v[34:49]
	s_waitcnt lgkmcnt(0)
	v_mfma_f32_32x32x16_bf16 v[34:49], v[94:97], v[74:77], v[34:49]
	v_mfma_f32_32x32x16_bf16 v[34:49], v[86:89], v[70:73], v[34:49]
	v_mfma_f32_32x32x16_bf16 v[34:49], v[82:85], v[66:69], v[34:49]
	ds_read_b128 v[82:85], v194 offset:54496
	ds_read_b128 v[86:89], v194 offset:54464
	ds_read_b128 v[90:93], v194 offset:54400
	ds_read_b128 v[94:97], v194 offset:54432
	s_waitcnt lgkmcnt(1)
	v_mfma_f32_32x32x16_bf16 v[18:33], v[90:93], v[78:81], v[18:33]
	s_waitcnt lgkmcnt(0)
	v_mfma_f32_32x32x16_bf16 v[18:33], v[94:97], v[74:77], v[18:33]
	v_mfma_f32_32x32x16_bf16 v[18:33], v[86:89], v[70:73], v[18:33]
	v_mfma_f32_32x32x16_bf16 v[18:33], v[82:85], v[66:69], v[18:33]
	ds_read_b128 v[82:85], v194 offset:63200
	ds_read_b128 v[86:89], v194 offset:63168
	ds_read_b128 v[90:93], v194 offset:63104
	ds_read_b128 v[94:97], v194 offset:63136
	s_waitcnt lgkmcnt(1)
	v_mfma_f32_32x32x16_bf16 v[2:17], v[90:93], v[78:81], v[2:17]
	s_waitcnt lgkmcnt(0)
	v_mfma_f32_32x32x16_bf16 v[2:17], v[94:97], v[74:77], v[2:17]
	v_mfma_f32_32x32x16_bf16 v[2:17], v[86:89], v[70:73], v[2:17]
	v_mfma_f32_32x32x16_bf16 v[2:17], v[82:85], v[66:69], v[2:17]
	v_add_u32_e32 v66, 0x8800, v193
	s_waitcnt vmcnt(5)
	ds_write_b128 v190, v[98:101] offset:18432
	s_waitcnt vmcnt(4)
	ds_write_b128 v190, v[118:121] offset:27648
	s_waitcnt vmcnt(3)
	ds_write2_b64 v66, v[114:115], v[116:117] offset1:2
	v_add_u32_e32 v66, 0xa800, v193
	s_waitcnt vmcnt(2)
	ds_write2_b64 v66, v[110:111], v[112:113] offset0:64 offset1:66
	v_add_u32_e32 v66, 0xc800, v193
	s_waitcnt vmcnt(1)
	ds_write2_b64 v66, v[106:107], v[108:109] offset0:128 offset1:130
	v_add_u32_e32 v66, 0xe800, v193
	s_waitcnt vmcnt(0)
	ds_write2_b64 v66, v[102:103], v[104:105] offset0:192 offset1:194
	s_waitcnt lgkmcnt(0)
	s_barrier
	ds_read_b128 v[66:69], v192 offset:18432
	ds_read_b128 v[70:73], v192 offset:18464
	ds_read_b128 v[74:77], v192 offset:23040
	ds_read_b128 v[78:81], v192 offset:23072
	ds_read_b128 v[82:85], v192 offset:18496
	ds_read_b128 v[86:89], v192 offset:18528
	ds_read_b128 v[90:93], v192 offset:23104
	ds_read_b128 v[94:97], v192 offset:23136
	s_waitcnt lgkmcnt(7)
	v_mfma_f32_32x32x16_bf16 v[114:129], v[66:69], v[130:133], 0
	s_waitcnt lgkmcnt(5)
	v_mfma_f32_32x32x16_bf16 v[98:113], v[74:77], v[130:133], 0
	v_mfma_f32_32x32x16_bf16 v[114:129], v[70:73], v[134:137], v[114:129]
	s_waitcnt lgkmcnt(4)
	v_mfma_f32_32x32x16_bf16 v[98:113], v[78:81], v[134:137], v[98:113]
	s_waitcnt lgkmcnt(3)
	v_mfma_f32_32x32x16_bf16 v[114:129], v[82:85], v[138:141], v[114:129]
	s_waitcnt lgkmcnt(1)
	v_mfma_f32_32x32x16_bf16 v[98:113], v[90:93], v[138:141], v[98:113]
	v_mfma_f32_32x32x16_bf16 v[114:129], v[86:89], v[142:145], v[114:129]
	s_waitcnt lgkmcnt(0)
	v_mfma_f32_32x32x16_bf16 v[98:113], v[94:97], v[142:145], v[98:113]
	ds_read_b128 v[66:69], v192 offset:27648
	ds_read_b128 v[146:149], v192 offset:27680
	ds_read_b128 v[70:73], v192 offset:32256
	ds_read_b128 v[150:153], v192 offset:32288
	ds_read_b128 v[198:201], v192 offset:27712
	ds_read_b128 v[210:213], v192 offset:27744
	ds_read_b128 v[214:217], v192 offset:32320
	ds_read_b128 v[244:247], v192 offset:32352
	s_waitcnt lgkmcnt(7)
	v_mfma_f32_32x32x16_bf16 v[82:97], v[66:69], v[130:133], 0
	s_waitcnt lgkmcnt(5)
	v_mfma_f32_32x32x16_bf16 v[66:81], v[70:73], v[130:133], 0
	v_mfma_f32_32x32x16_bf16 v[82:97], v[146:149], v[134:137], v[82:97]
	s_waitcnt lgkmcnt(4)
	v_mfma_f32_32x32x16_bf16 v[66:81], v[150:153], v[134:137], v[66:81]
	s_waitcnt lgkmcnt(3)
	v_mfma_f32_32x32x16_bf16 v[82:97], v[198:201], v[138:141], v[82:97]
	s_waitcnt lgkmcnt(1)
	v_mfma_f32_32x32x16_bf16 v[66:81], v[214:217], v[138:141], v[66:81]
	v_mfma_f32_32x32x16_bf16 v[82:97], v[210:213], v[142:145], v[82:97]
	s_waitcnt lgkmcnt(0)
	v_mfma_f32_32x32x16_bf16 v[66:81], v[244:247], v[142:145], v[66:81]
	ds_read_b128 v[142:145], v191 offset:34816
	ds_read_b128 v[138:141], v191 offset:34848
	ds_read_b128 v[130:133], v191 offset:34880
	ds_read_b128 v[134:137], v191 offset:34912
	v_max3_f32 v146, v114, v98, v115
	v_max_f32_e32 v147, v113, v113
	v_max3_f32 v146, v146, v99, v116
	v_max3_f32 v146, v146, v100, v117
	v_max3_f32 v146, v146, v101, v118
	v_max3_f32 v146, v146, v102, v119
	v_max3_f32 v146, v146, v103, v120
	v_max3_f32 v146, v146, v104, v121
	v_max3_f32 v146, v146, v105, v122
	v_max3_f32 v146, v146, v106, v123
	v_max3_f32 v146, v146, v107, v124
	v_max3_f32 v146, v146, v108, v125
	v_max3_f32 v146, v146, v109, v126
	v_max3_f32 v146, v146, v110, v127
	v_max3_f32 v146, v146, v111, v128
	v_max3_f32 v146, v146, v112, v129
	s_nop 0
	v_max_f32_e32 v146, v146, v146
	v_max_f32_e32 v146, v146, v147
	v_mov_b32_e32 v147, v146
	v_nop
	v_nop
	v_permlane32_swap_b32 v146, v147
	s_nop 0
	v_max3_f32 v251, v243, v146, v147
	v_sub_f32_e32 v146, v243, v251
	v_exp_f32_e32 v146, v146
	s_nop 0
	v_cmp_neq_f32_e32 vcc, 1.0, v146
	s_cbranch_vccz .LBB0_163
	v_pk_mul_f32 v[64:65], v[64:65], v[146:147] op_sel_hi:[1,0]
	v_pk_mul_f32 v[62:63], v[62:63], v[146:147] op_sel_hi:[1,0]
	v_pk_mul_f32 v[60:61], v[60:61], v[146:147] op_sel_hi:[1,0]
	v_pk_mul_f32 v[58:59], v[58:59], v[146:147] op_sel_hi:[1,0]
	v_pk_mul_f32 v[56:57], v[56:57], v[146:147] op_sel_hi:[1,0]
	v_pk_mul_f32 v[54:55], v[54:55], v[146:147] op_sel_hi:[1,0]
	v_pk_mul_f32 v[52:53], v[52:53], v[146:147] op_sel_hi:[1,0]
	v_pk_mul_f32 v[50:51], v[50:51], v[146:147] op_sel_hi:[1,0]
	v_pk_mul_f32 v[48:49], v[48:49], v[146:147] op_sel_hi:[1,0]
	v_pk_mul_f32 v[46:47], v[46:47], v[146:147] op_sel_hi:[1,0]
	v_pk_mul_f32 v[44:45], v[44:45], v[146:147] op_sel_hi:[1,0]
	v_pk_mul_f32 v[42:43], v[42:43], v[146:147] op_sel_hi:[1,0]
	v_pk_mul_f32 v[40:41], v[40:41], v[146:147] op_sel_hi:[1,0]
	v_pk_mul_f32 v[38:39], v[38:39], v[146:147] op_sel_hi:[1,0]
	v_pk_mul_f32 v[36:37], v[36:37], v[146:147] op_sel_hi:[1,0]
	v_pk_mul_f32 v[34:35], v[34:35], v[146:147] op_sel_hi:[1,0]
	v_pk_mul_f32 v[32:33], v[32:33], v[146:147] op_sel_hi:[1,0]
	v_pk_mul_f32 v[30:31], v[30:31], v[146:147] op_sel_hi:[1,0]
	v_pk_mul_f32 v[28:29], v[28:29], v[146:147] op_sel_hi:[1,0]
	v_pk_mul_f32 v[26:27], v[26:27], v[146:147] op_sel_hi:[1,0]
	v_pk_mul_f32 v[24:25], v[24:25], v[146:147] op_sel_hi:[1,0]
	v_pk_mul_f32 v[22:23], v[22:23], v[146:147] op_sel_hi:[1,0]
	v_pk_mul_f32 v[20:21], v[20:21], v[146:147] op_sel_hi:[1,0]
	v_pk_mul_f32 v[18:19], v[18:19], v[146:147] op_sel_hi:[1,0]
	v_pk_mul_f32 v[16:17], v[16:17], v[146:147] op_sel_hi:[1,0]
	v_pk_mul_f32 v[14:15], v[14:15], v[146:147] op_sel_hi:[1,0]
	v_pk_mul_f32 v[12:13], v[12:13], v[146:147] op_sel_hi:[1,0]
	v_pk_mul_f32 v[10:11], v[10:11], v[146:147] op_sel_hi:[1,0]
	v_pk_mul_f32 v[8:9], v[8:9], v[146:147] op_sel_hi:[1,0]
	v_pk_mul_f32 v[6:7], v[6:7], v[146:147] op_sel_hi:[1,0]
	v_pk_mul_f32 v[4:5], v[4:5], v[146:147] op_sel_hi:[1,0]
	v_pk_mul_f32 v[2:3], v[2:3], v[146:147] op_sel_hi:[1,0]
.LBB0_163:
	v_sub_f32_e32 v98, v98, v251
	v_exp_f32_e32 v148, v98
	v_sub_f32_e32 v98, v115, v251
	v_exp_f32_e32 v115, v98
	v_sub_f32_e32 v98, v99, v251
	v_exp_f32_e32 v149, v98
	v_sub_f32_e32 v98, v116, v251
	v_exp_f32_e32 v150, v98
	v_sub_f32_e32 v98, v100, v251
	v_exp_f32_e32 v151, v98
	v_sub_f32_e32 v98, v117, v251
	v_exp_f32_e32 v152, v98
	v_sub_f32_e32 v98, v101, v251
	v_exp_f32_e32 v153, v98
	v_sub_f32_e32 v98, v118, v251
	v_exp_f32_e32 v118, v98
	v_sub_f32_e32 v98, v102, v251
	v_exp_f32_e32 v190, v98
	v_sub_f32_e32 v98, v119, v251
	v_exp_f32_e32 v119, v98
	v_sub_f32_e32 v98, v103, v251
	v_exp_f32_e32 v192, v98
	v_sub_f32_e32 v98, v120, v251
	v_exp_f32_e32 v120, v98
	v_sub_f32_e32 v98, v104, v251
	v_exp_f32_e32 v193, v98
	v_sub_f32_e32 v98, v121, v251
	v_exp_f32_e32 v121, v98
	v_sub_f32_e32 v98, v105, v251
	v_exp_f32_e32 v194, v98
	v_sub_f32_e32 v98, v122, v251
	v_exp_f32_e32 v122, v98
	v_sub_f32_e32 v98, v106, v251
	v_exp_f32_e32 v243, v98
	v_sub_f32_e32 v98, v123, v251
	v_exp_f32_e32 v123, v98
	v_sub_f32_e32 v98, v107, v251
	v_exp_f32_e32 v244, v98
	v_sub_f32_e32 v98, v124, v251
	v_exp_f32_e32 v124, v98
	v_sub_f32_e32 v98, v108, v251
	v_exp_f32_e32 v245, v98
	v_sub_f32_e32 v98, v125, v251
	v_exp_f32_e32 v125, v98
	v_sub_f32_e32 v98, v109, v251
	v_exp_f32_e32 v246, v98
	v_sub_f32_e32 v98, v126, v251
	v_exp_f32_e32 v126, v98
	v_sub_f32_e32 v98, v110, v251
	v_exp_f32_e32 v247, v98
	v_sub_f32_e32 v98, v127, v251
	v_exp_f32_e32 v127, v98
	v_sub_f32_e32 v98, v111, v251
	v_exp_f32_e32 v248, v98
	v_sub_f32_e32 v98, v128, v251
	v_exp_f32_e32 v128, v98
	v_sub_f32_e32 v98, v112, v251
	v_exp_f32_e32 v249, v98
	v_sub_f32_e32 v98, v129, v251
	v_sub_f32_e32 v114, v114, v251
	v_exp_f32_e32 v129, v98
	v_sub_f32_e32 v98, v113, v251
	v_exp_f32_e32 v147, v114
	v_exp_f32_e32 v250, v98
	v_cvt_pk_bf16_f32 v98, v243, v244
	v_cvt_pk_bf16_f32 v99, v245, v246
	v_cvt_pk_bf16_f32 v100, v247, v248
	v_cvt_pk_bf16_f32 v101, v249, v250
	v_cvt_pk_bf16_f32 v102, v148, v149
	v_cvt_pk_bf16_f32 v103, v151, v153
	v_cvt_pk_bf16_f32 v104, v190, v192
	v_cvt_pk_bf16_f32 v105, v193, v194
	v_cvt_pk_bf16_f32 v106, v122, v123
	v_cvt_pk_bf16_f32 v107, v124, v125
	v_cvt_pk_bf16_f32 v108, v126, v127
	v_cvt_pk_bf16_f32 v109, v128, v129
	v_cvt_pk_bf16_f32 v110, v147, v115
	v_cvt_pk_bf16_f32 v111, v150, v152
	v_cvt_pk_bf16_f32 v112, v118, v119
	v_cvt_pk_bf16_f32 v113, v120, v121
	s_waitcnt lgkmcnt(3)
	s_nop 0
	v_mfma_f32_32x32x16_bf16 v[50:65], v[142:145], v[110:113], v[50:65]
	s_waitcnt lgkmcnt(2)
	v_mfma_f32_32x32x16_bf16 v[50:65], v[138:141], v[106:109], v[50:65]
	s_waitcnt lgkmcnt(1)
	v_mfma_f32_32x32x16_bf16 v[50:65], v[130:133], v[102:105], v[50:65]
	s_waitcnt lgkmcnt(0)
	v_mfma_f32_32x32x16_bf16 v[50:65], v[134:137], v[98:101], v[50:65]
	ds_read_b128 v[130:133], v191 offset:43616
	ds_read_b128 v[134:137], v191 offset:43584
	ds_read_b128 v[138:141], v191 offset:43520
	ds_read_b128 v[142:145], v191 offset:43552
	s_waitcnt lgkmcnt(1)
	v_mfma_f32_32x32x16_bf16 v[34:49], v[138:141], v[110:113], v[34:49]
	s_waitcnt lgkmcnt(0)
	v_mfma_f32_32x32x16_bf16 v[34:49], v[142:145], v[106:109], v[34:49]
	v_mfma_f32_32x32x16_bf16 v[34:49], v[134:137], v[102:105], v[34:49]
	v_mfma_f32_32x32x16_bf16 v[34:49], v[130:133], v[98:101], v[34:49]
	ds_read_b128 v[130:133], v191 offset:52320
	ds_read_b128 v[134:137], v191 offset:52288
	ds_read_b128 v[138:141], v191 offset:52224
	ds_read_b128 v[142:145], v191 offset:52256
	s_waitcnt lgkmcnt(1)
	v_mfma_f32_32x32x16_bf16 v[18:33], v[138:141], v[110:113], v[18:33]
	s_waitcnt lgkmcnt(0)
	v_mfma_f32_32x32x16_bf16 v[18:33], v[142:145], v[106:109], v[18:33]
	v_mfma_f32_32x32x16_bf16 v[18:33], v[134:137], v[102:105], v[18:33]
	v_mfma_f32_32x32x16_bf16 v[18:33], v[130:133], v[98:101], v[18:33]
	ds_read_b128 v[130:133], v191 offset:61024
	ds_read_b128 v[134:137], v191 offset:60992
	ds_read_b128 v[138:141], v191 offset:60928
	ds_read_b128 v[142:145], v191 offset:60960
	s_waitcnt lgkmcnt(1)
	v_mfma_f32_32x32x16_bf16 v[2:17], v[138:141], v[110:113], v[2:17]
	s_waitcnt lgkmcnt(0)
	v_mfma_f32_32x32x16_bf16 v[2:17], v[142:145], v[106:109], v[2:17]
	v_mfma_f32_32x32x16_bf16 v[2:17], v[134:137], v[102:105], v[2:17]
	v_mfma_f32_32x32x16_bf16 v[2:17], v[130:133], v[98:101], v[2:17]
	ds_read_b128 v[110:113], v191 offset:34944
	ds_read_b128 v[106:109], v191 offset:34976
	ds_read_b128 v[98:101], v191 offset:35008
	ds_read_b128 v[102:105], v191 offset:35040
	v_max3_f32 v114, v82, v66, v83
	v_max_f32_e32 v116, v81, v81
	v_max3_f32 v114, v114, v67, v84
	v_max3_f32 v114, v114, v68, v85
	v_max3_f32 v114, v114, v69, v86
	v_max3_f32 v114, v114, v70, v87
	v_max3_f32 v114, v114, v71, v88
	v_max3_f32 v114, v114, v72, v89
	v_max3_f32 v114, v114, v73, v90
	v_max3_f32 v114, v114, v74, v91
	v_max3_f32 v114, v114, v75, v92
	v_max3_f32 v114, v114, v76, v93
	v_max3_f32 v114, v114, v77, v94
	v_max3_f32 v114, v114, v78, v95
	v_max3_f32 v114, v114, v79, v96
	v_max3_f32 v114, v114, v80, v97
	s_nop 0
	v_max_f32_e32 v114, v114, v114
	v_max_f32_e32 v114, v114, v116
	v_mov_b32_e32 v116, v114
	v_nop
	v_nop
	v_permlane32_swap_b32 v114, v116
	s_nop 0
	v_max3_f32 v130, v251, v114, v116
	v_sub_f32_e32 v114, v251, v130
	v_exp_f32_e32 v114, v114
	s_nop 0
	v_cmp_neq_f32_e32 vcc, 1.0, v114
	s_cbranch_vccz .LBB0_165
	v_pk_mul_f32 v[64:65], v[64:65], v[114:115] op_sel_hi:[1,0]
	v_pk_mul_f32 v[62:63], v[62:63], v[114:115] op_sel_hi:[1,0]
	v_pk_mul_f32 v[60:61], v[60:61], v[114:115] op_sel_hi:[1,0]
	v_pk_mul_f32 v[58:59], v[58:59], v[114:115] op_sel_hi:[1,0]
	v_pk_mul_f32 v[56:57], v[56:57], v[114:115] op_sel_hi:[1,0]
	v_pk_mul_f32 v[54:55], v[54:55], v[114:115] op_sel_hi:[1,0]
	v_pk_mul_f32 v[52:53], v[52:53], v[114:115] op_sel_hi:[1,0]
	v_pk_mul_f32 v[50:51], v[50:51], v[114:115] op_sel_hi:[1,0]
	v_pk_mul_f32 v[48:49], v[48:49], v[114:115] op_sel_hi:[1,0]
	v_pk_mul_f32 v[46:47], v[46:47], v[114:115] op_sel_hi:[1,0]
	v_pk_mul_f32 v[44:45], v[44:45], v[114:115] op_sel_hi:[1,0]
	v_pk_mul_f32 v[42:43], v[42:43], v[114:115] op_sel_hi:[1,0]
	v_pk_mul_f32 v[40:41], v[40:41], v[114:115] op_sel_hi:[1,0]
	v_pk_mul_f32 v[38:39], v[38:39], v[114:115] op_sel_hi:[1,0]
	v_pk_mul_f32 v[36:37], v[36:37], v[114:115] op_sel_hi:[1,0]
	v_pk_mul_f32 v[34:35], v[34:35], v[114:115] op_sel_hi:[1,0]
	v_pk_mul_f32 v[32:33], v[32:33], v[114:115] op_sel_hi:[1,0]
	v_pk_mul_f32 v[30:31], v[30:31], v[114:115] op_sel_hi:[1,0]
	v_pk_mul_f32 v[28:29], v[28:29], v[114:115] op_sel_hi:[1,0]
	v_pk_mul_f32 v[26:27], v[26:27], v[114:115] op_sel_hi:[1,0]
	v_pk_mul_f32 v[24:25], v[24:25], v[114:115] op_sel_hi:[1,0]
	v_pk_mul_f32 v[22:23], v[22:23], v[114:115] op_sel_hi:[1,0]
	v_pk_mul_f32 v[20:21], v[20:21], v[114:115] op_sel_hi:[1,0]
	v_pk_mul_f32 v[18:19], v[18:19], v[114:115] op_sel_hi:[1,0]
	v_pk_mul_f32 v[16:17], v[16:17], v[114:115] op_sel_hi:[1,0]
	v_pk_mul_f32 v[14:15], v[14:15], v[114:115] op_sel_hi:[1,0]
	v_pk_mul_f32 v[12:13], v[12:13], v[114:115] op_sel_hi:[1,0]
	v_pk_mul_f32 v[10:11], v[10:11], v[114:115] op_sel_hi:[1,0]
	v_pk_mul_f32 v[8:9], v[8:9], v[114:115] op_sel_hi:[1,0]
	v_pk_mul_f32 v[6:7], v[6:7], v[114:115] op_sel_hi:[1,0]
	v_pk_mul_f32 v[4:5], v[4:5], v[114:115] op_sel_hi:[1,0]
	v_pk_mul_f32 v[2:3], v[2:3], v[114:115] op_sel_hi:[1,0]
.LBB0_165:
	v_add_f32_e32 v131, v157, v158
	v_add_f32_e32 v131, 0, v131
	v_add_f32_e32 v132, v159, v160
	v_add_f32_e32 v131, v132, v131
	v_add_f32_e32 v132, v161, v162
	v_add_f32_e32 v131, v132, v131
	v_add_f32_e32 v132, v163, v164
	v_add_f32_e32 v131, v132, v131
	v_add_f32_e32 v132, v165, v166
	v_add_f32_e32 v131, v132, v131
	v_add_f32_e32 v132, v167, v168
	v_add_f32_e32 v131, v132, v131
	v_add_f32_e32 v132, v169, v170
	v_add_f32_e32 v131, v132, v131
	v_add_f32_e32 v132, v171, v172
	v_add_f32_e32 v131, v132, v131
	v_add_f32_e32 v132, v173, v174
	v_add_f32_e32 v131, v132, v131
	v_add_f32_e32 v132, v175, v176
	v_add_f32_e32 v131, v132, v131
	v_add_f32_e32 v132, v177, v178
	v_add_f32_e32 v131, v132, v131
	v_add_f32_e32 v132, v179, v180
	v_add_f32_e32 v131, v132, v131
	v_add_f32_e32 v132, v181, v182
	v_add_f32_e32 v131, v132, v131
	v_add_f32_e32 v132, v183, v184
	v_add_f32_e32 v131, v132, v131
	v_add_f32_e32 v132, v185, v186
	v_add_f32_e32 v131, v132, v131
	v_add_f32_e32 v132, v187, v189
	v_add_f32_e32 v131, v132, v131
	v_add_f32_e32 v132, v195, v202
	v_add_f32_e32 v132, 0, v132
	v_add_f32_e32 v133, v203, v204
	v_add_f32_e32 v132, v133, v132
	v_add_f32_e32 v133, v205, v206
	v_add_f32_e32 v132, v133, v132
	v_add_f32_e32 v133, v207, v208
	v_add_f32_e32 v132, v133, v132
	v_add_f32_e32 v133, v209, v220
	v_add_f32_e32 v132, v133, v132
	v_add_f32_e32 v133, v221, v222
	v_add_f32_e32 v132, v133, v132
	v_add_f32_e32 v133, v223, v224
	v_add_f32_e32 v132, v133, v132
	v_add_f32_e32 v133, v225, v226
	v_add_f32_e32 v132, v133, v132
	v_add_f32_e32 v133, v227, v228
	v_add_f32_e32 v132, v133, v132
	v_add_f32_e32 v133, v229, v230
	v_add_f32_e32 v132, v133, v132
	v_add_f32_e32 v133, v231, v232
	v_add_f32_e32 v132, v133, v132
	v_add_f32_e32 v133, v233, v234
	v_add_f32_e32 v132, v133, v132
	v_add_f32_e32 v133, v235, v236
	v_add_f32_e32 v132, v133, v132
	v_add_f32_e32 v133, v237, v238
	v_add_f32_e32 v132, v133, v132
	v_add_f32_e32 v133, v239, v240
	v_add_f32_e32 v132, v133, v132
	v_add_f32_e32 v133, v241, v242
	v_add_f32_e32 v131, v188, v131
	v_add_f32_e32 v132, v133, v132
	v_fmac_f32_e32 v132, v131, v0
	v_add_f32_e32 v0, v147, v148
	v_add_f32_e32 v0, 0, v0
	v_add_f32_e32 v115, v115, v149
	v_add_f32_e32 v0, v115, v0
	v_add_f32_e32 v115, v150, v151
	v_add_f32_e32 v0, v115, v0
	v_add_f32_e32 v115, v152, v153
	v_add_f32_e32 v0, v115, v0
	v_add_f32_e32 v115, v118, v190
	v_add_f32_e32 v0, v115, v0
	v_add_f32_e32 v115, v119, v192
	v_add_f32_e32 v0, v115, v0
	v_add_f32_e32 v115, v120, v193
	v_add_f32_e32 v0, v115, v0
	v_add_f32_e32 v115, v121, v194
	v_add_f32_e32 v0, v115, v0
	v_add_f32_e32 v115, v122, v243
	v_add_f32_e32 v0, v115, v0
	v_add_f32_e32 v115, v123, v244
	v_add_f32_e32 v0, v115, v0
	v_add_f32_e32 v115, v124, v245
	v_add_f32_e32 v0, v115, v0
	v_add_f32_e32 v115, v125, v246
	v_add_f32_e32 v0, v115, v0
	v_add_f32_e32 v115, v126, v247
	v_sub_f32_e32 v68, v68, v130
	v_add_f32_e32 v0, v115, v0
	v_add_f32_e32 v115, v127, v248
	v_exp_f32_e32 v119, v68
	v_sub_f32_e32 v68, v85, v130
	v_add_f32_e32 v0, v115, v0
	v_add_f32_e32 v115, v128, v249
	v_exp_f32_e32 v85, v68
	v_sub_f32_e32 v68, v69, v130
	v_add_f32_e32 v0, v115, v0
	v_add_f32_e32 v115, v129, v250
	v_sub_f32_e32 v66, v66, v130
	v_exp_f32_e32 v120, v68
	v_sub_f32_e32 v68, v86, v130
	v_add_f32_e32 v0, v115, v0
	v_sub_f32_e32 v82, v82, v130
	v_exp_f32_e32 v115, v66
	v_sub_f32_e32 v66, v83, v130
	v_exp_f32_e32 v86, v68
	v_sub_f32_e32 v68, v70, v130
	v_exp_f32_e32 v82, v82
	v_exp_f32_e32 v83, v66
	v_sub_f32_e32 v66, v67, v130
	v_exp_f32_e32 v121, v68
	v_sub_f32_e32 v68, v87, v130
	v_exp_f32_e32 v118, v66
	v_sub_f32_e32 v84, v84, v130
	v_exp_f32_e32 v87, v68
	v_sub_f32_e32 v68, v71, v130
	v_exp_f32_e32 v84, v84
	v_exp_f32_e32 v122, v68
	v_sub_f32_e32 v68, v88, v130
	v_exp_f32_e32 v88, v68
	v_sub_f32_e32 v68, v72, v130
	v_add_f32_e32 v66, v82, v115
	v_exp_f32_e32 v123, v68
	v_sub_f32_e32 v68, v89, v130
	v_add_f32_e32 v66, 0, v66
	v_add_f32_e32 v67, v83, v118
	v_exp_f32_e32 v89, v68
	v_sub_f32_e32 v68, v73, v130
	v_add_f32_e32 v66, v67, v66
	v_add_f32_e32 v67, v84, v119
	v_exp_f32_e32 v73, v68
	v_sub_f32_e32 v68, v90, v130
	v_add_f32_e32 v66, v67, v66
	v_add_f32_e32 v67, v85, v120
	v_exp_f32_e32 v90, v68
	v_sub_f32_e32 v68, v74, v130
	v_sub_f32_e32 v69, v91, v130
	v_add_f32_e32 v66, v67, v66
	v_add_f32_e32 v67, v86, v121
	v_exp_f32_e32 v68, v68
	v_exp_f32_e32 v74, v69
	v_sub_f32_e32 v69, v75, v130
	v_sub_f32_e32 v70, v92, v130
	v_add_f32_e32 v66, v67, v66
	v_add_f32_e32 v67, v87, v122
	v_exp_f32_e32 v69, v69
	v_exp_f32_e32 v75, v70
	v_sub_f32_e32 v70, v76, v130
	v_sub_f32_e32 v71, v93, v130
	v_add_f32_e32 v66, v67, v66
	v_add_f32_e32 v67, v88, v123
	v_exp_f32_e32 v70, v70
	v_exp_f32_e32 v76, v71
	v_sub_f32_e32 v71, v77, v130
	v_sub_f32_e32 v72, v94, v130
	v_add_f32_e32 v66, v67, v66
	v_add_f32_e32 v67, v89, v73
	v_exp_f32_e32 v71, v71
	v_exp_f32_e32 v77, v72
	v_sub_f32_e32 v72, v78, v130
	v_add_f32_e32 v66, v67, v66
	v_add_f32_e32 v67, v90, v68
	v_exp_f32_e32 v72, v72
	v_sub_f32_e32 v78, v95, v130
	v_sub_f32_e32 v79, v79, v130
	v_add_f32_e32 v66, v67, v66
	v_add_f32_e32 v67, v74, v69
	v_exp_f32_e32 v78, v78
	v_exp_f32_e32 v79, v79
	v_sub_f32_e32 v91, v96, v130
	v_sub_f32_e32 v80, v80, v130
	v_add_f32_e32 v66, v67, v66
	v_add_f32_e32 v67, v75, v70
	v_exp_f32_e32 v91, v91
	v_exp_f32_e32 v80, v80
	v_sub_f32_e32 v92, v97, v130
	v_sub_f32_e32 v81, v81, v130
	v_add_f32_e32 v66, v67, v66
	v_add_f32_e32 v67, v76, v71
	v_exp_f32_e32 v92, v92
	v_exp_f32_e32 v81, v81
	v_add_f32_e32 v66, v67, v66
	v_add_f32_e32 v67, v77, v72
	v_add_f32_e32 v66, v67, v66
	v_add_f32_e32 v67, v78, v79
	v_add_f32_e32 v66, v67, v66
	v_add_f32_e32 v67, v91, v80
	v_add_f32_e32 v66, v67, v66
	v_add_f32_e32 v67, v92, v81
	v_fmac_f32_e32 v0, v132, v146
	v_add_f32_e32 v124, v67, v66
	v_lshlrev_b64 v[116:117], 10, v[154:155]
	v_fmac_f32_e32 v124, v0, v114
	v_cvt_pk_bf16_f32 v66, v68, v69
	v_cvt_pk_bf16_f32 v67, v70, v71
	v_cvt_pk_bf16_f32 v68, v72, v79
	v_cvt_pk_bf16_f32 v69, v80, v81
	v_cvt_pk_bf16_f32 v70, v115, v118
	v_cvt_pk_bf16_f32 v71, v119, v120
	v_cvt_pk_bf16_f32 v72, v121, v122
	v_cvt_pk_bf16_f32 v73, v123, v73
	v_cvt_pk_bf16_f32 v74, v90, v74
	v_cvt_pk_bf16_f32 v75, v75, v76
	v_cvt_pk_bf16_f32 v76, v77, v78
	v_cvt_pk_bf16_f32 v77, v91, v92
	v_cvt_pk_bf16_f32 v78, v82, v83
	v_cvt_pk_bf16_f32 v79, v84, v85
	v_cvt_pk_bf16_f32 v80, v86, v87
	v_cvt_pk_bf16_f32 v81, v88, v89
	s_waitcnt lgkmcnt(3)
	s_nop 0
	v_mfma_f32_32x32x16_bf16 v[50:65], v[110:113], v[78:81], v[50:65]
	ds_read_b128 v[82:85], v191 offset:43744
	ds_read_b128 v[86:89], v191 offset:43712
	ds_read_b128 v[90:93], v191 offset:43648
	ds_read_b128 v[94:97], v191 offset:43680
	s_waitcnt lgkmcnt(6)
	v_mfma_f32_32x32x16_bf16 v[50:65], v[106:109], v[74:77], v[50:65]
	s_waitcnt lgkmcnt(5)
	v_mfma_f32_32x32x16_bf16 v[50:65], v[98:101], v[70:73], v[50:65]
	s_waitcnt lgkmcnt(4)
	v_mfma_f32_32x32x16_bf16 v[50:65], v[102:105], v[66:69], v[50:65]
	s_waitcnt lgkmcnt(1)
	v_mfma_f32_32x32x16_bf16 v[34:49], v[90:93], v[78:81], v[34:49]
	s_waitcnt lgkmcnt(0)
	v_mfma_f32_32x32x16_bf16 v[34:49], v[94:97], v[74:77], v[34:49]
	v_mfma_f32_32x32x16_bf16 v[34:49], v[86:89], v[70:73], v[34:49]
	v_mfma_f32_32x32x16_bf16 v[34:49], v[82:85], v[66:69], v[34:49]
	ds_read_b128 v[82:85], v191 offset:52448
	ds_read_b128 v[86:89], v191 offset:52416
	ds_read_b128 v[90:93], v191 offset:52352
	ds_read_b128 v[94:97], v191 offset:52384
	s_waitcnt lgkmcnt(1)
	v_mfma_f32_32x32x16_bf16 v[18:33], v[90:93], v[78:81], v[18:33]
	s_waitcnt lgkmcnt(0)
	v_mfma_f32_32x32x16_bf16 v[18:33], v[94:97], v[74:77], v[18:33]
	v_mfma_f32_32x32x16_bf16 v[18:33], v[86:89], v[70:73], v[18:33]
	v_mfma_f32_32x32x16_bf16 v[18:33], v[82:85], v[66:69], v[18:33]
	ds_read_b128 v[82:85], v191 offset:61152
	ds_read_b128 v[86:89], v191 offset:61120
	ds_read_b128 v[90:93], v191 offset:61056
	ds_read_b128 v[94:97], v191 offset:61088
	s_waitcnt lgkmcnt(1)
	v_mfma_f32_32x32x16_bf16 v[2:17], v[90:93], v[78:81], v[2:17]
	s_waitcnt lgkmcnt(0)
	v_mfma_f32_32x32x16_bf16 v[2:17], v[94:97], v[74:77], v[2:17]
	v_mfma_f32_32x32x16_bf16 v[2:17], v[86:89], v[70:73], v[2:17]
	v_mfma_f32_32x32x16_bf16 v[2:17], v[82:85], v[66:69], v[2:17]
	v_mov_b32_e32 v0, v124
	s_barrier
	v_nop
	v_nop
	v_permlane32_swap_b32 v124, v0
	s_nop 0
	v_add_f32_e32 v0, v124, v0
	v_div_scale_f32 v66, s[28:29], v0, v0, 1.0
	v_rcp_f32_e32 v67, v66
	s_mov_b32 s28, 0x3e38aa3b
	v_fma_f32 v68, -v66, v67, 1.0
	v_fmac_f32_e32 v67, v68, v67
	v_div_scale_f32 v68, vcc, 1.0, v0, 1.0
	v_mul_f32_e32 v69, v68, v67
	v_fma_f32 v70, -v66, v69, v68
	v_fmac_f32_e32 v69, v70, v67
	v_fma_f32 v66, -v66, v69, v68
	v_div_fmas_f32 v66, v66, v67, v69
	v_div_fixup_f32 v66, v66, v0, 1.0
	v_lshl_add_u64 v[68:69], v[116:117], 1, s[18:19]
	v_lshl_add_u64 v[68:69], v[68:69], 0, s[80:81]
	v_lshlrev_b32_e32 v0, 3, v156
	v_pk_mul_f32 v[2:3], v[2:3], v[66:67] op_sel_hi:[1,0]
	v_pk_mul_f32 v[4:5], v[4:5], v[66:67] op_sel_hi:[1,0]
	v_lshl_add_u64 v[68:69], v[68:69], 0, v[0:1]
	v_pk_mul_f32 v[50:51], v[50:51], v[66:67] op_sel_hi:[1,0]
	v_pk_mul_f32 v[52:53], v[52:53], v[66:67] op_sel_hi:[1,0]
	v_pk_mul_f32 v[34:35], v[34:35], v[66:67] op_sel_hi:[1,0]
	v_pk_mul_f32 v[36:37], v[36:37], v[66:67] op_sel_hi:[1,0]
	v_pk_mul_f32 v[18:19], v[18:19], v[66:67] op_sel_hi:[1,0]
	v_pk_mul_f32 v[20:21], v[20:21], v[66:67] op_sel_hi:[1,0]
	v_cvt_pk_bf16_f32 v2, v2, v3
	v_cvt_pk_bf16_f32 v3, v4, v5
	v_cvt_pk_bf16_f32 v50, v50, v51
	v_cvt_pk_bf16_f32 v51, v52, v53
	v_cvt_pk_bf16_f32 v34, v34, v35
	v_cvt_pk_bf16_f32 v35, v36, v37
	v_cvt_pk_bf16_f32 v18, v18, v19
	v_cvt_pk_bf16_f32 v19, v20, v21
	global_store_dwordx2 v[68:69], v[2:3], off offset:192
	v_pk_mul_f32 v[2:3], v[6:7], v[66:67] op_sel_hi:[1,0]
	v_pk_mul_f32 v[4:5], v[8:9], v[66:67] op_sel_hi:[1,0]
	global_store_dwordx2 v[68:69], v[50:51], off
	v_pk_mul_f32 v[50:51], v[54:55], v[66:67] op_sel_hi:[1,0]
	v_pk_mul_f32 v[52:53], v[56:57], v[66:67] op_sel_hi:[1,0]
	global_store_dwordx2 v[68:69], v[34:35], off offset:64
	v_pk_mul_f32 v[34:35], v[38:39], v[66:67] op_sel_hi:[1,0]
	v_pk_mul_f32 v[36:37], v[40:41], v[66:67] op_sel_hi:[1,0]
	global_store_dwordx2 v[68:69], v[18:19], off offset:128
	v_pk_mul_f32 v[18:19], v[22:23], v[66:67] op_sel_hi:[1,0]
	v_pk_mul_f32 v[20:21], v[24:25], v[66:67] op_sel_hi:[1,0]
	v_cvt_pk_bf16_f32 v2, v2, v3
	v_cvt_pk_bf16_f32 v3, v4, v5
	v_cvt_pk_bf16_f32 v50, v50, v51
	v_cvt_pk_bf16_f32 v51, v52, v53
	v_cvt_pk_bf16_f32 v34, v34, v35
	v_cvt_pk_bf16_f32 v35, v36, v37
	v_cvt_pk_bf16_f32 v18, v18, v19
	v_cvt_pk_bf16_f32 v19, v20, v21
	global_store_dwordx2 v[68:69], v[2:3], off offset:208
	v_pk_mul_f32 v[2:3], v[10:11], v[66:67] op_sel_hi:[1,0]
	v_pk_mul_f32 v[4:5], v[12:13], v[66:67] op_sel_hi:[1,0]
	global_store_dwordx2 v[68:69], v[50:51], off offset:16
	v_pk_mul_f32 v[50:51], v[58:59], v[66:67] op_sel_hi:[1,0]
	v_pk_mul_f32 v[52:53], v[60:61], v[66:67] op_sel_hi:[1,0]
	global_store_dwordx2 v[68:69], v[34:35], off offset:80
	v_pk_mul_f32 v[34:35], v[42:43], v[66:67] op_sel_hi:[1,0]
	v_pk_mul_f32 v[36:37], v[44:45], v[66:67] op_sel_hi:[1,0]
	global_store_dwordx2 v[68:69], v[18:19], off offset:144
	v_pk_mul_f32 v[18:19], v[26:27], v[66:67] op_sel_hi:[1,0]
	v_pk_mul_f32 v[20:21], v[28:29], v[66:67] op_sel_hi:[1,0]
	v_cvt_pk_bf16_f32 v2, v2, v3
	v_cvt_pk_bf16_f32 v3, v4, v5
	v_cvt_pk_bf16_f32 v50, v50, v51
	v_cvt_pk_bf16_f32 v51, v52, v53
	v_cvt_pk_bf16_f32 v34, v34, v35
	v_cvt_pk_bf16_f32 v35, v36, v37
	v_cvt_pk_bf16_f32 v18, v18, v19
	v_cvt_pk_bf16_f32 v19, v20, v21
	global_store_dwordx2 v[68:69], v[2:3], off offset:224
	v_pk_mul_f32 v[2:3], v[14:15], v[66:67] op_sel_hi:[1,0]
	v_pk_mul_f32 v[4:5], v[16:17], v[66:67] op_sel_hi:[1,0]
	global_store_dwordx2 v[68:69], v[50:51], off offset:32
	v_pk_mul_f32 v[50:51], v[62:63], v[66:67] op_sel_hi:[1,0]
	v_pk_mul_f32 v[52:53], v[64:65], v[66:67] op_sel_hi:[1,0]
	global_store_dwordx2 v[68:69], v[34:35], off offset:96
	v_pk_mul_f32 v[34:35], v[46:47], v[66:67] op_sel_hi:[1,0]
	v_pk_mul_f32 v[36:37], v[48:49], v[66:67] op_sel_hi:[1,0]
	global_store_dwordx2 v[68:69], v[18:19], off offset:160
	v_pk_mul_f32 v[18:19], v[30:31], v[66:67] op_sel_hi:[1,0]
	v_pk_mul_f32 v[20:21], v[32:33], v[66:67] op_sel_hi:[1,0]
	v_cvt_pk_bf16_f32 v2, v2, v3
	v_cvt_pk_bf16_f32 v3, v4, v5
	v_cvt_pk_bf16_f32 v50, v50, v51
	v_cvt_pk_bf16_f32 v51, v52, v53
	v_cvt_pk_bf16_f32 v34, v34, v35
	v_cvt_pk_bf16_f32 v35, v36, v37
	v_cvt_pk_bf16_f32 v18, v18, v19
	v_cvt_pk_bf16_f32 v19, v20, v21
	global_store_dwordx2 v[68:69], v[2:3], off offset:240
	v_mov_b32_e32 v3, v197
	global_store_dwordx2 v[68:69], v[50:51], off offset:48
	global_store_dwordx2 v[68:69], v[34:35], off offset:112
	global_store_dwordx2 v[68:69], v[18:19], off offset:176
	s_nop 0
	v_and_b32_e32 v2, 31, v3
	v_ashrrev_i32_e32 v0, 1, v3
	v_and_b32_e32 v0, 0xffffffe0, v0
	v_or_b32_e32 v4, s2, v2
	v_add_u32_e32 v156, v4, v0
	v_ashrrev_i32_e32 v157, 31, v156
	v_lshlrev_b64 v[154:155], 11, v[156:157]
	v_bfe_u32 v159, v3, 5, 1
	v_lshl_add_u64 v[4:5], s[48:49], 0, v[154:155]
	v_lshl_add_u64 v[4:5], v[4:5], 0, s[80:81]
	v_lshlrev_b32_e32 v0, 4, v159
	v_lshl_add_u64 v[16:17], v[4:5], 0, v[0:1]
	global_load_dwordx4 v[4:7], v[16:17], off offset:128
	global_load_dwordx4 v[8:11], v[16:17], off offset:160
	global_load_dwordx4 v[12:15], v[16:17], off offset:192
	s_nop 0
	global_load_dwordx4 v[16:19], v[16:17], off offset:224
	s_waitcnt vmcnt(3)
	v_and_b32_e32 v21, 0xffff0000, v4
	v_lshlrev_b32_e32 v20, 16, v4
	v_pk_mul_f32 v[20:21], v[20:21], s[28:29] op_sel_hi:[1,0]
	s_nop 0
	v_cvt_pk_bf16_f32 v130, v20, v21
	v_and_b32_e32 v21, 0xffff0000, v5
	v_lshlrev_b32_e32 v20, 16, v5
	v_pk_mul_f32 v[4:5], v[20:21], s[28:29] op_sel_hi:[1,0]
	s_nop 0
	v_cvt_pk_bf16_f32 v131, v4, v5
	v_and_b32_e32 v5, 0xffff0000, v6
	v_lshlrev_b32_e32 v4, 16, v6
	v_pk_mul_f32 v[4:5], v[4:5], s[28:29] op_sel_hi:[1,0]
	s_nop 0
	v_cvt_pk_bf16_f32 v132, v4, v5
	v_and_b32_e32 v5, 0xffff0000, v7
	v_lshlrev_b32_e32 v4, 16, v7
	v_pk_mul_f32 v[4:5], v[4:5], s[28:29] op_sel_hi:[1,0]
	v_ashrrev_i32_e32 v7, 3, v3
	v_cvt_pk_bf16_f32 v133, v4, v5
	s_waitcnt vmcnt(2)
	v_and_b32_e32 v5, 0xffff0000, v8
	v_lshlrev_b32_e32 v4, 16, v8
	v_pk_mul_f32 v[4:5], v[4:5], s[28:29] op_sel_hi:[1,0]
	v_ashrrev_i32_e32 v8, 4, v3
	v_cvt_pk_bf16_f32 v134, v4, v5
	v_and_b32_e32 v5, 0xffff0000, v9
	v_lshlrev_b32_e32 v4, 16, v9
	v_pk_mul_f32 v[4:5], v[4:5], s[28:29] op_sel_hi:[1,0]
	v_add_u32_e32 v9, s21, v8
	v_cvt_pk_bf16_f32 v135, v4, v5
	v_and_b32_e32 v5, 0xffff0000, v10
	v_lshlrev_b32_e32 v4, 16, v10
	v_pk_mul_f32 v[4:5], v[4:5], s[28:29] op_sel_hi:[1,0]
	v_and_b32_e32 v10, 15, v3
	v_cvt_pk_bf16_f32 v136, v4, v5
	v_and_b32_e32 v5, 0xffff0000, v11
	v_lshlrev_b32_e32 v4, 16, v11
	v_pk_mul_f32 v[4:5], v[4:5], s[28:29] op_sel_hi:[1,0]
	v_lshlrev_b32_e32 v11, 4, v3
	v_cvt_pk_bf16_f32 v137, v4, v5
	s_waitcnt vmcnt(1)
	v_and_b32_e32 v5, 0xffff0000, v12
	v_lshlrev_b32_e32 v4, 16, v12
	v_pk_mul_f32 v[4:5], v[4:5], s[28:29] op_sel_hi:[1,0]
	v_and_b32_e32 v6, 0x70, v11
	v_cvt_pk_bf16_f32 v138, v4, v5
	v_and_b32_e32 v5, 0xffff0000, v13
	v_lshlrev_b32_e32 v4, 16, v13
	v_pk_mul_f32 v[4:5], v[4:5], s[28:29] op_sel_hi:[1,0]
	v_mul_lo_u32 v40, v8, s43
	v_cvt_pk_bf16_f32 v139, v4, v5
	v_and_b32_e32 v5, 0xffff0000, v14
	v_lshlrev_b32_e32 v4, 16, v14
	v_pk_mul_f32 v[4:5], v[4:5], s[28:29] op_sel_hi:[1,0]
	v_lshlrev_b32_e32 v3, 3, v3
	v_cvt_pk_bf16_f32 v140, v4, v5
	v_and_b32_e32 v5, 0xffff0000, v15
	v_lshlrev_b32_e32 v4, 16, v15
	v_pk_mul_f32 v[4:5], v[4:5], s[28:29] op_sel_hi:[1,0]
	v_and_b32_e32 v3, 8, v3
	v_cvt_pk_bf16_f32 v141, v4, v5
	s_waitcnt vmcnt(0)
	v_and_b32_e32 v5, 0xffff0000, v16
	v_lshlrev_b32_e32 v4, 16, v16
	v_pk_mul_f32 v[4:5], v[4:5], s[28:29] op_sel_hi:[1,0]
	s_nop 0
	v_cvt_pk_bf16_f32 v142, v4, v5
	v_and_b32_e32 v5, 0xffff0000, v17
	v_lshlrev_b32_e32 v4, 16, v17
	v_pk_mul_f32 v[4:5], v[4:5], s[28:29] op_sel_hi:[1,0]
	s_nop 0
	v_cvt_pk_bf16_f32 v143, v4, v5
	v_and_b32_e32 v5, 0xffff0000, v18
	v_lshlrev_b32_e32 v4, 16, v18
	v_pk_mul_f32 v[4:5], v[4:5], s[28:29] op_sel_hi:[1,0]
	s_nop 0
	v_cvt_pk_bf16_f32 v144, v4, v5
	v_and_b32_e32 v5, 0xffff0000, v19
	v_lshlrev_b32_e32 v4, 16, v19
	v_pk_mul_f32 v[4:5], v[4:5], s[28:29] op_sel_hi:[1,0]
	v_mad_u64_u32 v[28:29], s[28:29], v7, s42, v[6:7]
	v_cvt_pk_bf16_f32 v145, v4, v5
	v_add_u32_e32 v4, s2, v7
	v_ashrrev_i32_e32 v5, 31, v4
	v_lshlrev_b64 v[4:5], 11, v[4:5]
	v_lshl_add_u64 v[4:5], s[8:9], 0, v[4:5]
	v_lshl_add_u64 v[4:5], v[4:5], 0, s[80:81]
	v_mov_b32_e32 v7, v1
	v_lshl_add_u64 v[30:31], v[4:5], 0, v[6:7]
	v_mov_b64_e32 v[4:5], s[10:11]
	v_mad_i64_i32 v[4:5], s[28:29], v9, s68, v[4:5]
	v_lshl_add_u64 v[4:5], s[2:3], 1, v[4:5]
	s_mov_b32 s2, 0x20000
	v_lshlrev_b32_e32 v6, 4, v10
	v_add_co_u32_e32 v8, vcc, s2, v30
	v_lshl_add_u64 v[32:33], v[4:5], 0, v[6:7]
	s_nop 0
	v_addc_co_u32_e32 v9, vcc, 0, v31, vcc
	v_add_co_u32_e32 v34, vcc, s41, v32
	s_mov_b32 s2, 0x220000
	s_nop 0
	v_addc_co_u32_e32 v35, vcc, 0, v33, vcc
	global_load_dwordx4 v[4:7], v[30:31], off offset:128
	v_add_co_u32_e32 v36, vcc, s2, v32
	v_and_b32_e32 v29, 0xe0, v11
	global_load_dwordx4 v[8:11], v[8:9], off offset:128
	s_nop 0
	global_load_dwordx4 v[12:15], v[32:33], off
	v_addc_co_u32_e32 v37, vcc, 0, v33, vcc
	s_mov_b32 s2, 0x330000
	v_add_co_u32_e32 v38, vcc, s2, v32
	global_load_dwordx4 v[16:19], v[34:35], off
	global_load_dwordx4 v[20:23], v[36:37], off
	v_addc_co_u32_e32 v39, vcc, 0, v33, vcc
	global_load_dwordx4 v[24:27], v[38:39], off
	v_add_u32_e32 v202, 0, v28
	s_waitcnt vmcnt(5)
	ds_write_b128 v202, v[4:7]
	s_waitcnt vmcnt(4)
	ds_write_b128 v202, v[8:11] offset:9216
	v_add_u32_e32 v4, 0, v29
	v_add3_u32 v3, v4, v3, v40
	v_add_u32_e32 v4, 0xb000, v3
	v_add_u32_e32 v195, 0x9000, v3
	s_mov_b32 s2, 0x40000
	s_waitcnt vmcnt(3)
	ds_write2_b64 v195, v[12:13], v[14:15] offset1:2
	s_waitcnt vmcnt(2)
	ds_write2_b64 v4, v[16:17], v[18:19] offset0:64 offset1:66
	v_add_u32_e32 v4, 0xd000, v3
	v_add_u32_e32 v3, 0xf000, v3
	s_waitcnt vmcnt(1)
	ds_write2_b64 v4, v[20:21], v[22:23] offset0:128 offset1:130
	s_waitcnt vmcnt(0)
	ds_write2_b64 v3, v[24:25], v[26:27] offset0:192 offset1:194
	v_mad_u32_u24 v3, v2, s42, 0
	v_add_u32_e32 v194, v3, v0
	v_lshl_add_u32 v203, v2, 7, v194
	v_add_co_u32_e32 v2, vcc, s2, v30
	s_mov_b32 s2, 0x60000
	s_nop 0
	v_addc_co_u32_e32 v3, vcc, 0, v31, vcc
	s_waitcnt lgkmcnt(0)
	s_barrier
	global_load_dwordx4 v[106:109], v[2:3], off offset:128
	v_add_co_u32_e32 v2, vcc, s2, v30
	s_nop 1
	v_addc_co_u32_e32 v3, vcc, 0, v31, vcc
	global_load_dwordx4 v[118:121], v[2:3], off offset:128
	global_load_dwordx4 v[114:117], v[32:33], off offset:256
	global_load_dwordx4 v[110:113], v[34:35], off offset:256
	global_load_dwordx4 v[102:105], v[36:37], off offset:256
	global_load_dwordx4 v[98:101], v[38:39], off offset:256
	ds_read_b128 v[2:5], v194 offset:4608
	ds_read_b128 v[6:9], v194
	ds_read_b128 v[34:37], v194 offset:32
	ds_read_b128 v[38:41], v194 offset:4640
	ds_read_b128 v[42:45], v194 offset:64
	ds_read_b128 v[46:49], v194 offset:4672
	ds_read_b128 v[50:53], v194 offset:96
	ds_read_b128 v[54:57], v194 offset:4704
	s_waitcnt lgkmcnt(6)
	v_mfma_f32_32x32x16_bf16 v[18:33], v[6:9], v[130:133], 0
	v_mfma_f32_32x32x16_bf16 v[2:17], v[2:5], v[130:133], 0
	s_waitcnt lgkmcnt(5)
	v_mfma_f32_32x32x16_bf16 v[18:33], v[34:37], v[134:137], v[18:33]
	s_waitcnt lgkmcnt(4)
	v_mfma_f32_32x32x16_bf16 v[2:17], v[38:41], v[134:137], v[2:17]
	s_waitcnt lgkmcnt(3)
	v_mfma_f32_32x32x16_bf16 v[18:33], v[42:45], v[138:141], v[18:33]
	s_waitcnt lgkmcnt(2)
	v_mfma_f32_32x32x16_bf16 v[2:17], v[46:49], v[138:141], v[2:17]
	s_waitcnt lgkmcnt(1)
	v_mfma_f32_32x32x16_bf16 v[18:33], v[50:53], v[142:145], v[18:33]
	s_waitcnt lgkmcnt(0)
	v_mfma_f32_32x32x16_bf16 v[2:17], v[54:57], v[142:145], v[2:17]
	ds_read_b128 v[34:37], v194 offset:9216
	ds_read_b128 v[38:41], v194 offset:9248
	ds_read_b128 v[42:45], v194 offset:13824
	ds_read_b128 v[46:49], v194 offset:13856
	ds_read_b128 v[50:53], v194 offset:9280
	ds_read_b128 v[54:57], v194 offset:9312
	ds_read_b128 v[58:61], v194 offset:13888
	ds_read_b128 v[62:65], v194 offset:13920
	s_waitcnt lgkmcnt(7)
	v_mfma_f32_32x32x16_bf16 v[82:97], v[34:37], v[130:133], 0
	s_waitcnt lgkmcnt(5)
	v_mfma_f32_32x32x16_bf16 v[66:81], v[42:45], v[130:133], 0
	v_mfma_f32_32x32x16_bf16 v[82:97], v[38:41], v[134:137], v[82:97]
	s_waitcnt lgkmcnt(4)
	v_mfma_f32_32x32x16_bf16 v[66:81], v[46:49], v[134:137], v[66:81]
	s_waitcnt lgkmcnt(3)
	v_mfma_f32_32x32x16_bf16 v[82:97], v[50:53], v[138:141], v[82:97]
	s_waitcnt lgkmcnt(1)
	v_mfma_f32_32x32x16_bf16 v[66:81], v[58:61], v[138:141], v[66:81]
	v_mfma_f32_32x32x16_bf16 v[82:97], v[54:57], v[142:145], v[82:97]
	s_waitcnt lgkmcnt(0)
	v_mfma_f32_32x32x16_bf16 v[66:81], v[62:65], v[142:145], v[66:81]
	ds_read_b128 v[34:37], v203 offset:36864
	ds_read_b128 v[38:41], v203 offset:36896
	ds_read_b128 v[42:45], v203 offset:36928
	ds_read_b128 v[46:49], v203 offset:36960
	v_max3_f32 v50, v18, v2, v19
	v_max_f32_e32 v51, v17, v17
	v_max3_f32 v50, v50, v3, v20
	s_mov_b32 s2, 0xf149f2ca
	v_max3_f32 v50, v50, v4, v21
	v_max3_f32 v50, v50, v5, v22
	v_max3_f32 v50, v50, v6, v23
	v_max3_f32 v50, v50, v7, v24
	v_max3_f32 v50, v50, v8, v25
	v_max3_f32 v50, v50, v9, v26
	v_max3_f32 v50, v50, v10, v27
	v_max3_f32 v50, v50, v11, v28
	v_max3_f32 v50, v50, v12, v29
	v_max3_f32 v50, v50, v13, v30
	v_max3_f32 v50, v50, v14, v31
	v_max3_f32 v50, v50, v15, v32
	v_max3_f32 v50, v50, v16, v33
	s_nop 0
	v_max_f32_e32 v50, v50, v50
	v_max_f32_e32 v50, v50, v51
	v_mov_b32_e32 v51, v50
	v_nop
	v_nop
	v_permlane32_swap_b32 v50, v51
	s_nop 0
	v_max3_f32 v158, v50, v51, s2
	v_sub_f32_e32 v2, v2, v158
	v_exp_f32_e32 v161, v2
	v_sub_f32_e32 v2, v19, v158
	v_exp_f32_e32 v162, v2
	v_sub_f32_e32 v2, v3, v158
	v_exp_f32_e32 v163, v2
	v_sub_f32_e32 v2, v20, v158
	v_exp_f32_e32 v164, v2
	v_sub_f32_e32 v2, v4, v158
	v_exp_f32_e32 v165, v2
	v_sub_f32_e32 v2, v21, v158
	v_exp_f32_e32 v166, v2
	v_sub_f32_e32 v2, v5, v158
	v_exp_f32_e32 v167, v2
	v_sub_f32_e32 v2, v22, v158
	v_exp_f32_e32 v168, v2
	v_sub_f32_e32 v2, v6, v158
	v_exp_f32_e32 v169, v2
	v_sub_f32_e32 v2, v23, v158
	v_exp_f32_e32 v170, v2
	v_sub_f32_e32 v2, v7, v158
	v_exp_f32_e32 v171, v2
	v_sub_f32_e32 v2, v24, v158
	v_exp_f32_e32 v172, v2
	v_sub_f32_e32 v2, v8, v158
	v_exp_f32_e32 v173, v2
	v_sub_f32_e32 v2, v25, v158
	v_exp_f32_e32 v174, v2
	v_sub_f32_e32 v2, v9, v158
	v_exp_f32_e32 v175, v2
	v_sub_f32_e32 v2, v26, v158
	v_exp_f32_e32 v176, v2
	v_sub_f32_e32 v2, v10, v158
	v_exp_f32_e32 v177, v2
	v_sub_f32_e32 v2, v27, v158
	v_exp_f32_e32 v178, v2
	v_sub_f32_e32 v2, v11, v158
	v_exp_f32_e32 v179, v2
	v_sub_f32_e32 v2, v28, v158
	v_exp_f32_e32 v180, v2
	v_sub_f32_e32 v2, v12, v158
	v_exp_f32_e32 v181, v2
	v_sub_f32_e32 v2, v29, v158
	v_exp_f32_e32 v182, v2
	v_sub_f32_e32 v2, v13, v158
	v_exp_f32_e32 v183, v2
	v_sub_f32_e32 v2, v30, v158
	v_exp_f32_e32 v184, v2
	v_sub_f32_e32 v2, v14, v158
	v_exp_f32_e32 v185, v2
	v_sub_f32_e32 v2, v31, v158
	v_sub_f32_e32 v50, 0xf149f2ca, v158
	v_exp_f32_e32 v186, v2
	v_sub_f32_e32 v2, v15, v158
	v_exp_f32_e32 v187, v2
	v_sub_f32_e32 v2, v32, v158
	v_exp_f32_e32 v3, v50
	v_exp_f32_e32 v188, v2
	v_sub_f32_e32 v2, v16, v158
	v_exp_f32_e32 v189, v2
	v_sub_f32_e32 v2, v33, v158
	v_sub_f32_e32 v18, v18, v158
	v_exp_f32_e32 v190, v2
	v_sub_f32_e32 v2, v17, v158
	v_exp_f32_e32 v160, v18
	v_exp_f32_e32 v192, v2
	v_cmp_neq_f32_e32 vcc, 1.0, v3
	s_cmp_lg_u64 vcc, 0
	v_mul_f32_e32 v191, 0, v3
	s_cselect_b64 vcc, -1, 0
	v_cndmask_b32_e32 v18, 0, v191, vcc
	v_mov_b32_e32 v19, v18
	v_mov_b32_e32 v20, v18
	v_mov_b32_e32 v21, v18
	v_mov_b32_e32 v22, v18
	v_mov_b32_e32 v23, v18
	v_mov_b32_e32 v24, v18
	v_mov_b32_e32 v25, v18
	v_mov_b32_e32 v26, v18
	v_mov_b32_e32 v27, v18
	v_mov_b32_e32 v28, v18
	v_mov_b32_e32 v29, v18
	v_mov_b32_e32 v30, v18
	v_mov_b32_e32 v31, v18
	v_mov_b32_e32 v32, v18
	v_mov_b32_e32 v33, v18
	v_cvt_pk_bf16_f32 v122, v177, v179
	v_cvt_pk_bf16_f32 v123, v181, v183
	v_cvt_pk_bf16_f32 v124, v185, v187
	v_cvt_pk_bf16_f32 v125, v189, v192
	v_cvt_pk_bf16_f32 v126, v161, v163
	v_cvt_pk_bf16_f32 v127, v165, v167
	v_cvt_pk_bf16_f32 v128, v169, v171
	v_cvt_pk_bf16_f32 v129, v173, v175
	v_cvt_pk_bf16_f32 v146, v176, v178
	v_cvt_pk_bf16_f32 v147, v180, v182
	v_cvt_pk_bf16_f32 v148, v184, v186
	v_cvt_pk_bf16_f32 v149, v188, v190
	v_cvt_pk_bf16_f32 v150, v160, v162
	v_cvt_pk_bf16_f32 v151, v164, v166
	v_cvt_pk_bf16_f32 v152, v168, v170
	v_cvt_pk_bf16_f32 v153, v172, v174
	s_waitcnt lgkmcnt(3)
	s_nop 0
	v_mfma_f32_32x32x16_bf16 v[2:17], v[34:37], v[150:153], v[18:33]
	s_waitcnt lgkmcnt(2)
	v_mfma_f32_32x32x16_bf16 v[2:17], v[38:41], v[146:149], v[2:17]
	s_waitcnt lgkmcnt(1)
	v_mfma_f32_32x32x16_bf16 v[2:17], v[42:45], v[126:129], v[2:17]
	s_waitcnt lgkmcnt(0)
	v_mfma_f32_32x32x16_bf16 v[2:17], v[46:49], v[122:125], v[2:17]
	ds_read_b128 v[34:37], v203 offset:45664
	ds_read_b128 v[38:41], v203 offset:45632
	ds_read_b128 v[42:45], v203 offset:45568
	ds_read_b128 v[46:49], v203 offset:45600
	s_waitcnt lgkmcnt(1)
	v_mfma_f32_32x32x16_bf16 v[50:65], v[42:45], v[150:153], v[18:33]
	ds_read_b128 v[198:201], v203 offset:54368
	ds_read_b128 v[204:207], v203 offset:54336
	ds_read_b128 v[208:211], v203 offset:54272
	ds_read_b128 v[212:215], v203 offset:54304
	s_waitcnt lgkmcnt(4)
	v_mfma_f32_32x32x16_bf16 v[50:65], v[46:49], v[146:149], v[50:65]
	v_mfma_f32_32x32x16_bf16 v[50:65], v[38:41], v[126:129], v[50:65]
	v_mfma_f32_32x32x16_bf16 v[50:65], v[34:37], v[122:125], v[50:65]
	s_waitcnt lgkmcnt(1)
	v_mfma_f32_32x32x16_bf16 v[34:49], v[208:211], v[150:153], v[18:33]
	s_waitcnt lgkmcnt(0)
	v_mfma_f32_32x32x16_bf16 v[34:49], v[212:215], v[146:149], v[34:49]
	v_mfma_f32_32x32x16_bf16 v[34:49], v[204:207], v[126:129], v[34:49]
	v_mfma_f32_32x32x16_bf16 v[34:49], v[198:201], v[122:125], v[34:49]
	ds_read_b128 v[198:201], v203 offset:63072
	ds_read_b128 v[204:207], v203 offset:63040
	ds_read_b128 v[208:211], v203 offset:62976
	ds_read_b128 v[212:215], v203 offset:63008
	s_waitcnt lgkmcnt(1)
	v_mfma_f32_32x32x16_bf16 v[18:33], v[208:211], v[150:153], v[18:33]
	s_waitcnt lgkmcnt(0)
	v_mfma_f32_32x32x16_bf16 v[18:33], v[212:215], v[146:149], v[18:33]
	v_mfma_f32_32x32x16_bf16 v[18:33], v[204:207], v[126:129], v[18:33]
	v_mfma_f32_32x32x16_bf16 v[18:33], v[198:201], v[122:125], v[18:33]
	ds_read_b128 v[150:153], v203 offset:36992
	ds_read_b128 v[146:149], v203 offset:37024
	ds_read_b128 v[122:125], v203 offset:37056
	ds_read_b128 v[126:129], v203 offset:37088
	v_max3_f32 v193, v82, v66, v83
	v_max_f32_e32 v198, v81, v81
	v_max3_f32 v193, v193, v67, v84
	v_max3_f32 v193, v193, v68, v85
	v_max3_f32 v193, v193, v69, v86
	v_max3_f32 v193, v193, v70, v87
	v_max3_f32 v193, v193, v71, v88
	v_max3_f32 v193, v193, v72, v89
	v_max3_f32 v193, v193, v73, v90
	v_max3_f32 v193, v193, v74, v91
	v_max3_f32 v193, v193, v75, v92
	v_max3_f32 v193, v193, v76, v93
	v_max3_f32 v193, v193, v77, v94
	v_max3_f32 v193, v193, v78, v95
	v_max3_f32 v193, v193, v79, v96
	v_max3_f32 v193, v193, v80, v97
	s_nop 0
	v_max_f32_e32 v193, v193, v193
	v_max_f32_e32 v193, v193, v198
	v_mov_b32_e32 v198, v193
	v_nop
	v_nop
	v_permlane32_swap_b32 v193, v198
	s_nop 0
	v_max3_f32 v246, v158, v193, v198
	v_sub_f32_e32 v158, v158, v246
	v_exp_f32_e32 v158, v158
	s_nop 0
	v_cmp_neq_f32_e32 vcc, 1.0, v158
	s_cbranch_vccz .LBB0_167
	v_pk_mul_f32 v[16:17], v[16:17], v[158:159] op_sel_hi:[1,0]
	v_pk_mul_f32 v[14:15], v[14:15], v[158:159] op_sel_hi:[1,0]
	v_pk_mul_f32 v[12:13], v[12:13], v[158:159] op_sel_hi:[1,0]
	v_pk_mul_f32 v[10:11], v[10:11], v[158:159] op_sel_hi:[1,0]
	v_pk_mul_f32 v[8:9], v[8:9], v[158:159] op_sel_hi:[1,0]
	v_pk_mul_f32 v[6:7], v[6:7], v[158:159] op_sel_hi:[1,0]
	v_pk_mul_f32 v[4:5], v[4:5], v[158:159] op_sel_hi:[1,0]
	v_pk_mul_f32 v[2:3], v[2:3], v[158:159] op_sel_hi:[1,0]
	v_pk_mul_f32 v[64:65], v[64:65], v[158:159] op_sel_hi:[1,0]
	v_pk_mul_f32 v[62:63], v[62:63], v[158:159] op_sel_hi:[1,0]
	v_pk_mul_f32 v[60:61], v[60:61], v[158:159] op_sel_hi:[1,0]
	v_pk_mul_f32 v[58:59], v[58:59], v[158:159] op_sel_hi:[1,0]
	v_pk_mul_f32 v[56:57], v[56:57], v[158:159] op_sel_hi:[1,0]
	v_pk_mul_f32 v[54:55], v[54:55], v[158:159] op_sel_hi:[1,0]
	v_pk_mul_f32 v[52:53], v[52:53], v[158:159] op_sel_hi:[1,0]
	v_pk_mul_f32 v[50:51], v[50:51], v[158:159] op_sel_hi:[1,0]
	v_pk_mul_f32 v[48:49], v[48:49], v[158:159] op_sel_hi:[1,0]
	v_pk_mul_f32 v[46:47], v[46:47], v[158:159] op_sel_hi:[1,0]
	v_pk_mul_f32 v[44:45], v[44:45], v[158:159] op_sel_hi:[1,0]
	v_pk_mul_f32 v[42:43], v[42:43], v[158:159] op_sel_hi:[1,0]
	v_pk_mul_f32 v[40:41], v[40:41], v[158:159] op_sel_hi:[1,0]
	v_pk_mul_f32 v[38:39], v[38:39], v[158:159] op_sel_hi:[1,0]
	v_pk_mul_f32 v[36:37], v[36:37], v[158:159] op_sel_hi:[1,0]
	v_pk_mul_f32 v[34:35], v[34:35], v[158:159] op_sel_hi:[1,0]
	v_pk_mul_f32 v[32:33], v[32:33], v[158:159] op_sel_hi:[1,0]
	v_pk_mul_f32 v[30:31], v[30:31], v[158:159] op_sel_hi:[1,0]
	v_pk_mul_f32 v[28:29], v[28:29], v[158:159] op_sel_hi:[1,0]
	v_pk_mul_f32 v[26:27], v[26:27], v[158:159] op_sel_hi:[1,0]
	v_pk_mul_f32 v[24:25], v[24:25], v[158:159] op_sel_hi:[1,0]
	v_pk_mul_f32 v[22:23], v[22:23], v[158:159] op_sel_hi:[1,0]
	v_pk_mul_f32 v[20:21], v[20:21], v[158:159] op_sel_hi:[1,0]
	v_pk_mul_f32 v[18:19], v[18:19], v[158:159] op_sel_hi:[1,0]
.LBB0_167:
	v_sub_f32_e32 v66, v66, v246
	v_exp_f32_e32 v205, v66
	v_sub_f32_e32 v66, v83, v246
	v_exp_f32_e32 v206, v66
	v_sub_f32_e32 v66, v67, v246
	v_exp_f32_e32 v207, v66
	v_sub_f32_e32 v66, v84, v246
	v_exp_f32_e32 v208, v66
	v_sub_f32_e32 v66, v68, v246
	v_exp_f32_e32 v209, v66
	v_sub_f32_e32 v66, v85, v246
	v_exp_f32_e32 v220, v66
	v_sub_f32_e32 v66, v69, v246
	v_exp_f32_e32 v221, v66
	v_sub_f32_e32 v66, v86, v246
	v_exp_f32_e32 v222, v66
	v_sub_f32_e32 v66, v70, v246
	v_exp_f32_e32 v223, v66
	v_sub_f32_e32 v66, v87, v246
	v_exp_f32_e32 v224, v66
	v_sub_f32_e32 v66, v71, v246
	v_exp_f32_e32 v225, v66
	v_sub_f32_e32 v66, v88, v246
	v_exp_f32_e32 v226, v66
	v_sub_f32_e32 v66, v72, v246
	v_exp_f32_e32 v227, v66
	v_sub_f32_e32 v66, v89, v246
	v_exp_f32_e32 v228, v66
	v_sub_f32_e32 v66, v73, v246
	v_exp_f32_e32 v229, v66
	v_sub_f32_e32 v66, v90, v246
	v_exp_f32_e32 v230, v66
	v_sub_f32_e32 v66, v74, v246
	v_exp_f32_e32 v231, v66
	v_sub_f32_e32 v66, v91, v246
	v_exp_f32_e32 v232, v66
	v_sub_f32_e32 v66, v75, v246
	v_exp_f32_e32 v233, v66
	v_sub_f32_e32 v66, v92, v246
	v_exp_f32_e32 v234, v66
	v_sub_f32_e32 v66, v76, v246
	v_exp_f32_e32 v235, v66
	v_sub_f32_e32 v66, v93, v246
	v_exp_f32_e32 v236, v66
	v_sub_f32_e32 v66, v77, v246
	v_exp_f32_e32 v237, v66
	v_sub_f32_e32 v66, v94, v246
	v_exp_f32_e32 v238, v66
	v_sub_f32_e32 v66, v78, v246
	v_exp_f32_e32 v239, v66
	v_sub_f32_e32 v66, v95, v246
	v_exp_f32_e32 v240, v66
	v_sub_f32_e32 v66, v79, v246
	v_exp_f32_e32 v241, v66
	v_sub_f32_e32 v66, v96, v246
	v_exp_f32_e32 v242, v66
	v_sub_f32_e32 v66, v80, v246
	v_exp_f32_e32 v243, v66
	v_sub_f32_e32 v66, v97, v246
	v_sub_f32_e32 v82, v82, v246
	v_exp_f32_e32 v244, v66
	v_sub_f32_e32 v66, v81, v246
	v_exp_f32_e32 v204, v82
	v_exp_f32_e32 v245, v66
	v_add_u32_e32 v193, 0x9000, v203
	v_cvt_pk_bf16_f32 v66, v231, v233
	v_cvt_pk_bf16_f32 v67, v235, v237
	v_cvt_pk_bf16_f32 v68, v239, v241
	v_cvt_pk_bf16_f32 v69, v243, v245
	v_cvt_pk_bf16_f32 v70, v205, v207
	v_cvt_pk_bf16_f32 v71, v209, v221
	v_cvt_pk_bf16_f32 v72, v223, v225
	v_cvt_pk_bf16_f32 v73, v227, v229
	v_cvt_pk_bf16_f32 v74, v230, v232
	v_cvt_pk_bf16_f32 v75, v234, v236
	v_cvt_pk_bf16_f32 v76, v238, v240
	v_cvt_pk_bf16_f32 v77, v242, v244
	v_cvt_pk_bf16_f32 v78, v204, v206
	v_cvt_pk_bf16_f32 v79, v208, v220
	v_cvt_pk_bf16_f32 v80, v222, v224
	v_cvt_pk_bf16_f32 v81, v226, v228
	s_waitcnt lgkmcnt(3)
	s_nop 0
	v_mfma_f32_32x32x16_bf16 v[2:17], v[150:153], v[78:81], v[2:17]
	ds_read_b128 v[82:85], v203 offset:45792
	ds_read_b128 v[86:89], v203 offset:45760
	ds_read_b128 v[90:93], v203 offset:45696
	ds_read_b128 v[94:97], v203 offset:45728
	s_waitcnt lgkmcnt(6)
	v_mfma_f32_32x32x16_bf16 v[2:17], v[146:149], v[74:77], v[2:17]
	s_waitcnt lgkmcnt(5)
	v_mfma_f32_32x32x16_bf16 v[2:17], v[122:125], v[70:73], v[2:17]
	s_waitcnt lgkmcnt(4)
	v_mfma_f32_32x32x16_bf16 v[2:17], v[126:129], v[66:69], v[2:17]
	s_waitcnt lgkmcnt(1)
	v_mfma_f32_32x32x16_bf16 v[50:65], v[90:93], v[78:81], v[50:65]
	s_waitcnt lgkmcnt(0)
	v_mfma_f32_32x32x16_bf16 v[50:65], v[94:97], v[74:77], v[50:65]
	v_mfma_f32_32x32x16_bf16 v[50:65], v[86:89], v[70:73], v[50:65]
	v_mfma_f32_32x32x16_bf16 v[50:65], v[82:85], v[66:69], v[50:65]
	ds_read_b128 v[82:85], v203 offset:54496
	ds_read_b128 v[86:89], v203 offset:54464
	ds_read_b128 v[90:93], v203 offset:54400
	ds_read_b128 v[94:97], v203 offset:54432
	s_waitcnt lgkmcnt(1)
	v_mfma_f32_32x32x16_bf16 v[34:49], v[90:93], v[78:81], v[34:49]
	s_waitcnt lgkmcnt(0)
	v_mfma_f32_32x32x16_bf16 v[34:49], v[94:97], v[74:77], v[34:49]
	v_mfma_f32_32x32x16_bf16 v[34:49], v[86:89], v[70:73], v[34:49]
	v_mfma_f32_32x32x16_bf16 v[34:49], v[82:85], v[66:69], v[34:49]
	ds_read_b128 v[82:85], v203 offset:63200
	ds_read_b128 v[86:89], v203 offset:63168
	ds_read_b128 v[90:93], v203 offset:63104
	ds_read_b128 v[94:97], v203 offset:63136
	s_waitcnt lgkmcnt(1)
	v_mfma_f32_32x32x16_bf16 v[18:33], v[90:93], v[78:81], v[18:33]
	s_waitcnt lgkmcnt(0)
	v_mfma_f32_32x32x16_bf16 v[18:33], v[94:97], v[74:77], v[18:33]
	v_mfma_f32_32x32x16_bf16 v[18:33], v[86:89], v[70:73], v[18:33]
	v_mfma_f32_32x32x16_bf16 v[18:33], v[82:85], v[66:69], v[18:33]
	v_add_u32_e32 v66, 0x8800, v195
	s_waitcnt vmcnt(5)
	ds_write_b128 v202, v[106:109] offset:18432
	s_waitcnt vmcnt(4)
	ds_write_b128 v202, v[118:121] offset:27648
	s_waitcnt vmcnt(3)
	ds_write2_b64 v66, v[114:115], v[116:117] offset1:2
	v_add_u32_e32 v66, 0xa800, v195
	s_waitcnt vmcnt(2)
	ds_write2_b64 v66, v[110:111], v[112:113] offset0:64 offset1:66
	v_add_u32_e32 v66, 0xc800, v195
	s_waitcnt vmcnt(1)
	ds_write2_b64 v66, v[102:103], v[104:105] offset0:128 offset1:130
	v_add_u32_e32 v66, 0xe800, v195
	s_waitcnt vmcnt(0)
	ds_write2_b64 v66, v[98:99], v[100:101] offset0:192 offset1:194
	s_waitcnt lgkmcnt(0)
	s_barrier
	ds_read_b128 v[66:69], v194 offset:18432
	ds_read_b128 v[70:73], v194 offset:18464
	ds_read_b128 v[74:77], v194 offset:23040
	ds_read_b128 v[78:81], v194 offset:23072
	ds_read_b128 v[82:85], v194 offset:18496
	ds_read_b128 v[86:89], v194 offset:18528
	ds_read_b128 v[90:93], v194 offset:23104
	ds_read_b128 v[94:97], v194 offset:23136
	s_waitcnt lgkmcnt(7)
	v_mfma_f32_32x32x16_bf16 v[114:129], v[66:69], v[130:133], 0
	s_waitcnt lgkmcnt(5)
	v_mfma_f32_32x32x16_bf16 v[98:113], v[74:77], v[130:133], 0
	v_mfma_f32_32x32x16_bf16 v[114:129], v[70:73], v[134:137], v[114:129]
	s_waitcnt lgkmcnt(4)
	v_mfma_f32_32x32x16_bf16 v[98:113], v[78:81], v[134:137], v[98:113]
	s_waitcnt lgkmcnt(3)
	v_mfma_f32_32x32x16_bf16 v[114:129], v[82:85], v[138:141], v[114:129]
	s_waitcnt lgkmcnt(1)
	v_mfma_f32_32x32x16_bf16 v[98:113], v[90:93], v[138:141], v[98:113]
	v_mfma_f32_32x32x16_bf16 v[114:129], v[86:89], v[142:145], v[114:129]
	s_waitcnt lgkmcnt(0)
	v_mfma_f32_32x32x16_bf16 v[98:113], v[94:97], v[142:145], v[98:113]
	ds_read_b128 v[66:69], v194 offset:27648
	ds_read_b128 v[146:149], v194 offset:27680
	ds_read_b128 v[70:73], v194 offset:32256
	ds_read_b128 v[150:153], v194 offset:32288
	ds_read_b128 v[198:201], v194 offset:27712
	ds_read_b128 v[210:213], v194 offset:27744
	ds_read_b128 v[214:217], v194 offset:32320
	ds_read_b128 v[248:251], v194 offset:32352
	s_waitcnt lgkmcnt(7)
	v_mfma_f32_32x32x16_bf16 v[82:97], v[66:69], v[130:133], 0
	s_waitcnt lgkmcnt(5)
	v_mfma_f32_32x32x16_bf16 v[66:81], v[70:73], v[130:133], 0
	v_mfma_f32_32x32x16_bf16 v[82:97], v[146:149], v[134:137], v[82:97]
	s_waitcnt lgkmcnt(4)
	v_mfma_f32_32x32x16_bf16 v[66:81], v[150:153], v[134:137], v[66:81]
	s_waitcnt lgkmcnt(3)
	v_mfma_f32_32x32x16_bf16 v[82:97], v[198:201], v[138:141], v[82:97]
	s_waitcnt lgkmcnt(1)
	v_mfma_f32_32x32x16_bf16 v[66:81], v[214:217], v[138:141], v[66:81]
	v_mfma_f32_32x32x16_bf16 v[82:97], v[210:213], v[142:145], v[82:97]
	s_waitcnt lgkmcnt(0)
	v_mfma_f32_32x32x16_bf16 v[66:81], v[248:251], v[142:145], v[66:81]
	ds_read_b128 v[142:145], v193 offset:34816
	ds_read_b128 v[138:141], v193 offset:34848
	ds_read_b128 v[130:133], v193 offset:34880
	ds_read_b128 v[134:137], v193 offset:34912
	v_max3_f32 v146, v114, v98, v115
	v_max_f32_e32 v147, v113, v113
	v_max3_f32 v146, v146, v99, v116
	v_max3_f32 v146, v146, v100, v117
	v_max3_f32 v146, v146, v101, v118
	v_max3_f32 v146, v146, v102, v119
	v_max3_f32 v146, v146, v103, v120
	v_max3_f32 v146, v146, v104, v121
	v_max3_f32 v146, v146, v105, v122
	v_max3_f32 v146, v146, v106, v123
	v_max3_f32 v146, v146, v107, v124
	v_max3_f32 v146, v146, v108, v125
	v_max3_f32 v146, v146, v109, v126
	v_max3_f32 v146, v146, v110, v127
	v_max3_f32 v146, v146, v111, v128
	v_max3_f32 v146, v146, v112, v129
	s_nop 0
	v_max_f32_e32 v146, v146, v146
	v_max_f32_e32 v146, v146, v147
	v_mov_b32_e32 v147, v146
	v_nop
	v_nop
	v_permlane32_swap_b32 v146, v147
	s_nop 0
	v_max3_f32 v219, v246, v146, v147
	v_sub_f32_e32 v146, v246, v219
	v_exp_f32_e32 v146, v146
	s_nop 0
	v_cmp_neq_f32_e32 vcc, 1.0, v146
	s_cbranch_vccz .LBB0_169
	v_pk_mul_f32 v[16:17], v[16:17], v[146:147] op_sel_hi:[1,0]
	v_pk_mul_f32 v[14:15], v[14:15], v[146:147] op_sel_hi:[1,0]
	v_pk_mul_f32 v[12:13], v[12:13], v[146:147] op_sel_hi:[1,0]
	v_pk_mul_f32 v[10:11], v[10:11], v[146:147] op_sel_hi:[1,0]
	v_pk_mul_f32 v[8:9], v[8:9], v[146:147] op_sel_hi:[1,0]
	v_pk_mul_f32 v[6:7], v[6:7], v[146:147] op_sel_hi:[1,0]
	v_pk_mul_f32 v[4:5], v[4:5], v[146:147] op_sel_hi:[1,0]
	v_pk_mul_f32 v[2:3], v[2:3], v[146:147] op_sel_hi:[1,0]
	v_pk_mul_f32 v[64:65], v[64:65], v[146:147] op_sel_hi:[1,0]
	v_pk_mul_f32 v[62:63], v[62:63], v[146:147] op_sel_hi:[1,0]
	v_pk_mul_f32 v[60:61], v[60:61], v[146:147] op_sel_hi:[1,0]
	v_pk_mul_f32 v[58:59], v[58:59], v[146:147] op_sel_hi:[1,0]
	v_pk_mul_f32 v[56:57], v[56:57], v[146:147] op_sel_hi:[1,0]
	v_pk_mul_f32 v[54:55], v[54:55], v[146:147] op_sel_hi:[1,0]
	v_pk_mul_f32 v[52:53], v[52:53], v[146:147] op_sel_hi:[1,0]
	v_pk_mul_f32 v[50:51], v[50:51], v[146:147] op_sel_hi:[1,0]
	v_pk_mul_f32 v[48:49], v[48:49], v[146:147] op_sel_hi:[1,0]
	v_pk_mul_f32 v[46:47], v[46:47], v[146:147] op_sel_hi:[1,0]
	v_pk_mul_f32 v[44:45], v[44:45], v[146:147] op_sel_hi:[1,0]
	v_pk_mul_f32 v[42:43], v[42:43], v[146:147] op_sel_hi:[1,0]
	v_pk_mul_f32 v[40:41], v[40:41], v[146:147] op_sel_hi:[1,0]
	v_pk_mul_f32 v[38:39], v[38:39], v[146:147] op_sel_hi:[1,0]
	v_pk_mul_f32 v[36:37], v[36:37], v[146:147] op_sel_hi:[1,0]
	v_pk_mul_f32 v[34:35], v[34:35], v[146:147] op_sel_hi:[1,0]
	v_pk_mul_f32 v[32:33], v[32:33], v[146:147] op_sel_hi:[1,0]
	v_pk_mul_f32 v[30:31], v[30:31], v[146:147] op_sel_hi:[1,0]
	v_pk_mul_f32 v[28:29], v[28:29], v[146:147] op_sel_hi:[1,0]
	v_pk_mul_f32 v[26:27], v[26:27], v[146:147] op_sel_hi:[1,0]
	v_pk_mul_f32 v[24:25], v[24:25], v[146:147] op_sel_hi:[1,0]
	v_pk_mul_f32 v[22:23], v[22:23], v[146:147] op_sel_hi:[1,0]
	v_pk_mul_f32 v[20:21], v[20:21], v[146:147] op_sel_hi:[1,0]
	v_pk_mul_f32 v[18:19], v[18:19], v[146:147] op_sel_hi:[1,0]
.LBB0_169:
	v_sub_f32_e32 v98, v98, v219
	v_exp_f32_e32 v148, v98
	v_sub_f32_e32 v98, v115, v219
	v_exp_f32_e32 v149, v98
	v_sub_f32_e32 v98, v99, v219
	v_exp_f32_e32 v150, v98
	v_sub_f32_e32 v98, v116, v219
	v_exp_f32_e32 v151, v98
	v_sub_f32_e32 v98, v100, v219
	v_exp_f32_e32 v152, v98
	v_sub_f32_e32 v98, v117, v219
	v_exp_f32_e32 v117, v98
	v_sub_f32_e32 v98, v101, v219
	v_exp_f32_e32 v153, v98
	v_sub_f32_e32 v98, v118, v219
	v_exp_f32_e32 v118, v98
	v_sub_f32_e32 v98, v102, v219
	v_exp_f32_e32 v194, v98
	v_sub_f32_e32 v98, v119, v219
	v_exp_f32_e32 v119, v98
	v_sub_f32_e32 v98, v103, v219
	v_exp_f32_e32 v195, v98
	v_sub_f32_e32 v98, v120, v219
	v_exp_f32_e32 v120, v98
	v_sub_f32_e32 v98, v104, v219
	v_exp_f32_e32 v202, v98
	v_sub_f32_e32 v98, v121, v219
	v_exp_f32_e32 v121, v98
	v_sub_f32_e32 v98, v105, v219
	v_exp_f32_e32 v203, v98
	v_sub_f32_e32 v98, v122, v219
	v_exp_f32_e32 v122, v98
	v_sub_f32_e32 v98, v106, v219
	v_exp_f32_e32 v246, v98
	v_sub_f32_e32 v98, v123, v219
	v_exp_f32_e32 v123, v98
	v_sub_f32_e32 v98, v107, v219
	v_exp_f32_e32 v247, v98
	v_sub_f32_e32 v98, v124, v219
	v_exp_f32_e32 v124, v98
	v_sub_f32_e32 v98, v108, v219
	v_exp_f32_e32 v248, v98
	v_sub_f32_e32 v98, v125, v219
	v_exp_f32_e32 v125, v98
	v_sub_f32_e32 v98, v109, v219
	v_exp_f32_e32 v249, v98
	v_sub_f32_e32 v98, v126, v219
	v_exp_f32_e32 v126, v98
	v_sub_f32_e32 v98, v110, v219
	v_exp_f32_e32 v250, v98
	v_sub_f32_e32 v98, v127, v219
	v_exp_f32_e32 v127, v98
	v_sub_f32_e32 v98, v111, v219
	v_exp_f32_e32 v251, v98
	v_sub_f32_e32 v98, v128, v219
	v_exp_f32_e32 v128, v98
	v_sub_f32_e32 v98, v112, v219
	v_exp_f32_e32 v252, v98
	v_sub_f32_e32 v98, v129, v219
	v_sub_f32_e32 v114, v114, v219
	v_exp_f32_e32 v129, v98
	v_sub_f32_e32 v98, v113, v219
	v_exp_f32_e32 v147, v114
	v_exp_f32_e32 v253, v98
	v_cvt_pk_bf16_f32 v98, v246, v247
	v_cvt_pk_bf16_f32 v99, v248, v249
	v_cvt_pk_bf16_f32 v100, v250, v251
	v_cvt_pk_bf16_f32 v101, v252, v253
	v_cvt_pk_bf16_f32 v102, v148, v150
	v_cvt_pk_bf16_f32 v103, v152, v153
	v_cvt_pk_bf16_f32 v104, v194, v195
	v_cvt_pk_bf16_f32 v105, v202, v203
	v_cvt_pk_bf16_f32 v106, v122, v123
	v_cvt_pk_bf16_f32 v107, v124, v125
	v_cvt_pk_bf16_f32 v108, v126, v127
	v_cvt_pk_bf16_f32 v109, v128, v129
	v_cvt_pk_bf16_f32 v110, v147, v149
	v_cvt_pk_bf16_f32 v111, v151, v117
	v_cvt_pk_bf16_f32 v112, v118, v119
	v_cvt_pk_bf16_f32 v113, v120, v121
	s_waitcnt lgkmcnt(3)
	s_nop 0
	v_mfma_f32_32x32x16_bf16 v[2:17], v[142:145], v[110:113], v[2:17]
	s_waitcnt lgkmcnt(2)
	v_mfma_f32_32x32x16_bf16 v[2:17], v[138:141], v[106:109], v[2:17]
	s_waitcnt lgkmcnt(1)
	v_mfma_f32_32x32x16_bf16 v[2:17], v[130:133], v[102:105], v[2:17]
	s_waitcnt lgkmcnt(0)
	v_mfma_f32_32x32x16_bf16 v[2:17], v[134:137], v[98:101], v[2:17]
	ds_read_b128 v[130:133], v193 offset:43616
	ds_read_b128 v[134:137], v193 offset:43584
	ds_read_b128 v[138:141], v193 offset:43520
	ds_read_b128 v[142:145], v193 offset:43552
	s_waitcnt lgkmcnt(1)
	v_mfma_f32_32x32x16_bf16 v[50:65], v[138:141], v[110:113], v[50:65]
	s_waitcnt lgkmcnt(0)
	v_mfma_f32_32x32x16_bf16 v[50:65], v[142:145], v[106:109], v[50:65]
	v_mfma_f32_32x32x16_bf16 v[50:65], v[134:137], v[102:105], v[50:65]
	v_mfma_f32_32x32x16_bf16 v[50:65], v[130:133], v[98:101], v[50:65]
	ds_read_b128 v[130:133], v193 offset:52320
	ds_read_b128 v[134:137], v193 offset:52288
	ds_read_b128 v[138:141], v193 offset:52224
	ds_read_b128 v[142:145], v193 offset:52256
	s_waitcnt lgkmcnt(1)
	v_mfma_f32_32x32x16_bf16 v[34:49], v[138:141], v[110:113], v[34:49]
	s_waitcnt lgkmcnt(0)
	v_mfma_f32_32x32x16_bf16 v[34:49], v[142:145], v[106:109], v[34:49]
	v_mfma_f32_32x32x16_bf16 v[34:49], v[134:137], v[102:105], v[34:49]
	v_mfma_f32_32x32x16_bf16 v[34:49], v[130:133], v[98:101], v[34:49]
	ds_read_b128 v[130:133], v193 offset:61024
	ds_read_b128 v[134:137], v193 offset:60992
	ds_read_b128 v[138:141], v193 offset:60928
	ds_read_b128 v[142:145], v193 offset:60960
	s_waitcnt lgkmcnt(1)
	v_mfma_f32_32x32x16_bf16 v[18:33], v[138:141], v[110:113], v[18:33]
	s_waitcnt lgkmcnt(0)
	v_mfma_f32_32x32x16_bf16 v[18:33], v[142:145], v[106:109], v[18:33]
	v_mfma_f32_32x32x16_bf16 v[18:33], v[134:137], v[102:105], v[18:33]
	v_mfma_f32_32x32x16_bf16 v[18:33], v[130:133], v[98:101], v[18:33]
	ds_read_b128 v[110:113], v193 offset:34944
	ds_read_b128 v[106:109], v193 offset:34976
	ds_read_b128 v[98:101], v193 offset:35008
	ds_read_b128 v[102:105], v193 offset:35040
	v_max3_f32 v114, v82, v66, v83
	v_max_f32_e32 v115, v81, v81
	v_max3_f32 v114, v114, v67, v84
	v_max3_f32 v114, v114, v68, v85
	v_max3_f32 v114, v114, v69, v86
	v_max3_f32 v114, v114, v70, v87
	v_max3_f32 v114, v114, v71, v88
	v_max3_f32 v114, v114, v72, v89
	v_max3_f32 v114, v114, v73, v90
	v_max3_f32 v114, v114, v74, v91
	v_max3_f32 v114, v114, v75, v92
	v_max3_f32 v114, v114, v76, v93
	v_max3_f32 v114, v114, v77, v94
	v_max3_f32 v114, v114, v78, v95
	v_max3_f32 v114, v114, v79, v96
	v_max3_f32 v114, v114, v80, v97
	s_nop 0
	v_max_f32_e32 v114, v114, v114
	v_max_f32_e32 v114, v114, v115
	v_mov_b32_e32 v115, v114
	v_nop
	v_nop
	v_permlane32_swap_b32 v114, v115
	s_nop 0
	v_max3_f32 v130, v219, v114, v115
	v_sub_f32_e32 v114, v219, v130
	v_exp_f32_e32 v116, v114
	s_nop 0
	v_cmp_neq_f32_e32 vcc, 1.0, v116
	s_cbranch_vccz .LBB0_158
	v_pk_mul_f32 v[16:17], v[16:17], v[116:117] op_sel_hi:[1,0]
	v_pk_mul_f32 v[14:15], v[14:15], v[116:117] op_sel_hi:[1,0]
	v_pk_mul_f32 v[12:13], v[12:13], v[116:117] op_sel_hi:[1,0]
	v_pk_mul_f32 v[10:11], v[10:11], v[116:117] op_sel_hi:[1,0]
	v_pk_mul_f32 v[8:9], v[8:9], v[116:117] op_sel_hi:[1,0]
	v_pk_mul_f32 v[6:7], v[6:7], v[116:117] op_sel_hi:[1,0]
	v_pk_mul_f32 v[4:5], v[4:5], v[116:117] op_sel_hi:[1,0]
	v_pk_mul_f32 v[2:3], v[2:3], v[116:117] op_sel_hi:[1,0]
	v_pk_mul_f32 v[64:65], v[64:65], v[116:117] op_sel_hi:[1,0]
	v_pk_mul_f32 v[62:63], v[62:63], v[116:117] op_sel_hi:[1,0]
	v_pk_mul_f32 v[60:61], v[60:61], v[116:117] op_sel_hi:[1,0]
	v_pk_mul_f32 v[58:59], v[58:59], v[116:117] op_sel_hi:[1,0]
	v_pk_mul_f32 v[56:57], v[56:57], v[116:117] op_sel_hi:[1,0]
	v_pk_mul_f32 v[54:55], v[54:55], v[116:117] op_sel_hi:[1,0]
	v_pk_mul_f32 v[52:53], v[52:53], v[116:117] op_sel_hi:[1,0]
	v_pk_mul_f32 v[50:51], v[50:51], v[116:117] op_sel_hi:[1,0]
	v_pk_mul_f32 v[48:49], v[48:49], v[116:117] op_sel_hi:[1,0]
	v_pk_mul_f32 v[46:47], v[46:47], v[116:117] op_sel_hi:[1,0]
	v_pk_mul_f32 v[44:45], v[44:45], v[116:117] op_sel_hi:[1,0]
	v_pk_mul_f32 v[42:43], v[42:43], v[116:117] op_sel_hi:[1,0]
	v_pk_mul_f32 v[40:41], v[40:41], v[116:117] op_sel_hi:[1,0]
	v_pk_mul_f32 v[38:39], v[38:39], v[116:117] op_sel_hi:[1,0]
	v_pk_mul_f32 v[36:37], v[36:37], v[116:117] op_sel_hi:[1,0]
	v_pk_mul_f32 v[34:35], v[34:35], v[116:117] op_sel_hi:[1,0]
	v_pk_mul_f32 v[32:33], v[32:33], v[116:117] op_sel_hi:[1,0]
	v_pk_mul_f32 v[30:31], v[30:31], v[116:117] op_sel_hi:[1,0]
	v_pk_mul_f32 v[28:29], v[28:29], v[116:117] op_sel_hi:[1,0]
	v_pk_mul_f32 v[26:27], v[26:27], v[116:117] op_sel_hi:[1,0]
	v_pk_mul_f32 v[24:25], v[24:25], v[116:117] op_sel_hi:[1,0]
	v_pk_mul_f32 v[22:23], v[22:23], v[116:117] op_sel_hi:[1,0]
	v_pk_mul_f32 v[20:21], v[20:21], v[116:117] op_sel_hi:[1,0]
	v_pk_mul_f32 v[18:19], v[18:19], v[116:117] op_sel_hi:[1,0]
	s_branch .LBB0_158

.LBB0_186:
	s_or_b64 exec, exec, s[0:1]
	global_load_dwordx4 v[2:5], v[204:205], off
	s_and_b32 s0, s4, 1
	s_mul_i32 s1, s0, 0x3400
	v_add_u32_e32 v10, s1, v225
	ds_read_b128 v[12:15], v10 offset:6656
	ds_read_b128 v[80:83], v10
	ds_read_b128 v[230:233], v10 offset:32
	s_waitcnt lgkmcnt(2)
	v_mfma_f32_32x32x16_bf16 v[112:127], v[12:15], v[160:163], 0
	s_waitcnt lgkmcnt(1)
	v_mfma_f32_32x32x16_bf16 v[128:143], v[80:83], v[160:163], 0
	v_mfma_f32_32x32x16_bf16 v[96:111], v[80:83], v[188:191], 0
	v_mfma_f32_32x32x16_bf16 v[80:95], v[12:15], v[188:191], 0
	ds_read_b128 v[12:15], v10 offset:6688
	s_waitcnt lgkmcnt(1)
	v_mfma_f32_32x32x16_bf16 v[128:143], v[230:233], v[156:159], v[128:143]
	s_waitcnt lgkmcnt(0)
	v_mfma_f32_32x32x16_bf16 v[112:127], v[12:15], v[156:159], v[112:127]
	v_mfma_f32_32x32x16_bf16 v[96:111], v[230:233], v[184:187], v[96:111]
	v_mfma_f32_32x32x16_bf16 v[80:95], v[12:15], v[184:187], v[80:95]
	ds_read_b128 v[12:15], v10 offset:64
	ds_read_b128 v[230:233], v10 offset:6720
	s_waitcnt lgkmcnt(1)
	v_mfma_f32_32x32x16_bf16 v[128:143], v[12:15], v[164:167], v[128:143]
	s_waitcnt lgkmcnt(0)
	v_mfma_f32_32x32x16_bf16 v[112:127], v[230:233], v[164:167], v[112:127]
	v_mfma_f32_32x32x16_bf16 v[96:111], v[12:15], v[192:195], v[96:111]
	v_mfma_f32_32x32x16_bf16 v[80:95], v[230:233], v[192:195], v[80:95]
	ds_read_b128 v[12:15], v10 offset:96
	ds_read_b128 v[230:233], v10 offset:6752
	s_waitcnt lgkmcnt(1)
	v_mfma_f32_32x32x16_bf16 v[128:143], v[12:15], v[152:155], v[128:143]
	s_waitcnt lgkmcnt(0)
	v_mfma_f32_32x32x16_bf16 v[112:127], v[230:233], v[152:155], v[112:127]
	v_mfma_f32_32x32x16_bf16 v[96:111], v[12:15], v[180:183], v[96:111]
	v_mfma_f32_32x32x16_bf16 v[80:95], v[230:233], v[180:183], v[80:95]
	ds_read_b128 v[12:15], v10 offset:128
	ds_read_b128 v[230:233], v10 offset:6784
	s_waitcnt lgkmcnt(1)
	v_mfma_f32_32x32x16_bf16 v[128:143], v[12:15], v[168:171], v[128:143]
	s_waitcnt lgkmcnt(0)
	v_mfma_f32_32x32x16_bf16 v[112:127], v[230:233], v[168:171], v[112:127]
	v_mfma_f32_32x32x16_bf16 v[96:111], v[12:15], v[176:179], v[96:111]
	v_mfma_f32_32x32x16_bf16 v[80:95], v[230:233], v[176:179], v[80:95]
	ds_read_b128 v[12:15], v10 offset:160
	ds_read_b128 v[230:233], v10 offset:6816
	s_waitcnt lgkmcnt(1)
	v_mfma_f32_32x32x16_bf16 v[128:143], v[12:15], v[148:151], v[128:143]
	s_waitcnt lgkmcnt(0)
	v_mfma_f32_32x32x16_bf16 v[112:127], v[230:233], v[148:151], v[112:127]
	v_max3_f32 v10, v128, v112, v129
	v_max3_f32 v10, v10, v113, v130
	v_max3_f32 v10, v10, v114, v131
	v_max3_f32 v10, v10, v115, v132
	v_mfma_f32_32x32x16_bf16 v[96:111], v[12:15], v[172:175], v[96:111]
	v_max3_f32 v10, v10, v116, v133
	s_nop 7
	v_max_f32_e32 v12, v127, v127
	v_max3_f32 v10, v10, v117, v134
	v_max3_f32 v10, v10, v118, v135
	v_max3_f32 v10, v10, v119, v136
	v_mfma_f32_32x32x16_bf16 v[80:95], v[230:233], v[172:175], v[80:95]
	v_max3_f32 v10, v10, v120, v137
	v_max3_f32 v10, v10, v121, v138
	v_max3_f32 v10, v10, v122, v139
	v_max3_f32 v10, v10, v123, v140
	v_max3_f32 v10, v10, v124, v141
	v_max3_f32 v10, v10, v125, v142
	v_max3_f32 v10, v10, v126, v143
	s_nop 0
	v_max_f32_e32 v10, v10, v10
	v_max_f32_e32 v10, v10, v12
	v_mov_b32_e32 v12, v10
	v_nop
	v_nop
	v_permlane32_swap_b32 v12, v10
	s_nop 0
	v_max3_f32 v12, v0, v12, v10
	v_sub_f32_e32 v0, v0, v12
	v_exp_f32_e32 v0, v0
	s_nop 0
	v_cmp_neq_f32_e32 vcc, 1.0, v0
	s_cbranch_vccz .LBB0_188
	v_pk_mul_f32 v[78:79], v[78:79], v[0:1] op_sel_hi:[1,0]
	v_pk_mul_f32 v[76:77], v[76:77], v[0:1] op_sel_hi:[1,0]
	v_pk_mul_f32 v[74:75], v[74:75], v[0:1] op_sel_hi:[1,0]
	v_pk_mul_f32 v[72:73], v[72:73], v[0:1] op_sel_hi:[1,0]
	v_pk_mul_f32 v[70:71], v[70:71], v[0:1] op_sel_hi:[1,0]
	v_pk_mul_f32 v[68:69], v[68:69], v[0:1] op_sel_hi:[1,0]
	v_pk_mul_f32 v[66:67], v[66:67], v[0:1] op_sel_hi:[1,0]
	v_pk_mul_f32 v[64:65], v[64:65], v[0:1] op_sel_hi:[1,0]
	v_pk_mul_f32 v[62:63], v[62:63], v[0:1] op_sel_hi:[1,0]
	v_pk_mul_f32 v[60:61], v[60:61], v[0:1] op_sel_hi:[1,0]
	v_pk_mul_f32 v[58:59], v[58:59], v[0:1] op_sel_hi:[1,0]
	v_pk_mul_f32 v[56:57], v[56:57], v[0:1] op_sel_hi:[1,0]
	v_pk_mul_f32 v[54:55], v[54:55], v[0:1] op_sel_hi:[1,0]
	v_pk_mul_f32 v[52:53], v[52:53], v[0:1] op_sel_hi:[1,0]
	v_pk_mul_f32 v[50:51], v[50:51], v[0:1] op_sel_hi:[1,0]
	v_pk_mul_f32 v[48:49], v[48:49], v[0:1] op_sel_hi:[1,0]
.LBB0_188:
	v_max3_f32 v10, v96, v80, v97
	v_max_f32_e32 v13, v95, v95
	v_max3_f32 v10, v10, v81, v98
	v_max3_f32 v10, v10, v82, v99
	v_max3_f32 v10, v10, v83, v100
	v_max3_f32 v10, v10, v84, v101
	v_max3_f32 v10, v10, v85, v102
	v_max3_f32 v10, v10, v86, v103
	v_max3_f32 v10, v10, v87, v104
	v_max3_f32 v10, v10, v88, v105
	v_max3_f32 v10, v10, v89, v106
	v_max3_f32 v10, v10, v90, v107
	v_max3_f32 v10, v10, v91, v108
	v_max3_f32 v10, v10, v92, v109
	v_max3_f32 v10, v10, v93, v110
	v_max3_f32 v10, v10, v94, v111
	s_nop 0
	v_max_f32_e32 v10, v10, v10
	v_max_f32_e32 v10, v10, v13
	v_mov_b32_e32 v13, v10
	v_nop
	v_nop
	v_permlane32_swap_b32 v10, v13
	s_nop 0
	v_max3_f32 v13, v228, v10, v13
	v_sub_f32_e32 v10, v228, v13
	v_exp_f32_e32 v10, v10
	s_nop 0
	v_cmp_neq_f32_e32 vcc, 1.0, v10
	s_cbranch_vccz .LBB0_190
	v_pk_mul_f32 v[46:47], v[46:47], v[10:11] op_sel_hi:[1,0]
	v_pk_mul_f32 v[44:45], v[44:45], v[10:11] op_sel_hi:[1,0]
	v_pk_mul_f32 v[42:43], v[42:43], v[10:11] op_sel_hi:[1,0]
	v_pk_mul_f32 v[40:41], v[40:41], v[10:11] op_sel_hi:[1,0]
	v_pk_mul_f32 v[38:39], v[38:39], v[10:11] op_sel_hi:[1,0]
	v_pk_mul_f32 v[36:37], v[36:37], v[10:11] op_sel_hi:[1,0]
	v_pk_mul_f32 v[34:35], v[34:35], v[10:11] op_sel_hi:[1,0]
	v_pk_mul_f32 v[32:33], v[32:33], v[10:11] op_sel_hi:[1,0]
	v_pk_mul_f32 v[30:31], v[30:31], v[10:11] op_sel_hi:[1,0]
	v_pk_mul_f32 v[28:29], v[28:29], v[10:11] op_sel_hi:[1,0]
	v_pk_mul_f32 v[26:27], v[26:27], v[10:11] op_sel_hi:[1,0]
	v_pk_mul_f32 v[24:25], v[24:25], v[10:11] op_sel_hi:[1,0]
	v_pk_mul_f32 v[22:23], v[22:23], v[10:11] op_sel_hi:[1,0]
	v_pk_mul_f32 v[20:21], v[20:21], v[10:11] op_sel_hi:[1,0]
	v_pk_mul_f32 v[18:19], v[18:19], v[10:11] op_sel_hi:[1,0]
	v_pk_mul_f32 v[16:17], v[16:17], v[10:11] op_sel_hi:[1,0]

.Lmla_stag_out:
	ds_read_b128 v[2:5], v225 offset:13312
	ds_read_b128 v[144:147], v225 offset:13472
	ds_read_b128 v[6:9], v225 offset:19968
	s_waitcnt lgkmcnt(2)
	v_mfma_f32_32x32x16_bf16 v[80:95], v[2:5], v[160:163], 0
	v_mfma_f32_32x32x16_bf16 v[112:127], v[2:5], v[188:191], 0
	ds_read_b128 v[2:5], v225 offset:13344
	s_waitcnt lgkmcnt(1)
	v_mfma_f32_32x32x16_bf16 v[96:111], v[6:9], v[160:163], 0
	v_mfma_f32_32x32x16_bf16 v[128:143], v[6:9], v[188:191], 0
	ds_read_b128 v[6:9], v225 offset:20000
	s_waitcnt lgkmcnt(1)
	v_mfma_f32_32x32x16_bf16 v[80:95], v[2:5], v[156:159], v[80:95]
	v_mfma_f32_32x32x16_bf16 v[112:127], v[2:5], v[184:187], v[112:127]
	ds_read_b128 v[2:5], v225 offset:13376
	s_waitcnt lgkmcnt(1)
	v_mfma_f32_32x32x16_bf16 v[96:111], v[6:9], v[156:159], v[96:111]
	v_mfma_f32_32x32x16_bf16 v[128:143], v[6:9], v[184:187], v[128:143]
	ds_read_b128 v[6:9], v225 offset:20032
	s_waitcnt lgkmcnt(1)
	v_mfma_f32_32x32x16_bf16 v[80:95], v[2:5], v[164:167], v[80:95]
	v_mfma_f32_32x32x16_bf16 v[112:127], v[2:5], v[192:195], v[112:127]
	ds_read_b128 v[2:5], v225 offset:13408
	s_waitcnt lgkmcnt(1)
	v_mfma_f32_32x32x16_bf16 v[96:111], v[6:9], v[164:167], v[96:111]
	v_mfma_f32_32x32x16_bf16 v[128:143], v[6:9], v[192:195], v[128:143]
	ds_read_b128 v[6:9], v225 offset:20064
	s_waitcnt lgkmcnt(1)
	v_mfma_f32_32x32x16_bf16 v[80:95], v[2:5], v[152:155], v[80:95]
	v_mfma_f32_32x32x16_bf16 v[112:127], v[2:5], v[180:183], v[112:127]
	ds_read_b128 v[2:5], v225 offset:13440
	s_waitcnt lgkmcnt(1)
	v_mfma_f32_32x32x16_bf16 v[96:111], v[6:9], v[152:155], v[96:111]
	ds_read_b128 v[152:155], v225 offset:20128
	v_mfma_f32_32x32x16_bf16 v[128:143], v[6:9], v[180:183], v[128:143]
	ds_read_b128 v[6:9], v225 offset:20096
	s_waitcnt lgkmcnt(2)
	v_mfma_f32_32x32x16_bf16 v[80:95], v[2:5], v[168:171], v[80:95]
	s_waitcnt lgkmcnt(0)
	v_mfma_f32_32x32x16_bf16 v[96:111], v[6:9], v[168:171], v[96:111]
	v_mfma_f32_32x32x16_bf16 v[80:95], v[144:147], v[148:151], v[80:95]
	v_mfma_f32_32x32x16_bf16 v[96:111], v[152:155], v[148:151], v[96:111]
	v_max3_f32 v0, v80, v96, v81
	v_max3_f32 v0, v0, v97, v82
	v_max3_f32 v0, v0, v98, v83
	v_max3_f32 v0, v0, v99, v84
	v_mfma_f32_32x32x16_bf16 v[112:127], v[2:5], v[176:179], v[112:127]
	v_max3_f32 v0, v0, v100, v85
	s_nop 7
	v_max_f32_e32 v2, v111, v111
	v_max3_f32 v0, v0, v101, v86
	v_max3_f32 v0, v0, v102, v87
	v_max3_f32 v0, v0, v103, v88
	v_mfma_f32_32x32x16_bf16 v[128:143], v[6:9], v[176:179], v[128:143]
	v_max3_f32 v0, v0, v104, v89
	v_max3_f32 v0, v0, v105, v90
	v_max3_f32 v0, v0, v106, v91
	v_max3_f32 v0, v0, v107, v92
	v_mfma_f32_32x32x16_bf16 v[112:127], v[144:147], v[172:175], v[112:127]
	v_max3_f32 v0, v0, v108, v93
	v_max3_f32 v0, v0, v109, v94
	v_max3_f32 v0, v0, v110, v95
	s_nop 0
	v_max_f32_e32 v0, v0, v0
	v_max_f32_e32 v0, v0, v2
	v_mov_b32_e32 v2, v0
	v_mfma_f32_32x32x16_bf16 v[128:143], v[152:155], v[172:175], v[128:143]
	v_nop
	v_nop
	v_permlane32_swap_b32 v0, v2
	s_nop 0
	v_max3_f32 v147, v12, v0, v2
	v_sub_f32_e32 v0, v12, v147
	v_exp_f32_e32 v14, v0
	s_nop 0
	v_cmp_neq_f32_e32 vcc, 1.0, v14
	s_cbranch_vccz .LBB0_195
	v_pk_mul_f32 v[78:79], v[78:79], v[14:15] op_sel_hi:[1,0]
	v_pk_mul_f32 v[76:77], v[76:77], v[14:15] op_sel_hi:[1,0]
	v_pk_mul_f32 v[74:75], v[74:75], v[14:15] op_sel_hi:[1,0]
	v_pk_mul_f32 v[72:73], v[72:73], v[14:15] op_sel_hi:[1,0]
	v_pk_mul_f32 v[70:71], v[70:71], v[14:15] op_sel_hi:[1,0]
	v_pk_mul_f32 v[68:69], v[68:69], v[14:15] op_sel_hi:[1,0]
	v_pk_mul_f32 v[66:67], v[66:67], v[14:15] op_sel_hi:[1,0]
	v_pk_mul_f32 v[64:65], v[64:65], v[14:15] op_sel_hi:[1,0]
	v_pk_mul_f32 v[62:63], v[62:63], v[14:15] op_sel_hi:[1,0]
	v_pk_mul_f32 v[60:61], v[60:61], v[14:15] op_sel_hi:[1,0]
	v_pk_mul_f32 v[58:59], v[58:59], v[14:15] op_sel_hi:[1,0]
	v_pk_mul_f32 v[56:57], v[56:57], v[14:15] op_sel_hi:[1,0]
	v_pk_mul_f32 v[54:55], v[54:55], v[14:15] op_sel_hi:[1,0]
	v_pk_mul_f32 v[52:53], v[52:53], v[14:15] op_sel_hi:[1,0]
	v_pk_mul_f32 v[50:51], v[50:51], v[14:15] op_sel_hi:[1,0]
	v_pk_mul_f32 v[48:49], v[48:49], v[14:15] op_sel_hi:[1,0]
.LBB0_195:
	v_max3_f32 v0, v112, v128, v113
	v_max_f32_e32 v2, v143, v143
	v_max3_f32 v0, v0, v129, v114
	v_max3_f32 v0, v0, v130, v115
	v_max3_f32 v0, v0, v131, v116
	v_max3_f32 v0, v0, v132, v117
	v_max3_f32 v0, v0, v133, v118
	v_max3_f32 v0, v0, v134, v119
	v_max3_f32 v0, v0, v135, v120
	v_max3_f32 v0, v0, v136, v121
	v_max3_f32 v0, v0, v137, v122
	v_max3_f32 v0, v0, v138, v123
	v_max3_f32 v0, v0, v139, v124
	v_max3_f32 v0, v0, v140, v125
	v_max3_f32 v0, v0, v141, v126
	v_max3_f32 v0, v0, v142, v127
	s_nop 0
	v_max_f32_e32 v0, v0, v0
	v_max_f32_e32 v0, v0, v2
	v_mov_b32_e32 v2, v0
	v_nop
	v_nop
	v_permlane32_swap_b32 v2, v0
	s_nop 0
	v_max3_f32 v2, v13, v2, v0
	v_sub_f32_e32 v0, v13, v2
	v_exp_f32_e32 v144, v0
	s_nop 0
	v_cmp_neq_f32_e32 vcc, 1.0, v144
	s_cbranch_vccz .LBB0_176
	v_pk_mul_f32 v[46:47], v[46:47], v[144:145] op_sel_hi:[1,0]
	v_pk_mul_f32 v[44:45], v[44:45], v[144:145] op_sel_hi:[1,0]
	v_pk_mul_f32 v[42:43], v[42:43], v[144:145] op_sel_hi:[1,0]
	v_pk_mul_f32 v[40:41], v[40:41], v[144:145] op_sel_hi:[1,0]
	v_pk_mul_f32 v[38:39], v[38:39], v[144:145] op_sel_hi:[1,0]
	v_pk_mul_f32 v[36:37], v[36:37], v[144:145] op_sel_hi:[1,0]
	v_pk_mul_f32 v[34:35], v[34:35], v[144:145] op_sel_hi:[1,0]
	v_pk_mul_f32 v[32:33], v[32:33], v[144:145] op_sel_hi:[1,0]
	v_pk_mul_f32 v[30:31], v[30:31], v[144:145] op_sel_hi:[1,0]
	v_pk_mul_f32 v[28:29], v[28:29], v[144:145] op_sel_hi:[1,0]
	v_pk_mul_f32 v[26:27], v[26:27], v[144:145] op_sel_hi:[1,0]
	v_pk_mul_f32 v[24:25], v[24:25], v[144:145] op_sel_hi:[1,0]
	v_pk_mul_f32 v[22:23], v[22:23], v[144:145] op_sel_hi:[1,0]
	v_pk_mul_f32 v[20:21], v[20:21], v[144:145] op_sel_hi:[1,0]
	v_pk_mul_f32 v[18:19], v[18:19], v[144:145] op_sel_hi:[1,0]
	v_pk_mul_f32 v[16:17], v[16:17], v[144:145] op_sel_hi:[1,0]
	s_branch .LBB0_176

.LBB0_227:
	s_mul_i32 s10, s7, 0x6800
	v_add_u32_e32 v0, s10, v192
	ds_read_b128 v[2:5], v0
	ds_read_b128 v[6:9], v0 offset:32
	ds_read_b128 v[10:13], v0 offset:6656
	ds_read_b128 v[48:51], v0 offset:64
	ds_read_b128 v[52:55], v0 offset:6688
	ds_read_b128 v[56:59], v0 offset:6720
	s_mulk_i32 s7, 0x4400
	s_waitcnt lgkmcnt(5)
	v_mfma_f32_32x32x16_bf16 v[96:111], v[2:5], v[120:123], 0
	s_waitcnt lgkmcnt(3)
	v_mfma_f32_32x32x16_bf16 v[80:95], v[10:13], v[120:123], 0
	v_mfma_f32_32x32x16_bf16 v[96:111], v[6:9], v[124:127], v[96:111]
	s_waitcnt lgkmcnt(1)
	v_mfma_f32_32x32x16_bf16 v[80:95], v[52:55], v[124:127], v[80:95]
	v_mfma_f32_32x32x16_bf16 v[96:111], v[48:51], v[128:131], v[96:111]
	s_waitcnt lgkmcnt(0)
	v_mfma_f32_32x32x16_bf16 v[80:95], v[56:59], v[128:131], v[80:95]
	ds_read_b128 v[2:5], v0 offset:96
	ds_read_b128 v[6:9], v0 offset:128
	ds_read_b128 v[10:13], v0 offset:6752
	ds_read_b128 v[48:51], v0 offset:160
	ds_read_b128 v[52:55], v0 offset:6784
	ds_read_b128 v[56:59], v0 offset:6816
	s_waitcnt lgkmcnt(5)
	v_mfma_f32_32x32x16_bf16 v[96:111], v[2:5], v[144:147], v[96:111]
	s_waitcnt lgkmcnt(3)
	v_mfma_f32_32x32x16_bf16 v[80:95], v[10:13], v[144:147], v[80:95]
	v_mfma_f32_32x32x16_bf16 v[96:111], v[6:9], v[148:151], v[96:111]
	s_waitcnt lgkmcnt(1)
	v_mfma_f32_32x32x16_bf16 v[80:95], v[52:55], v[148:151], v[80:95]
	v_mfma_f32_32x32x16_bf16 v[96:111], v[48:51], v[152:155], v[96:111]
	s_waitcnt lgkmcnt(0)
	v_mfma_f32_32x32x16_bf16 v[80:95], v[56:59], v[152:155], v[80:95]
	ds_read_b128 v[2:5], v0 offset:13312
	ds_read_b128 v[6:9], v0 offset:13344
	ds_read_b128 v[10:13], v0 offset:19968
	ds_read_b128 v[156:159], v0 offset:13376
	ds_read_b128 v[160:163], v0 offset:20000
	ds_read_b128 v[164:167], v0 offset:20032
	s_waitcnt lgkmcnt(5)
	v_mfma_f32_32x32x16_bf16 v[64:79], v[2:5], v[120:123], 0
	s_waitcnt lgkmcnt(3)
	v_mfma_f32_32x32x16_bf16 v[48:63], v[10:13], v[120:123], 0
	v_mfma_f32_32x32x16_bf16 v[64:79], v[6:9], v[124:127], v[64:79]
	s_waitcnt lgkmcnt(1)
	v_mfma_f32_32x32x16_bf16 v[48:63], v[160:163], v[124:127], v[48:63]
	v_mfma_f32_32x32x16_bf16 v[64:79], v[156:159], v[128:131], v[64:79]
	s_waitcnt lgkmcnt(0)
	v_mfma_f32_32x32x16_bf16 v[48:63], v[164:167], v[128:131], v[48:63]
	ds_read_b128 v[2:5], v0 offset:13408
	ds_read_b128 v[6:9], v0 offset:13440
	ds_read_b128 v[10:13], v0 offset:20064
	ds_read_b128 v[156:159], v0 offset:13472
	ds_read_b128 v[160:163], v0 offset:20096
	ds_read_b128 v[164:167], v0 offset:20128
	s_waitcnt lgkmcnt(5)
	v_mfma_f32_32x32x16_bf16 v[64:79], v[2:5], v[144:147], v[64:79]
	s_waitcnt lgkmcnt(3)
	v_mfma_f32_32x32x16_bf16 v[48:63], v[10:13], v[144:147], v[48:63]
	v_mfma_f32_32x32x16_bf16 v[64:79], v[6:9], v[148:151], v[64:79]
	s_waitcnt lgkmcnt(1)
	v_mfma_f32_32x32x16_bf16 v[48:63], v[160:163], v[148:151], v[48:63]
	v_mfma_f32_32x32x16_bf16 v[64:79], v[156:159], v[152:155], v[64:79]
	s_waitcnt lgkmcnt(0)
	v_mfma_f32_32x32x16_bf16 v[48:63], v[164:167], v[152:155], v[48:63]
	v_add_u32_e32 v14, s7, v193
	ds_read_b128 v[172:175], v14 offset:53248
	ds_read_b128 v[168:171], v14 offset:53280
	ds_read_b128 v[164:167], v14 offset:53312
	ds_read_b128 v[160:163], v14 offset:53344
	ds_read_b128 v[156:159], v14 offset:61952
	ds_read_b128 v[10:13], v14 offset:61984
	ds_read_b128 v[6:9], v14 offset:62016
	ds_read_b128 v[2:5], v14 offset:62048
	v_max3_f32 v0, v96, v80, v97
	v_max_f32_e32 v15, v95, v95
	v_max3_f32 v0, v0, v81, v98
	v_max3_f32 v0, v0, v82, v99
	v_max3_f32 v0, v0, v83, v100
	v_max3_f32 v0, v0, v84, v101
	v_max3_f32 v0, v0, v85, v102
	v_max3_f32 v0, v0, v86, v103
	v_max3_f32 v0, v0, v87, v104
	v_max3_f32 v0, v0, v88, v105
	v_max3_f32 v0, v0, v89, v106
	v_max3_f32 v0, v0, v90, v107
	v_max3_f32 v0, v0, v91, v108
	v_max3_f32 v0, v0, v92, v109
	v_max3_f32 v0, v0, v93, v110
	v_max3_f32 v0, v0, v94, v111
	s_nop 0
	v_max_f32_e32 v0, v0, v0
	v_max_f32_e32 v0, v0, v15
	v_mov_b32_e32 v15, v0
	v_nop
	v_nop
	v_permlane32_swap_b32 v0, v15
	s_nop 0
	v_max3_f32 v230, v195, v0, v15
	v_sub_f32_e32 v0, v195, v230
	v_exp_f32_e32 v0, v0
	s_nop 0
	v_cmp_neq_f32_e32 vcc, 1.0, v0
	s_cbranch_vccz .LBB0_229
	v_pk_mul_f32 v[46:47], v[46:47], v[0:1] op_sel_hi:[1,0]
	v_pk_mul_f32 v[44:45], v[44:45], v[0:1] op_sel_hi:[1,0]
	v_pk_mul_f32 v[42:43], v[42:43], v[0:1] op_sel_hi:[1,0]
	v_pk_mul_f32 v[40:41], v[40:41], v[0:1] op_sel_hi:[1,0]
	v_pk_mul_f32 v[38:39], v[38:39], v[0:1] op_sel_hi:[1,0]
	v_pk_mul_f32 v[36:37], v[36:37], v[0:1] op_sel_hi:[1,0]
	v_pk_mul_f32 v[34:35], v[34:35], v[0:1] op_sel_hi:[1,0]
	v_pk_mul_f32 v[32:33], v[32:33], v[0:1] op_sel_hi:[1,0]
	v_pk_mul_f32 v[30:31], v[30:31], v[0:1] op_sel_hi:[1,0]
	v_pk_mul_f32 v[28:29], v[28:29], v[0:1] op_sel_hi:[1,0]
	v_pk_mul_f32 v[26:27], v[26:27], v[0:1] op_sel_hi:[1,0]
	v_pk_mul_f32 v[24:25], v[24:25], v[0:1] op_sel_hi:[1,0]
	v_pk_mul_f32 v[22:23], v[22:23], v[0:1] op_sel_hi:[1,0]
	v_pk_mul_f32 v[20:21], v[20:21], v[0:1] op_sel_hi:[1,0]
	v_pk_mul_f32 v[18:19], v[18:19], v[0:1] op_sel_hi:[1,0]
	v_pk_mul_f32 v[16:17], v[16:17], v[0:1] op_sel_hi:[1,0]
.LBB0_229:
	v_sub_f32_e32 v80, v80, v230
	v_exp_f32_e32 v202, v80
	v_sub_f32_e32 v80, v97, v230
	v_exp_f32_e32 v203, v80
	v_sub_f32_e32 v80, v81, v230
	v_exp_f32_e32 v204, v80
	v_sub_f32_e32 v80, v98, v230
	v_exp_f32_e32 v205, v80
	v_sub_f32_e32 v80, v82, v230
	v_exp_f32_e32 v206, v80
	v_sub_f32_e32 v80, v99, v230
	v_exp_f32_e32 v207, v80
	v_sub_f32_e32 v80, v83, v230
	v_exp_f32_e32 v208, v80
	v_sub_f32_e32 v80, v100, v230
	v_exp_f32_e32 v100, v80
	v_sub_f32_e32 v80, v84, v230
	v_exp_f32_e32 v209, v80
	v_sub_f32_e32 v80, v101, v230
	v_exp_f32_e32 v101, v80
	v_sub_f32_e32 v80, v85, v230
	v_exp_f32_e32 v219, v80
	v_sub_f32_e32 v80, v102, v230
	v_exp_f32_e32 v102, v80
	v_sub_f32_e32 v80, v86, v230
	v_exp_f32_e32 v220, v80
	v_sub_f32_e32 v80, v103, v230
	v_exp_f32_e32 v103, v80
	v_sub_f32_e32 v80, v87, v230
	v_exp_f32_e32 v221, v80
	v_sub_f32_e32 v80, v104, v230
	v_exp_f32_e32 v104, v80
	v_sub_f32_e32 v80, v88, v230
	v_exp_f32_e32 v222, v80
	v_sub_f32_e32 v80, v105, v230
	v_exp_f32_e32 v105, v80
	v_sub_f32_e32 v80, v89, v230
	v_exp_f32_e32 v223, v80
	v_sub_f32_e32 v80, v106, v230
	v_exp_f32_e32 v106, v80
	v_sub_f32_e32 v80, v90, v230
	v_exp_f32_e32 v224, v80
	v_sub_f32_e32 v80, v107, v230
	v_exp_f32_e32 v107, v80
	v_sub_f32_e32 v80, v91, v230
	v_exp_f32_e32 v225, v80
	v_sub_f32_e32 v80, v108, v230
	v_exp_f32_e32 v108, v80
	v_sub_f32_e32 v80, v92, v230
	v_exp_f32_e32 v226, v80
	v_sub_f32_e32 v80, v109, v230
	v_exp_f32_e32 v109, v80
	v_sub_f32_e32 v80, v93, v230
	v_exp_f32_e32 v227, v80
	v_sub_f32_e32 v80, v110, v230
	v_exp_f32_e32 v110, v80
	v_sub_f32_e32 v80, v94, v230
	v_exp_f32_e32 v228, v80
	v_sub_f32_e32 v80, v111, v230
	v_sub_f32_e32 v15, v96, v230
	v_exp_f32_e32 v111, v80
	v_sub_f32_e32 v80, v95, v230
	v_exp_f32_e32 v15, v15
	v_exp_f32_e32 v229, v80
	v_cvt_pk_bf16_f32 v80, v222, v223
	v_cvt_pk_bf16_f32 v81, v224, v225
	v_cvt_pk_bf16_f32 v82, v226, v227
	v_cvt_pk_bf16_f32 v83, v228, v229
	v_cvt_pk_bf16_f32 v84, v202, v204
	v_cvt_pk_bf16_f32 v85, v206, v208
	v_cvt_pk_bf16_f32 v86, v209, v219
	v_cvt_pk_bf16_f32 v87, v220, v221
	v_cvt_pk_bf16_f32 v88, v104, v105
	v_cvt_pk_bf16_f32 v89, v106, v107
	v_cvt_pk_bf16_f32 v90, v108, v109
	v_cvt_pk_bf16_f32 v91, v110, v111
	v_cvt_pk_bf16_f32 v92, v15, v203
	v_cvt_pk_bf16_f32 v93, v205, v207
	v_cvt_pk_bf16_f32 v94, v100, v101
	v_cvt_pk_bf16_f32 v95, v102, v103
	s_waitcnt lgkmcnt(7)
	s_nop 0
	v_mfma_f32_32x32x16_bf16 v[32:47], v[172:175], v[92:95], v[32:47]
	s_waitcnt lgkmcnt(3)
	v_mfma_f32_32x32x16_bf16 v[16:31], v[156:159], v[92:95], v[16:31]
	v_mfma_f32_32x32x16_bf16 v[32:47], v[168:171], v[88:91], v[32:47]
	s_waitcnt lgkmcnt(2)
	v_mfma_f32_32x32x16_bf16 v[16:31], v[10:13], v[88:91], v[16:31]
	v_mfma_f32_32x32x16_bf16 v[32:47], v[164:167], v[84:87], v[32:47]
	s_waitcnt lgkmcnt(1)
	v_mfma_f32_32x32x16_bf16 v[16:31], v[6:9], v[84:87], v[16:31]
	v_mfma_f32_32x32x16_bf16 v[32:47], v[160:163], v[80:83], v[32:47]
	s_waitcnt lgkmcnt(0)
	v_mfma_f32_32x32x16_bf16 v[16:31], v[2:5], v[80:83], v[16:31]
	ds_read_b128 v[96:99], v14 offset:53376
	ds_read_b128 v[92:95], v14 offset:53408
	ds_read_b128 v[88:91], v14 offset:53440
	ds_read_b128 v[84:87], v14 offset:53472
	ds_read_b128 v[80:83], v14 offset:62080
	ds_read_b128 v[10:13], v14 offset:62112
	ds_read_b128 v[6:9], v14 offset:62144
	ds_read_b128 v[2:5], v14 offset:62176
	v_max3_f32 v14, v64, v48, v65
	v_max_f32_e32 v156, v63, v63
	v_max3_f32 v14, v14, v49, v66
	v_max3_f32 v14, v14, v50, v67
	v_max3_f32 v14, v14, v51, v68
	v_max3_f32 v14, v14, v52, v69
	v_max3_f32 v14, v14, v53, v70
	v_max3_f32 v14, v14, v54, v71
	v_max3_f32 v14, v14, v55, v72
	v_max3_f32 v14, v14, v56, v73
	v_max3_f32 v14, v14, v57, v74
	v_max3_f32 v14, v14, v58, v75
	v_max3_f32 v14, v14, v59, v76
	v_max3_f32 v14, v14, v60, v77
	v_max3_f32 v14, v14, v61, v78
	v_max3_f32 v14, v14, v62, v79
	s_nop 0
	v_max_f32_e32 v14, v14, v14
	v_max_f32_e32 v14, v14, v156
	v_mov_b32_e32 v156, v14
	v_nop
	v_nop
	v_permlane32_swap_b32 v14, v156
	s_nop 0
	v_max3_f32 v195, v230, v14, v156
	v_sub_f32_e32 v14, v230, v195
	v_exp_f32_e32 v14, v14
	s_nop 0
	v_cmp_neq_f32_e32 vcc, 1.0, v14
	s_cbranch_vccz .LBB0_231
	v_pk_mul_f32 v[46:47], v[46:47], v[14:15] op_sel_hi:[1,0]
	v_pk_mul_f32 v[44:45], v[44:45], v[14:15] op_sel_hi:[1,0]
	v_pk_mul_f32 v[42:43], v[42:43], v[14:15] op_sel_hi:[1,0]
	v_pk_mul_f32 v[40:41], v[40:41], v[14:15] op_sel_hi:[1,0]
	v_pk_mul_f32 v[38:39], v[38:39], v[14:15] op_sel_hi:[1,0]
	v_pk_mul_f32 v[36:37], v[36:37], v[14:15] op_sel_hi:[1,0]
	v_pk_mul_f32 v[34:35], v[34:35], v[14:15] op_sel_hi:[1,0]
	v_pk_mul_f32 v[32:33], v[32:33], v[14:15] op_sel_hi:[1,0]
	v_pk_mul_f32 v[30:31], v[30:31], v[14:15] op_sel_hi:[1,0]
	v_pk_mul_f32 v[28:29], v[28:29], v[14:15] op_sel_hi:[1,0]
	v_pk_mul_f32 v[26:27], v[26:27], v[14:15] op_sel_hi:[1,0]
	v_pk_mul_f32 v[24:25], v[24:25], v[14:15] op_sel_hi:[1,0]
	v_pk_mul_f32 v[22:23], v[22:23], v[14:15] op_sel_hi:[1,0]
	v_pk_mul_f32 v[20:21], v[20:21], v[14:15] op_sel_hi:[1,0]
	v_pk_mul_f32 v[18:19], v[18:19], v[14:15] op_sel_hi:[1,0]
	v_pk_mul_f32 v[16:17], v[16:17], v[14:15] op_sel_hi:[1,0]
